# P0 (prologue) stores written through (sc1) so the first grid barrier's L2 write-back has less to flush
# speedup vs baseline: 1.0010x; 1.0010x over previous
.LBB0_24:
	s_waitcnt vmcnt(3)
	v_mul_f32_e32 v43, v31, v31
	v_mul_f32_e32 v55, v33, v33
	v_fmac_f32_e32 v43, v30, v30
	v_fmac_f32_e32 v55, v32, v32
	v_add_f32_e32 v43, v43, v55
	s_waitcnt vmcnt(2)
	v_mul_f32_e32 v55, v27, v27
	v_mul_f32_e32 v56, v29, v29
	v_fmac_f32_e32 v55, v26, v26
	v_fmac_f32_e32 v56, v28, v28
	v_add_f32_e32 v55, v55, v56
	v_add_f32_e32 v43, v43, v55
	s_waitcnt vmcnt(1)
	v_mul_f32_e32 v55, v23, v23
	v_mul_f32_e32 v56, v25, v25
	v_fmac_f32_e32 v55, v22, v22
	v_fmac_f32_e32 v56, v24, v24
	v_add_f32_e32 v55, v55, v56
	v_add_f32_e32 v43, v43, v55
	s_waitcnt vmcnt(0)
	v_mul_f32_e32 v55, v19, v19
	v_mul_f32_e32 v56, v21, v21
	v_fmac_f32_e32 v55, v18, v18
	v_fmac_f32_e32 v56, v20, v20
	v_add_f32_e32 v55, v55, v56
	v_add_f32_e32 v43, v43, v55
	ds_bpermute_b32 v55, v1, v43
	s_waitcnt lgkmcnt(0)
	v_add_f32_e32 v43, v43, v55
	ds_bpermute_b32 v55, v46, v43
	s_waitcnt lgkmcnt(0)
	v_add_f32_e32 v43, v43, v55
	ds_bpermute_b32 v55, v47, v43
	s_waitcnt lgkmcnt(0)
	v_add_f32_e32 v43, v43, v55
	ds_bpermute_b32 v55, v48, v43
	s_waitcnt lgkmcnt(0)
	v_add_f32_e32 v43, v43, v55
	ds_bpermute_b32 v55, v49, v43
	s_waitcnt lgkmcnt(0)
	v_add_f32_e32 v43, v43, v55
	ds_bpermute_b32 v55, v50, v43
	s_waitcnt lgkmcnt(0)
	v_add_f32_e32 v43, v43, v55
	s_and_saveexec_b64 s[60:61], s[6:7]
	s_cbranch_execz .LBB0_26
	s_add_u32 s88, s72, s4
	s_addc_u32 s89, s73, s5
	global_store_dword v35, v43, s[88:89] sc1
.LBB0_26:
	s_or_b64 exec, exec, s[60:61]
	v_bfe_u32 v55, v30, 16, 1
	v_add3_u32 v55, v30, v55, s19
	v_bfe_u32 v58, v31, 16, 1
	v_lshrrev_b32_e32 v55, 16, v55
	v_add3_u32 v58, v31, v58, s19
	v_and_or_b32 v58, v58, s21, v55
	v_bfe_u32 v55, v32, 16, 1
	v_add3_u32 v55, v32, v55, s19
	v_bfe_u32 v59, v33, 16, 1
	v_lshrrev_b32_e32 v55, 16, v55
	v_add3_u32 v59, v33, v59, s19
	v_lshl_add_u64 v[56:57], s[72:73], 0, v[40:41]
	v_and_or_b32 v59, v59, s21, v55
	v_bfe_u32 v55, v26, 16, 1
	v_add_co_u32_e32 v60, vcc, s33, v56
	v_add3_u32 v55, v26, v55, s19
	v_bfe_u32 v56, v27, 16, 1
	v_lshrrev_b32_e32 v55, 16, v55
	v_add3_u32 v56, v27, v56, s19
	v_and_or_b32 v56, v56, s21, v55
	v_bfe_u32 v55, v28, 16, 1
	v_addc_co_u32_e32 v61, vcc, 0, v57, vcc
	v_add3_u32 v55, v28, v55, s19
	v_bfe_u32 v57, v29, 16, 1
	v_lshrrev_b32_e32 v55, 16, v55
	v_add3_u32 v57, v29, v57, s19
	v_and_or_b32 v57, v57, s21, v55
	v_bfe_u32 v55, v22, 16, 1
	global_store_dwordx2 v[60:61], v[56:57], off offset:512 sc1
	v_add3_u32 v55, v22, v55, s19
	v_bfe_u32 v56, v23, 16, 1
	v_lshrrev_b32_e32 v55, 16, v55
	v_add3_u32 v56, v23, v56, s19
	v_and_or_b32 v56, v56, s21, v55
	v_bfe_u32 v55, v24, 16, 1
	v_add3_u32 v55, v24, v55, s19
	v_bfe_u32 v57, v25, 16, 1
	v_lshrrev_b32_e32 v55, 16, v55
	v_add3_u32 v57, v25, v57, s19
	v_and_or_b32 v57, v57, s21, v55
	v_bfe_u32 v55, v18, 16, 1
	global_store_dwordx2 v[60:61], v[56:57], off offset:1024 sc1
	v_add3_u32 v55, v18, v55, s19
	v_bfe_u32 v56, v19, 16, 1
	v_lshrrev_b32_e32 v55, 16, v55
	v_add3_u32 v56, v19, v56, s19
	v_and_or_b32 v62, v56, s21, v55
	v_bfe_u32 v55, v20, 16, 1
	v_add3_u32 v55, v20, v55, s19
	v_bfe_u32 v63, v21, 16, 1
	global_store_dwordx2 v[60:61], v[58:59], off sc1
	v_lshrrev_b32_e32 v55, 16, v55
	ds_read_b128 v[56:59], v51
	v_add3_u32 v63, v21, v63, s19
	v_and_or_b32 v63, v63, s21, v55
	global_store_dwordx2 v[60:61], v[62:63], off offset:1536 sc1
	ds_read_b128 v[60:63], v51 offset:1024
	s_waitcnt lgkmcnt(1)
	v_mul_f32_e32 v55, v31, v57
	v_fmac_f32_e32 v55, v30, v56
	v_mul_f32_e32 v56, v33, v59
	v_fmac_f32_e32 v56, v32, v58
	s_waitcnt lgkmcnt(0)
	v_mul_f32_e32 v61, v27, v61
	v_add_f32_e32 v55, v55, v56
	v_fmac_f32_e32 v61, v26, v60
	v_mul_f32_e32 v60, v29, v63
	ds_read_b128 v[56:59], v51 offset:2048
	v_fmac_f32_e32 v60, v28, v62
	v_add_f32_e32 v55, 0, v55
	v_add_f32_e32 v60, v61, v60
	v_add_f32_e32 v55, v55, v60
	ds_read_b128 v[60:63], v51 offset:3072
	s_waitcnt lgkmcnt(1)
	v_mul_f32_e32 v57, v23, v57
	v_fmac_f32_e32 v57, v22, v56
	v_mul_f32_e32 v56, v25, v59
	v_fmac_f32_e32 v56, v24, v58
	v_add_f32_e32 v56, v57, v56
	s_waitcnt lgkmcnt(0)
	v_mul_f32_e32 v64, v19, v61
	v_mul_f32_e32 v65, v21, v63
	v_add_f32_e32 v55, v55, v56
	v_fmac_f32_e32 v64, v18, v60
	v_fmac_f32_e32 v65, v20, v62
	ds_read_b128 v[56:59], v51 offset:5120
	ds_read_b128 v[60:63], v51 offset:4096
	v_add_f32_e32 v64, v64, v65
	v_add_f32_e32 v55, v55, v64
	ds_read_b128 v[64:67], v51 offset:7168
	ds_read_b128 v[68:71], v51 offset:6144
	s_waitcnt lgkmcnt(3)
	v_mul_f32_e32 v57, v27, v57
	s_waitcnt lgkmcnt(2)
	v_mul_f32_e32 v61, v31, v61
	v_fmac_f32_e32 v61, v30, v60
	v_mul_f32_e32 v60, v33, v63
	v_fmac_f32_e32 v57, v26, v56
	v_mul_f32_e32 v56, v29, v59
	v_fmac_f32_e32 v60, v32, v62
	v_fmac_f32_e32 v56, v28, v58
	v_add_f32_e32 v60, v61, v60
	v_add_f32_e32 v56, v57, v56
	s_waitcnt lgkmcnt(0)
	v_mul_f32_e32 v57, v23, v69
	v_mul_f32_e32 v58, v25, v71
	v_add_f32_e32 v60, 0, v60
	v_fmac_f32_e32 v57, v22, v68
	v_fmac_f32_e32 v58, v24, v70
	v_add_f32_e32 v56, v60, v56
	v_add_f32_e32 v57, v57, v58
	v_add_f32_e32 v56, v56, v57
	v_mul_f32_e32 v57, v19, v65
	v_fmac_f32_e32 v57, v18, v64
	ds_read_b128 v[58:61], v51 offset:9216
	ds_read_b128 v[62:65], v51 offset:8192
	v_mul_f32_e32 v67, v21, v67
	v_fmac_f32_e32 v67, v20, v66
	v_add_f32_e32 v57, v57, v67
	v_add_f32_e32 v56, v56, v57
	ds_read_b128 v[66:69], v51 offset:11264
	ds_read_b128 v[70:73], v51 offset:10240
	s_waitcnt lgkmcnt(2)
	v_mul_f32_e32 v57, v31, v63
	v_fmac_f32_e32 v57, v30, v62
	v_mul_f32_e32 v62, v33, v65
	v_mul_f32_e32 v59, v27, v59
	v_fmac_f32_e32 v62, v32, v64
	v_fmac_f32_e32 v59, v26, v58
	v_mul_f32_e32 v58, v29, v61
	v_add_f32_e32 v57, v57, v62
	v_fmac_f32_e32 v58, v28, v60
	v_add_f32_e32 v57, 0, v57
	v_add_f32_e32 v58, v59, v58
	v_add_f32_e32 v57, v57, v58
	s_waitcnt lgkmcnt(0)
	v_mul_f32_e32 v58, v23, v71
	v_mul_f32_e32 v59, v25, v73
	v_fmac_f32_e32 v58, v22, v70
	v_fmac_f32_e32 v59, v24, v72
	v_add_f32_e32 v58, v58, v59
	v_mul_f32_e32 v67, v19, v67
	v_add_f32_e32 v57, v57, v58
	v_fmac_f32_e32 v67, v18, v66
	v_mul_f32_e32 v66, v21, v69
	ds_read_b128 v[58:61], v51 offset:13312
	ds_read_b128 v[62:65], v51 offset:12288
	v_fmac_f32_e32 v66, v20, v68
	v_add_f32_e32 v66, v67, v66
	v_add_f32_e32 v57, v57, v66
	ds_read_b128 v[66:69], v51 offset:15360
	ds_read_b128 v[70:73], v51 offset:14336
	s_waitcnt lgkmcnt(2)
	v_mul_f32_e32 v63, v31, v63
	v_mul_f32_e32 v59, v27, v59
	v_fmac_f32_e32 v63, v30, v62
	v_mul_f32_e32 v62, v33, v65
	v_fmac_f32_e32 v59, v26, v58
	v_mul_f32_e32 v58, v29, v61
	v_fmac_f32_e32 v62, v32, v64
	v_fmac_f32_e32 v58, v28, v60
	v_add_f32_e32 v62, v63, v62
	v_add_f32_e32 v58, v59, v58
	s_waitcnt lgkmcnt(0)
	v_mul_f32_e32 v59, v23, v71
	v_mul_f32_e32 v60, v25, v73
	v_add_f32_e32 v62, 0, v62
	v_fmac_f32_e32 v59, v22, v70
	v_fmac_f32_e32 v60, v24, v72
	v_add_f32_e32 v58, v62, v58
	v_add_f32_e32 v59, v59, v60
	v_add_f32_e32 v58, v58, v59
	v_mul_f32_e32 v59, v19, v67
	v_mul_f32_e32 v64, v21, v69
	ds_read_b128 v[60:63], v51 offset:16384
	v_fmac_f32_e32 v59, v18, v66
	v_fmac_f32_e32 v64, v20, v68
	v_add_f32_e32 v59, v59, v64
	ds_read_b128 v[64:67], v51 offset:17408
	v_add_f32_e32 v58, v58, v59
	s_waitcnt lgkmcnt(1)
	v_mul_f32_e32 v59, v31, v61
	v_fmac_f32_e32 v59, v30, v60
	v_mul_f32_e32 v60, v33, v63
	v_fmac_f32_e32 v60, v32, v62
	s_waitcnt lgkmcnt(0)
	v_mul_f32_e32 v65, v27, v65
	v_add_f32_e32 v59, v59, v60
	v_fmac_f32_e32 v65, v26, v64
	v_mul_f32_e32 v64, v29, v67
	ds_read_b128 v[60:63], v51 offset:18432
	v_fmac_f32_e32 v64, v28, v66
	v_add_f32_e32 v59, 0, v59
	v_add_f32_e32 v64, v65, v64
	v_add_f32_e32 v59, v59, v64
	ds_read_b128 v[64:67], v51 offset:19456
	s_waitcnt lgkmcnt(1)
	v_mul_f32_e32 v61, v23, v61
	v_fmac_f32_e32 v61, v22, v60
	v_mul_f32_e32 v60, v25, v63
	v_fmac_f32_e32 v60, v24, v62
	v_add_f32_e32 v60, v61, v60
	s_waitcnt lgkmcnt(0)
	v_mul_f32_e32 v68, v19, v65
	v_mul_f32_e32 v69, v21, v67
	v_add_f32_e32 v59, v59, v60
	v_fmac_f32_e32 v68, v18, v64
	v_fmac_f32_e32 v69, v20, v66
	ds_read_b128 v[60:63], v51 offset:21504
	ds_read_b128 v[64:67], v51 offset:20480
	v_add_f32_e32 v68, v68, v69
	v_add_f32_e32 v59, v59, v68
	ds_read_b128 v[68:71], v51 offset:23552
	ds_read_b128 v[72:75], v51 offset:22528
	s_waitcnt lgkmcnt(3)
	v_mul_f32_e32 v61, v27, v61
	s_waitcnt lgkmcnt(2)
	v_mul_f32_e32 v65, v31, v65
	v_fmac_f32_e32 v65, v30, v64
	v_mul_f32_e32 v64, v33, v67
	v_fmac_f32_e32 v61, v26, v60
	v_mul_f32_e32 v60, v29, v63
	v_fmac_f32_e32 v64, v32, v66
	v_fmac_f32_e32 v60, v28, v62
	v_add_f32_e32 v64, v65, v64
	v_add_f32_e32 v60, v61, v60
	s_waitcnt lgkmcnt(0)
	v_mul_f32_e32 v61, v23, v73
	v_mul_f32_e32 v62, v25, v75
	v_add_f32_e32 v64, 0, v64
	v_fmac_f32_e32 v61, v22, v72
	v_fmac_f32_e32 v62, v24, v74
	v_add_f32_e32 v60, v64, v60
	v_add_f32_e32 v61, v61, v62
	v_mul_f32_e32 v69, v19, v69
	v_add_f32_e32 v72, v60, v61
	v_fmac_f32_e32 v69, v18, v68
	v_mul_f32_e32 v68, v21, v71
	ds_read_b128 v[60:63], v51 offset:25600
	ds_read_b128 v[64:67], v51 offset:24576
	v_fmac_f32_e32 v68, v20, v70
	v_add_f32_e32 v68, v69, v68
	v_add_f32_e32 v76, v72, v68
	ds_read_b128 v[68:71], v51 offset:27648
	ds_read_b128 v[72:75], v51 offset:26624
	s_waitcnt lgkmcnt(2)
	v_mul_f32_e32 v65, v31, v65
	v_mul_f32_e32 v61, v27, v61
	v_fmac_f32_e32 v65, v30, v64
	v_mul_f32_e32 v64, v33, v67
	v_fmac_f32_e32 v61, v26, v60
	v_mul_f32_e32 v60, v29, v63
	v_fmac_f32_e32 v64, v32, v66
	v_fmac_f32_e32 v60, v28, v62
	v_add_f32_e32 v64, v65, v64
	v_add_f32_e32 v60, v61, v60
	s_waitcnt lgkmcnt(0)
	v_mul_f32_e32 v61, v23, v73
	v_mul_f32_e32 v62, v25, v75
	v_add_f32_e32 v64, 0, v64
	v_fmac_f32_e32 v61, v22, v72
	v_fmac_f32_e32 v62, v24, v74
	v_add_f32_e32 v60, v64, v60
	v_add_f32_e32 v61, v61, v62
	v_mul_f32_e32 v69, v19, v69
	v_add_f32_e32 v72, v60, v61
	v_fmac_f32_e32 v69, v18, v68
	v_mul_f32_e32 v68, v21, v71
	ds_read_b128 v[60:63], v51 offset:29696
	ds_read_b128 v[64:67], v51 offset:28672
	v_fmac_f32_e32 v68, v20, v70
	v_add_f32_e32 v68, v69, v68
	v_add_f32_e32 v77, v72, v68
	ds_read_b128 v[68:71], v51 offset:31744
	ds_read_b128 v[72:75], v51 offset:30720
	s_waitcnt lgkmcnt(2)
	v_mul_f32_e32 v65, v31, v65
	v_mul_f32_e32 v61, v27, v61
	v_fmac_f32_e32 v65, v30, v64
	v_mul_f32_e32 v64, v33, v67
	v_fmac_f32_e32 v61, v26, v60
	v_mul_f32_e32 v60, v29, v63
	v_fmac_f32_e32 v64, v32, v66
	v_fmac_f32_e32 v60, v28, v62
	v_add_f32_e32 v64, v65, v64
	v_add_f32_e32 v60, v61, v60
	s_waitcnt lgkmcnt(0)
	v_mul_f32_e32 v61, v23, v73
	v_mul_f32_e32 v62, v25, v75
	v_add_f32_e32 v64, 0, v64
	v_fmac_f32_e32 v61, v22, v72
	v_fmac_f32_e32 v62, v24, v74
	v_add_f32_e32 v60, v64, v60
	v_add_f32_e32 v61, v61, v62
	v_add_f32_e32 v64, v60, v61
	v_mul_f32_e32 v65, v19, v69
	v_mul_f32_e32 v66, v21, v71
	ds_read_b128 v[60:63], v51 offset:32768
	v_fmac_f32_e32 v65, v18, v68
	v_fmac_f32_e32 v66, v20, v70
	v_add_f32_e32 v65, v65, v66
	v_add_f32_e32 v78, v64, v65
	ds_read_b128 v[64:67], v51 offset:33792
	s_waitcnt lgkmcnt(1)
	v_mul_f32_e32 v61, v31, v61
	v_fmac_f32_e32 v61, v30, v60
	v_mul_f32_e32 v60, v33, v63
	v_fmac_f32_e32 v60, v32, v62
	v_add_f32_e32 v60, v61, v60
	s_waitcnt lgkmcnt(0)
	v_mul_f32_e32 v65, v27, v65
	v_add_f32_e32 v68, 0, v60
	v_fmac_f32_e32 v65, v26, v64
	v_mul_f32_e32 v64, v29, v67
	ds_read_b128 v[60:63], v51 offset:34816
	v_fmac_f32_e32 v64, v28, v66
	v_add_f32_e32 v64, v65, v64
	v_add_f32_e32 v68, v68, v64
	ds_read_b128 v[64:67], v51 offset:35840
	s_waitcnt lgkmcnt(1)
	v_mul_f32_e32 v61, v23, v61
	v_fmac_f32_e32 v61, v22, v60
	v_mul_f32_e32 v60, v25, v63
	v_fmac_f32_e32 v60, v24, v62
	v_add_f32_e32 v60, v61, v60
	s_waitcnt lgkmcnt(0)
	v_mul_f32_e32 v69, v19, v65
	v_mul_f32_e32 v70, v21, v67
	v_add_f32_e32 v68, v68, v60
	v_fmac_f32_e32 v69, v18, v64
	v_fmac_f32_e32 v70, v20, v66
	ds_read_b128 v[60:63], v51 offset:37888
	ds_read_b128 v[64:67], v51 offset:36864
	v_add_f32_e32 v69, v69, v70
	v_add_f32_e32 v79, v68, v69
	ds_read_b128 v[68:71], v51 offset:39936
	ds_read_b128 v[72:75], v51 offset:38912
	s_waitcnt lgkmcnt(3)
	v_mul_f32_e32 v61, v27, v61
	s_waitcnt lgkmcnt(2)
	v_mul_f32_e32 v65, v31, v65
	v_fmac_f32_e32 v65, v30, v64
	v_mul_f32_e32 v64, v33, v67
	v_fmac_f32_e32 v61, v26, v60
	v_mul_f32_e32 v60, v29, v63
	v_fmac_f32_e32 v64, v32, v66
	v_fmac_f32_e32 v60, v28, v62
	v_add_f32_e32 v64, v65, v64
	v_add_f32_e32 v60, v61, v60
	s_waitcnt lgkmcnt(0)
	v_mul_f32_e32 v61, v23, v73
	v_mul_f32_e32 v62, v25, v75
	v_add_f32_e32 v64, 0, v64
	v_fmac_f32_e32 v61, v22, v72
	v_fmac_f32_e32 v62, v24, v74
	v_add_f32_e32 v60, v64, v60
	v_add_f32_e32 v61, v61, v62
	v_mul_f32_e32 v69, v19, v69
	v_add_f32_e32 v72, v60, v61
	v_fmac_f32_e32 v69, v18, v68
	v_mul_f32_e32 v68, v21, v71
	ds_read_b128 v[60:63], v51 offset:41984
	ds_read_b128 v[64:67], v51 offset:40960
	v_fmac_f32_e32 v68, v20, v70
	v_add_f32_e32 v68, v69, v68
	v_add_f32_e32 v80, v72, v68
	ds_read_b128 v[68:71], v51 offset:44032
	ds_read_b128 v[72:75], v51 offset:43008
	s_waitcnt lgkmcnt(2)
	v_mul_f32_e32 v65, v31, v65
	v_mul_f32_e32 v61, v27, v61
	v_fmac_f32_e32 v65, v30, v64
	v_mul_f32_e32 v64, v33, v67
	v_fmac_f32_e32 v61, v26, v60
	v_mul_f32_e32 v60, v29, v63
	v_fmac_f32_e32 v64, v32, v66
	v_fmac_f32_e32 v60, v28, v62
	v_add_f32_e32 v64, v65, v64
	v_add_f32_e32 v60, v61, v60
	s_waitcnt lgkmcnt(0)
	v_mul_f32_e32 v61, v23, v73
	v_mul_f32_e32 v62, v25, v75
	v_add_f32_e32 v64, 0, v64
	v_fmac_f32_e32 v61, v22, v72
	v_fmac_f32_e32 v62, v24, v74
	v_add_f32_e32 v60, v64, v60
	v_add_f32_e32 v61, v61, v62
	v_mul_f32_e32 v69, v19, v69
	v_add_f32_e32 v72, v60, v61
	v_fmac_f32_e32 v69, v18, v68
	v_mul_f32_e32 v68, v21, v71
	ds_read_b128 v[60:63], v51 offset:46080
	ds_read_b128 v[64:67], v51 offset:45056
	v_fmac_f32_e32 v68, v20, v70
	v_add_f32_e32 v68, v69, v68
	v_add_f32_e32 v81, v72, v68
	ds_read_b128 v[68:71], v51 offset:48128
	ds_read_b128 v[72:75], v51 offset:47104
	s_waitcnt lgkmcnt(2)
	v_mul_f32_e32 v65, v31, v65
	v_mul_f32_e32 v61, v27, v61
	v_fmac_f32_e32 v65, v30, v64
	v_mul_f32_e32 v64, v33, v67
	v_fmac_f32_e32 v61, v26, v60
	v_mul_f32_e32 v60, v29, v63
	v_fmac_f32_e32 v64, v32, v66
	v_fmac_f32_e32 v60, v28, v62
	v_add_f32_e32 v64, v65, v64
	v_add_f32_e32 v60, v61, v60
	s_waitcnt lgkmcnt(0)
	v_mul_f32_e32 v61, v23, v73
	v_mul_f32_e32 v62, v25, v75
	v_add_f32_e32 v64, 0, v64
	v_fmac_f32_e32 v61, v22, v72
	v_fmac_f32_e32 v62, v24, v74
	v_add_f32_e32 v60, v64, v60
	v_add_f32_e32 v61, v61, v62
	v_add_f32_e32 v64, v60, v61
	v_mul_f32_e32 v65, v19, v69
	v_mul_f32_e32 v66, v21, v71
	ds_read_b128 v[60:63], v51 offset:49152
	v_fmac_f32_e32 v65, v18, v68
	v_fmac_f32_e32 v66, v20, v70
	v_add_f32_e32 v65, v65, v66
	v_add_f32_e32 v82, v64, v65
	ds_read_b128 v[64:67], v51 offset:50176
	s_waitcnt lgkmcnt(1)
	v_mul_f32_e32 v61, v31, v61
	v_fmac_f32_e32 v61, v30, v60
	v_mul_f32_e32 v60, v33, v63
	v_fmac_f32_e32 v60, v32, v62
	v_add_f32_e32 v60, v61, v60
	s_waitcnt lgkmcnt(0)
	v_mul_f32_e32 v65, v27, v65
	v_add_f32_e32 v68, 0, v60
	v_fmac_f32_e32 v65, v26, v64
	v_mul_f32_e32 v64, v29, v67
	ds_read_b128 v[60:63], v51 offset:51200
	v_fmac_f32_e32 v64, v28, v66
	v_add_f32_e32 v64, v65, v64
	v_add_f32_e32 v68, v68, v64
	ds_read_b128 v[64:67], v51 offset:52224
	s_waitcnt lgkmcnt(1)
	v_mul_f32_e32 v61, v23, v61
	v_fmac_f32_e32 v61, v22, v60
	v_mul_f32_e32 v60, v25, v63
	v_fmac_f32_e32 v60, v24, v62
	v_add_f32_e32 v60, v61, v60
	s_waitcnt lgkmcnt(0)
	v_mul_f32_e32 v69, v19, v65
	v_mul_f32_e32 v70, v21, v67
	v_add_f32_e32 v68, v68, v60
	v_fmac_f32_e32 v69, v18, v64
	v_fmac_f32_e32 v70, v20, v66
	ds_read_b128 v[60:63], v51 offset:54272
	ds_read_b128 v[64:67], v51 offset:53248
	v_add_f32_e32 v69, v69, v70
	v_add_f32_e32 v83, v68, v69
	ds_read_b128 v[68:71], v51 offset:56320
	ds_read_b128 v[72:75], v51 offset:55296
	s_waitcnt lgkmcnt(3)
	v_mul_f32_e32 v61, v27, v61
	s_waitcnt lgkmcnt(2)
	v_mul_f32_e32 v65, v31, v65
	v_fmac_f32_e32 v65, v30, v64
	v_mul_f32_e32 v64, v33, v67
	v_fmac_f32_e32 v61, v26, v60
	v_mul_f32_e32 v60, v29, v63
	v_fmac_f32_e32 v64, v32, v66
	v_fmac_f32_e32 v60, v28, v62
	v_add_f32_e32 v64, v65, v64
	v_add_f32_e32 v60, v61, v60
	s_waitcnt lgkmcnt(0)
	v_mul_f32_e32 v61, v23, v73
	v_mul_f32_e32 v62, v25, v75
	v_add_f32_e32 v64, 0, v64
	v_fmac_f32_e32 v61, v22, v72
	v_fmac_f32_e32 v62, v24, v74
	v_add_f32_e32 v60, v64, v60
	v_add_f32_e32 v61, v61, v62
	v_mul_f32_e32 v69, v19, v69
	v_add_f32_e32 v72, v60, v61
	v_fmac_f32_e32 v69, v18, v68
	v_mul_f32_e32 v68, v21, v71
	ds_read_b128 v[60:63], v51 offset:58368
	ds_read_b128 v[64:67], v51 offset:57344
	v_fmac_f32_e32 v68, v20, v70
	v_add_f32_e32 v68, v69, v68
	v_add_f32_e32 v84, v72, v68
	ds_read_b128 v[68:71], v51 offset:60416
	ds_read_b128 v[72:75], v51 offset:59392
	s_waitcnt lgkmcnt(2)
	v_mul_f32_e32 v65, v31, v65
	v_mul_f32_e32 v61, v27, v61
	v_fmac_f32_e32 v65, v30, v64
	v_mul_f32_e32 v64, v33, v67
	v_fmac_f32_e32 v61, v26, v60
	v_mul_f32_e32 v60, v29, v63
	v_fmac_f32_e32 v64, v32, v66
	v_fmac_f32_e32 v60, v28, v62
	v_add_f32_e32 v64, v65, v64
	v_add_f32_e32 v60, v61, v60
	s_waitcnt lgkmcnt(0)
	v_mul_f32_e32 v61, v23, v73
	v_mul_f32_e32 v62, v25, v75
	v_add_f32_e32 v64, 0, v64
	v_fmac_f32_e32 v61, v22, v72
	v_fmac_f32_e32 v62, v24, v74
	v_mul_f32_e32 v69, v19, v69
	v_add_f32_e32 v60, v64, v60
	v_add_f32_e32 v61, v61, v62
	v_fmac_f32_e32 v69, v18, v68
	v_mul_f32_e32 v68, v21, v71
	v_add_f32_e32 v72, v60, v61
	v_fmac_f32_e32 v68, v20, v70
	ds_read_b128 v[60:63], v51 offset:62464
	ds_read_b128 v[64:67], v51 offset:61440
	v_add_f32_e32 v68, v69, v68
	v_add_f32_e32 v85, v72, v68
	ds_read_b128 v[68:71], v51 offset:64512
	ds_read_b128 v[72:75], v51 offset:63488
	s_waitcnt lgkmcnt(3)
	v_mul_f32_e32 v27, v27, v61
	s_waitcnt lgkmcnt(2)
	v_mul_f32_e32 v31, v31, v65
	v_fmac_f32_e32 v31, v30, v64
	v_mul_f32_e32 v30, v33, v67
	v_fmac_f32_e32 v30, v32, v66
	v_fmac_f32_e32 v27, v26, v60
	v_mul_f32_e32 v26, v29, v63
	s_waitcnt lgkmcnt(0)
	v_mul_f32_e32 v23, v23, v73
	v_add_f32_e32 v30, v31, v30
	v_fmac_f32_e32 v26, v28, v62
	v_fmac_f32_e32 v23, v22, v72
	v_mul_f32_e32 v22, v25, v75
	v_mul_f32_e32 v19, v19, v69
	v_add_f32_e32 v30, 0, v30
	v_add_f32_e32 v26, v27, v26
	v_fmac_f32_e32 v22, v24, v74
	v_fmac_f32_e32 v19, v18, v68
	v_mul_f32_e32 v18, v21, v71
	v_add_f32_e32 v26, v30, v26
	v_add_f32_e32 v22, v23, v22
	v_fmac_f32_e32 v18, v20, v70
	v_cndmask_b32_e64 v20, v55, v79, s[8:9]
	v_add_f32_e32 v22, v26, v22
	v_add_f32_e32 v18, v19, v18
	ds_bpermute_b32 v20, v50, v20
	v_cndmask_b32_e64 v21, v56, v80, s[8:9]
	v_add_f32_e32 v18, v22, v18
	ds_bpermute_b32 v21, v50, v21
	v_cndmask_b32_e64 v22, v57, v81, s[8:9]
	ds_bpermute_b32 v22, v50, v22
	v_cndmask_b32_e64 v23, v58, v82, s[8:9]
	ds_bpermute_b32 v23, v50, v23
	v_cndmask_b32_e64 v24, v59, v83, s[8:9]
	v_cndmask_b32_e64 v19, v79, v55, s[8:9]
	ds_bpermute_b32 v24, v50, v24
	v_cndmask_b32_e64 v25, v76, v84, s[8:9]
	s_waitcnt lgkmcnt(4)
	v_add_f32_e32 v19, v19, v20
	v_cndmask_b32_e64 v20, v80, v56, s[8:9]
	ds_bpermute_b32 v25, v50, v25
	v_cndmask_b32_e64 v26, v77, v85, s[8:9]
	v_cndmask_b32_e64 v27, v78, v18, s[8:9]
	s_waitcnt lgkmcnt(4)
	v_add_f32_e32 v20, v20, v21
	v_cndmask_b32_e64 v21, v81, v57, s[8:9]
	ds_bpermute_b32 v26, v50, v26
	ds_bpermute_b32 v27, v50, v27
	s_waitcnt lgkmcnt(5)
	v_add_f32_e32 v21, v21, v22
	v_cndmask_b32_e64 v22, v82, v58, s[8:9]
	s_waitcnt lgkmcnt(4)
	v_add_f32_e32 v22, v22, v23
	v_cndmask_b32_e64 v23, v83, v59, s[8:9]
	s_waitcnt lgkmcnt(3)
	v_add_f32_e32 v23, v23, v24
	v_cndmask_b32_e64 v24, v84, v76, s[8:9]
	s_waitcnt lgkmcnt(2)
	v_add_f32_e32 v24, v24, v25
	v_cndmask_b32_e64 v25, v85, v77, s[8:9]
	v_cndmask_b32_e64 v18, v18, v78, s[8:9]
	s_waitcnt lgkmcnt(1)
	v_add_f32_e32 v25, v25, v26
	s_waitcnt lgkmcnt(0)
	v_add_f32_e32 v18, v18, v27
	v_cndmask_b32_e64 v28, v19, v23, s[10:11]
	v_cndmask_b32_e64 v19, v23, v19, s[10:11]
	v_cndmask_b32_e64 v23, v24, v20, s[10:11]
	v_cndmask_b32_e64 v20, v20, v24, s[10:11]
	v_cndmask_b32_e64 v24, v21, v25, s[10:11]
	v_cndmask_b32_e64 v26, v22, v18, s[10:11]
	ds_bpermute_b32 v28, v49, v28
	ds_bpermute_b32 v20, v49, v20
	ds_bpermute_b32 v24, v49, v24
	ds_bpermute_b32 v26, v49, v26
	v_cndmask_b32_e64 v21, v25, v21, s[10:11]
	v_cndmask_b32_e64 v18, v18, v22, s[10:11]
	s_waitcnt lgkmcnt(3)
	v_add_f32_e32 v19, v19, v28
	s_waitcnt lgkmcnt(2)
	v_add_f32_e32 v20, v23, v20
	s_waitcnt lgkmcnt(1)
	v_add_f32_e32 v21, v21, v24
	s_waitcnt lgkmcnt(0)
	v_add_f32_e32 v18, v18, v26
	v_cndmask_b32_e64 v22, v19, v21, s[12:13]
	v_cndmask_b32_e64 v23, v20, v18, s[12:13]
	ds_bpermute_b32 v22, v48, v22
	ds_bpermute_b32 v23, v48, v23
	v_cndmask_b32_e64 v19, v21, v19, s[12:13]
	v_cndmask_b32_e64 v18, v18, v20, s[12:13]
	s_waitcnt lgkmcnt(1)
	v_add_f32_e32 v19, v19, v22
	s_waitcnt lgkmcnt(0)
	v_add_f32_e32 v18, v18, v23
	v_cndmask_b32_e64 v20, v19, v18, s[14:15]
	ds_bpermute_b32 v20, v47, v20
	v_cndmask_b32_e64 v18, v18, v19, s[14:15]
	s_waitcnt lgkmcnt(0)
	v_add_f32_e32 v18, v18, v20
	ds_bpermute_b32 v19, v46, v18
	s_waitcnt lgkmcnt(0)
	v_add_f32_e32 v18, v18, v19
	ds_bpermute_b32 v19, v1, v18
	s_and_saveexec_b64 s[60:61], s[16:17]
	s_cbranch_execz .LBB0_21
	global_load_dword v20, v[38:39], off
	v_fmamk_f32 v21, v43, 0x3a800000, v34
	s_waitcnt lgkmcnt(0)
	v_add_f32_e32 v22, v18, v19
	v_mul_f32_e32 v18, 0x4b800000, v21
	v_cmp_gt_f32_e32 vcc, s74, v21
	s_ashr_i32 s35, s26, 9
	s_and_b32 s26, s26, 0x1fff
	v_cndmask_b32_e32 v18, v21, v18, vcc
	v_rsq_f32_e32 v21, v18
	v_and_or_b32 v18, s35, -16, v52
	v_ashrrev_i32_e32 v19, 31, v18
	v_lshlrev_b64 v[18:19], 15, v[18:19]
	v_mul_f32_e32 v23, 0x45800000, v21
	v_cndmask_b32_e32 v21, v21, v23, vcc
	s_lshl_b32 s26, s26, 2
	v_lshl_add_u64 v[18:19], s[24:25], 0, v[18:19]
	v_lshl_add_u64 v[18:19], v[18:19], 0, s[26:27]
	s_waitcnt vmcnt(0)
	v_fmac_f32_e32 v20, v21, v22
	v_mul_f32_e64 v21, |v20|, s75
	v_fma_f32 v22, |v20|, s75, -v21
	v_rndne_f32_e32 v23, v21
	v_fma_f32 v22, |v20|, s76, v22
	v_sub_f32_e32 v21, v21, v23
	v_add_f32_e32 v21, v21, v22
	v_cvt_i32_f32_e32 v23, v23
	v_exp_f32_e32 v21, v21
	v_cmp_ngt_f32_e64 vcc, |v20|, s77
	v_min_f32_e32 v55, 0, v20
	v_ldexp_f32 v21, v21, v23
	v_cndmask_b32_e32 v21, 0, v21, vcc
	v_cmp_nlt_f32_e64 vcc, |v20|, s80
	s_nop 1
	v_cndmask_b32_e32 v56, v54, v21, vcc
	v_add_f32_e32 v22, 1.0, v56
	v_add_f32_e32 v23, -1.0, v22
	v_frexp_mant_f32_e32 v24, v22
	v_cvt_f64_f32_e32 v[20:21], v22
	v_sub_f32_e32 v25, v23, v22
	v_frexp_exp_i32_f64_e32 v20, v[20:21]
	v_cmp_gt_f32_e32 vcc, s82, v24
	v_sub_f32_e32 v23, v56, v23
	v_add_f32_e32 v21, 1.0, v25
	v_subbrev_co_u32_e32 v20, vcc, 0, v20, vcc
	v_add_f32_e32 v21, v23, v21
	v_sub_u32_e32 v23, 0, v20
	v_ldexp_f32 v22, v22, v23
	v_add_f32_e32 v24, -1.0, v22
	v_add_f32_e32 v25, 1.0, v22
	v_ldexp_f32 v21, v21, v23
	v_add_f32_e32 v23, 1.0, v24
	v_add_f32_e32 v26, -1.0, v25
	v_sub_f32_e32 v23, v22, v23
	v_sub_f32_e32 v22, v22, v26
	v_add_f32_e32 v26, v21, v23
	v_add_f32_e32 v21, v21, v22
	v_add_f32_e32 v28, v25, v21
	v_rcp_f32_e32 v29, v28
	v_add_f32_e32 v23, v24, v26
	v_sub_f32_e32 v24, v24, v23
	v_sub_f32_e32 v22, v25, v28
	v_mul_f32_e32 v31, v23, v29
	v_add_f32_e32 v30, v26, v24
	v_mul_f32_e32 v24, v28, v31
	v_add_f32_e32 v21, v21, v22
	v_fma_f32 v26, v31, v28, -v24
	v_fmac_f32_e32 v26, v31, v21
	v_add_f32_e32 v22, v24, v26
	v_sub_f32_e32 v25, v23, v22
	v_mov_b32_e32 v27, v22
	v_pk_add_f32 v[22:23], v[22:23], v[24:25] neg_lo:[0,1] neg_hi:[0,1]
	v_cvt_f32_i32_e32 v20, v20
	v_pk_add_f32 v[22:23], v[22:23], v[26:27] neg_lo:[0,1] neg_hi:[0,1]
	v_cmp_neq_f32_e32 vcc, s81, v56
	v_add_f32_e32 v23, v30, v23
	v_add_f32_e32 v22, v22, v23
	v_add_f32_e32 v23, v25, v22
	v_mul_f32_e32 v27, v29, v23
	v_mul_f32_e32 v24, v28, v27
	v_sub_f32_e32 v25, v25, v23
	v_add_f32_e32 v32, v31, v27
	v_fma_f32 v26, v27, v28, -v24
	v_add_f32_e32 v30, v22, v25
	v_sub_f32_e32 v22, v32, v31
	v_fmac_f32_e32 v26, v27, v21
	v_sub_f32_e32 v21, v27, v22
	v_add_f32_e32 v22, v24, v26
	v_sub_f32_e32 v25, v23, v22
	v_mov_b32_e32 v27, v22
	v_pk_add_f32 v[22:23], v[22:23], v[24:25] neg_lo:[0,1] neg_hi:[0,1]
	s_nop 0
	v_pk_add_f32 v[22:23], v[22:23], v[26:27] neg_lo:[0,1] neg_hi:[0,1]
	s_nop 0
	v_add_f32_e32 v23, v30, v23
	v_add_f32_e32 v22, v22, v23
	v_add_f32_e32 v22, v25, v22
	v_mul_f32_e32 v22, v29, v22
	v_add_f32_e32 v21, v21, v22
	v_add_f32_e32 v22, v32, v21
	v_mul_f32_e32 v24, v22, v22
	v_sub_f32_e32 v25, v22, v32
	v_fmamk_f32 v26, v24, 0x3e9b6dac, v53
	v_sub_f32_e32 v25, v21, v25
	v_mul_f32_e32 v21, v22, v24
	v_fmaak_f32 v43, v24, v26, 0x3f2aaada
	v_ldexp_f32 v27, v25, 1
	v_pk_mul_f32 v[24:25], v[20:21], v[42:43]
	v_ldexp_f32 v23, v22, 1
	v_fma_f32 v22, v20, s83, -v24
	v_fmac_f32_e32 v22, 0xb102e308, v20
	v_pk_add_f32 v[20:21], v[24:25], v[22:23]
	v_mov_b32_e32 v26, v24
	v_sub_f32_e32 v30, v21, v23
	v_pk_add_f32 v[28:29], v[20:21], v[24:25] neg_lo:[0,1] neg_hi:[0,1]
	v_sub_f32_e32 v24, v25, v30
	v_add_f32_e32 v27, v27, v24
	v_pk_add_f32 v[24:25], v[20:21], v[26:27]
	v_mov_b32_e32 v23, v20
	v_mov_b32_e32 v29, v25
	v_pk_add_f32 v[32:33], v[22:23], v[28:29] neg_lo:[0,1] neg_hi:[0,1]
	v_pk_add_f32 v[22:23], v[22:23], v[28:29]
	v_mov_b32_e32 v31, v20
	v_pk_add_f32 v[28:29], v[22:23], v[20:21] op_sel:[1,0] op_sel_hi:[0,1] neg_lo:[0,1] neg_hi:[0,1]
	v_mov_b32_e32 v30, v27
	v_mov_b32_e32 v26, v25
	v_mov_b32_e32 v27, v23
	v_pk_mov_b32 v[20:21], v[20:21], v[28:29] op_sel:[1,0]
	v_pk_add_f32 v[24:25], v[24:25], v[28:29] op_sel_hi:[1,0] neg_lo:[0,1] neg_hi:[0,1]
	v_pk_add_f32 v[20:21], v[26:27], v[20:21] neg_lo:[0,1] neg_hi:[0,1]
	v_mov_b32_e32 v24, v32
	v_pk_add_f32 v[20:21], v[30:31], v[20:21] neg_lo:[0,1] neg_hi:[0,1]
	v_mov_b32_e32 v33, v23
	v_pk_add_f32 v[24:25], v[24:25], v[20:21]
	s_nop 0
	v_pk_add_f32 v[26:27], v[24:25], v[24:25] op_sel:[0,1] op_sel_hi:[1,0]
	s_nop 0
	v_pk_add_f32 v[22:23], v[22:23], v[26:27] op_sel:[1,0] op_sel_hi:[0,1]
	v_mov_b32_e32 v25, v22
	v_mov_b32_e32 v21, v26
	v_pk_add_f32 v[26:27], v[24:25], v[32:33] neg_lo:[0,1] neg_hi:[0,1]
	s_nop 0
	v_sub_f32_e32 v23, v24, v26
	v_pk_add_f32 v[20:21], v[20:21], v[26:27] neg_lo:[0,1] neg_hi:[0,1]
	v_sub_f32_e32 v23, v32, v23
	v_add_f32_e32 v20, v20, v23
	v_add_f32_e32 v20, v20, v21
	v_add_f32_e32 v20, v22, v20
	v_cndmask_b32_e32 v20, v54, v20, vcc
	v_cmp_lt_f32_e64 vcc, |v56|, s85
	s_nop 1
	v_cndmask_b32_e32 v20, v20, v56, vcc
	v_sub_f32_e32 v20, v55, v20
	global_store_dword v[18:19], v20, off sc1
	s_branch .LBB0_21

.LBB0_30:
	v_ashrrev_i32_e32 v6, 5, v4
	v_cvt_f32_i32_e32 v8, v6
	v_ashrrev_i32_e32 v3, 31, v2
	v_lshl_add_u64 v[6:7], v[2:3], 2, s[8:9]
	v_add_u32_e32 v4, s4, v4
	v_mul_f32_e32 v3, v5, v8
	v_cvt_f64_f32_e32 v[8:9], v3
	v_mul_f64 v[10:11], v[8:9], s[12:13]
	v_rndne_f64_e32 v[10:11], v[10:11]
	v_fma_f64 v[8:9], v[8:9], s[12:13], -v[10:11]
	v_cvt_f32_f64_e32 v3, v[8:9]
	v_cos_f32_e32 v8, v3
	v_sin_f32_e32 v9, v3
	v_cmp_lt_i32_e32 vcc, s14, v4
	v_add_u32_e32 v2, s5, v2
	s_or_b64 s[10:11], vcc, s[10:11]
	global_store_dwordx2 v[6:7], v[8:9], off sc1
	s_andn2_b64 exec, exec, s[10:11]
	s_cbranch_execnz .LBB0_30

.LBB0_33:
	s_waitcnt lgkmcnt(0)
	ds_read2_b32 v[8:9], v51 offset1:8
	ds_read2_b32 v[68:69], v51 offset0:66 offset1:74
	ds_read2_b32 v[72:73], v51 offset0:33 offset1:41
	ds_read2_b32 v[74:75], v51 offset0:99 offset1:107
	ds_read2_b32 v[76:77], v51 offset0:132 offset1:140
	ds_read2_b32 v[78:79], v51 offset0:198 offset1:206
	ds_read2_b32 v[80:81], v51 offset0:165 offset1:173
	ds_read2_b32 v[82:83], v51 offset0:231 offset1:239
	s_waitcnt lgkmcnt(7)
	v_mov_b32_e32 v64, v8
	s_waitcnt lgkmcnt(5)
	v_mov_b32_e32 v66, v72
	s_waitcnt lgkmcnt(4)
	v_mov_b32_e32 v67, v74
	v_mov_b32_e32 v65, v68
	v_pk_mul_f32 v[66:67], v[46:47], v[66:67]
	v_pk_mul_f32 v[64:65], v[2:3], v[64:65]
	s_waitcnt lgkmcnt(3)
	v_mov_b32_e32 v84, v76
	s_waitcnt lgkmcnt(2)
	v_mov_b32_e32 v85, v78
	v_bfe_u32 v68, v67, 16, 1
	v_pk_mul_f32 v[84:85], v[6:7], v[84:85]
	s_waitcnt lgkmcnt(1)
	v_mov_b32_e32 v86, v80
	s_waitcnt lgkmcnt(0)
	v_mov_b32_e32 v87, v82
	v_add3_u32 v68, v67, v68, s89
	v_bfe_u32 v67, v65, 16, 1
	v_pk_mul_f32 v[86:87], v[4:5], v[86:87]
	v_bfe_u32 v72, v66, 16, 1
	v_bfe_u32 v74, v84, 16, 1
	v_bfe_u32 v76, v85, 16, 1
	v_add3_u32 v65, v65, v67, s89
	v_bfe_u32 v8, v87, 16, 1
	v_add3_u32 v72, v66, v72, s89
	v_bfe_u32 v66, v64, 16, 1
	v_add3_u32 v76, v85, v76, s89
	v_add3_u32 v74, v84, v74, s89
	v_lshrrev_b32_e32 v65, 16, v65
	v_add_u32_e32 v84, s4, v50
	v_bfe_u32 v10, v86, 16, 1
	v_add3_u32 v8, v87, v8, s89
	v_add3_u32 v64, v64, v66, s89
	v_lshrrev_b32_e32 v67, 16, v76
	v_and_or_b32 v65, v68, s90, v65
	v_ashrrev_i32_e32 v85, 31, v84
	v_mov_b32_e32 v68, v9
	v_mov_b32_e32 v82, v81
	v_lshl_add_u64 v[70:71], s[28:29], 1, v[44:45]
	v_add3_u32 v10, v86, v10, s89
	v_lshrrev_b32_e32 v64, 16, v64
	v_lshrrev_b32_e32 v66, 16, v74
	v_and_or_b32 v67, v8, s90, v67
	v_lshlrev_b64 v[86:87], 11, v[84:85]
	v_pk_mul_f32 v[8:9], v[2:3], v[68:69]
	v_pk_mul_f32 v[68:69], v[4:5], v[82:83]
	v_and_or_b32 v66, v10, s90, v66
	v_and_or_b32 v64, v72, s90, v64
	v_lshl_add_u64 v[86:87], v[70:71], 0, v[86:87]
	v_mov_b32_e32 v74, v73
	v_bfe_u32 v10, v69, 16, 1
	global_store_dwordx4 v[86:87], v[64:67], off sc1
	v_bfe_u32 v72, v68, 16, 1
	v_add3_u32 v10, v69, v10, s89
	v_pk_mul_f32 v[64:65], v[46:47], v[74:75]
	v_bfe_u32 v69, v8, 16, 1
	v_mov_b32_e32 v78, v77
	v_bfe_u32 v74, v64, 16, 1
	v_add3_u32 v68, v68, v72, s89
	v_bfe_u32 v72, v9, 16, 1
	v_add3_u32 v8, v8, v69, s89
	v_pk_mul_f32 v[66:67], v[6:7], v[78:79]
	v_bfe_u32 v73, v65, 16, 1
	v_add3_u32 v64, v64, v74, s89
	v_add3_u32 v9, v9, v72, s89
	v_lshrrev_b32_e32 v8, 16, v8
	v_add3_u32 v65, v65, v73, s89
	v_bfe_u32 v73, v66, 16, 1
	v_bfe_u32 v74, v67, 16, 1
	v_lshrrev_b32_e32 v9, 16, v9
	v_and_or_b32 v64, v64, s90, v8
	v_add_u32_e32 v8, 8, v84
	v_add3_u32 v67, v67, v74, s89
	v_add3_u32 v66, v66, v73, s89
	v_and_or_b32 v65, v65, s90, v9
	v_ashrrev_i32_e32 v9, 31, v8
	v_lshrrev_b32_e32 v66, 16, v66
	v_lshrrev_b32_e32 v67, 16, v67
	v_lshlrev_b64 v[8:9], 11, v[8:9]
	v_and_or_b32 v67, v10, s90, v67
	v_and_or_b32 v66, v68, s90, v66
	v_lshl_add_u64 v[8:9], v[70:71], 0, v[8:9]
	ds_read2_b32 v[68:69], v51 offset0:16 offset1:24
	ds_read2_b32 v[72:73], v51 offset0:82 offset1:90
	global_store_dwordx4 v[8:9], v[64:67], off sc1
	ds_read2_b32 v[8:9], v51 offset0:49 offset1:57
	ds_read2_b32 v[74:75], v51 offset0:115 offset1:123
	ds_read2_b32 v[76:77], v51 offset0:148 offset1:156
	ds_read2_b32 v[78:79], v51 offset0:214 offset1:222
	ds_read2_b32 v[80:81], v51 offset0:181 offset1:189
	ds_read2_b32 v[82:83], v51 offset0:247 offset1:255
	s_waitcnt lgkmcnt(7)
	v_mov_b32_e32 v64, v68
	s_waitcnt lgkmcnt(5)
	v_mov_b32_e32 v66, v8
	s_waitcnt lgkmcnt(4)
	v_mov_b32_e32 v67, v74
	s_waitcnt lgkmcnt(3)
	v_mov_b32_e32 v86, v76
	s_waitcnt lgkmcnt(2)
	v_mov_b32_e32 v87, v78
	v_mov_b32_e32 v65, v72
	v_pk_mul_f32 v[66:67], v[46:47], v[66:67]
	v_pk_mul_f32 v[86:87], v[6:7], v[86:87]
	s_waitcnt lgkmcnt(1)
	v_mov_b32_e32 v88, v80
	s_waitcnt lgkmcnt(0)
	v_mov_b32_e32 v89, v82
	v_pk_mul_f32 v[64:65], v[2:3], v[64:65]
	v_pk_mul_f32 v[88:89], v[4:5], v[88:89]
	v_bfe_u32 v68, v67, 16, 1
	v_bfe_u32 v72, v66, 16, 1
	v_bfe_u32 v74, v86, 16, 1
	v_bfe_u32 v76, v87, 16, 1
	v_bfe_u32 v8, v89, 16, 1
	v_add3_u32 v72, v66, v72, s89
	v_add3_u32 v68, v67, v68, s89
	v_bfe_u32 v66, v64, 16, 1
	v_bfe_u32 v67, v65, 16, 1
	v_add3_u32 v76, v87, v76, s89
	v_add3_u32 v74, v86, v74, s89
	v_add_u32_e32 v86, 16, v84
	v_bfe_u32 v10, v88, 16, 1
	v_add3_u32 v8, v89, v8, s89
	v_add3_u32 v65, v65, v67, s89
	v_add3_u32 v64, v64, v66, s89
	v_lshrrev_b32_e32 v66, 16, v74
	v_lshrrev_b32_e32 v67, 16, v76
	v_ashrrev_i32_e32 v87, 31, v86
	v_mov_b32_e32 v74, v9
	v_add3_u32 v10, v88, v10, s89
	v_lshrrev_b32_e32 v64, 16, v64
	v_lshrrev_b32_e32 v65, 16, v65
	v_and_or_b32 v67, v8, s90, v67
	v_lshlrev_b64 v[86:87], 11, v[86:87]
	v_pk_mul_f32 v[8:9], v[46:47], v[74:75]
	v_mov_b32_e32 v78, v77
	v_and_or_b32 v66, v10, s90, v66
	v_and_or_b32 v65, v68, s90, v65
	v_and_or_b32 v64, v72, s90, v64
	v_lshl_add_u64 v[86:87], v[70:71], 0, v[86:87]
	v_pk_mul_f32 v[6:7], v[6:7], v[78:79]
	v_mov_b32_e32 v82, v81
	v_bfe_u32 v47, v9, 16, 1
	global_store_dwordx4 v[86:87], v[64:67], off sc1
	v_pk_mul_f32 v[4:5], v[4:5], v[82:83]
	v_add3_u32 v9, v9, v47, s89
	v_bfe_u32 v64, v8, 16, 1
	v_bfe_u32 v47, v6, 16, 1
	v_mov_b32_e32 v72, v69
	v_bfe_u32 v46, v4, 16, 1
	v_add3_u32 v8, v8, v64, s89
	v_bfe_u32 v64, v7, 16, 1
	v_add3_u32 v6, v6, v47, s89
	v_pk_mul_f32 v[2:3], v[2:3], v[72:73]
	v_bfe_u32 v10, v5, 16, 1
	v_add3_u32 v4, v4, v46, s89
	v_add3_u32 v7, v7, v64, s89
	v_lshrrev_b32_e32 v6, 16, v6
	v_add3_u32 v5, v5, v10, s89
	v_bfe_u32 v10, v2, 16, 1
	v_bfe_u32 v46, v3, 16, 1
	v_lshrrev_b32_e32 v7, 16, v7
	v_and_or_b32 v4, v4, s90, v6
	v_add_u32_e32 v6, 24, v84
	v_add3_u32 v3, v3, v46, s89
	v_add3_u32 v2, v2, v10, s89
	v_and_or_b32 v5, v5, s90, v7
	v_ashrrev_i32_e32 v7, 31, v6
	v_lshrrev_b32_e32 v2, 16, v2
	v_lshrrev_b32_e32 v3, 16, v3
	v_lshlrev_b64 v[6:7], 11, v[6:7]
	v_and_or_b32 v3, v9, s90, v3
	v_and_or_b32 v2, v8, s90, v2
	v_lshl_add_u64 v[6:7], v[70:71], 0, v[6:7]
	global_store_dwordx4 v[6:7], v[2:5], off sc1
	s_waitcnt lgkmcnt(0)

.LBB0_35:
	s_cmpk_gt_i32 s18, 0x5ff
	s_mov_b64 s[28:29], -1
	s_cbranch_scc0 .LBB0_102
	s_cmpk_gt_u32 s18, 0x7ff
	s_cbranch_scc0 .LBB0_99
	s_cmpk_gt_u32 s18, 0x97f
	s_cbranch_scc0 .LBB0_80
	s_cmpk_gt_u32 s18, 0xa7f
	s_cbranch_scc0 .LBB0_74
	s_cmpk_gt_u32 s18, 0xb9f
	s_cbranch_scc0 .LBB0_64
	s_cmpk_gt_u32 s18, 0xd9f
	s_cbranch_scc0 .LBB0_60
	s_cmpk_gt_u32 s18, 0x159f
	s_cbranch_scc0 .LBB0_54
	s_cmpk_gt_u32 s18, 0x1d9f
	s_cbranch_scc0 .LBB0_50
	s_cmpk_gt_u32 s18, 0x259f
	s_cbranch_scc0 .LBB0_47
	s_andn2_b64 vcc, exec, s[78:79]
	s_cbranch_vccnz .LBB0_46
	s_and_b32 s5, s21, 0x7fffffc0
	s_and_b32 s4, s3, 0x3e0
	v_or_b32_e32 v10, s5, v48
	v_or_b32_e32 v4, s4, v1
	v_lshlrev_b64 v[2:3], 12, v[10:11]
	v_lshl_add_u64 v[2:3], s[6:7], 0, v[2:3]
	v_lshlrev_b32_e32 v10, 2, v4
	v_lshl_add_u64 v[2:3], v[2:3], 0, v[10:11]
	v_add_co_u32_e32 v4, vcc, 0x2000, v2
	s_lshl_b32 s26, s5, 1
	s_nop 0
	v_addc_co_u32_e32 v5, vcc, 0, v3, vcc
	v_add_co_u32_e32 v6, vcc, 0x4000, v2
	s_nop 1
	v_addc_co_u32_e32 v7, vcc, 0, v3, vcc
	v_add_co_u32_e32 v8, vcc, 0x6000, v2
	s_nop 1
	v_addc_co_u32_e32 v9, vcc, 0, v3, vcc
	v_add_co_u32_e32 v46, vcc, 0x8000, v2
	s_nop 1
	v_addc_co_u32_e32 v47, vcc, 0, v3, vcc
	v_add_co_u32_e32 v64, vcc, 0xa000, v2
	s_nop 1
	v_addc_co_u32_e32 v65, vcc, 0, v3, vcc
	v_add_co_u32_e32 v66, vcc, 0xc000, v2
	s_nop 1
	v_addc_co_u32_e32 v67, vcc, 0, v3, vcc
	v_add_co_u32_e32 v68, vcc, 0xe000, v2
	s_nop 1
	v_addc_co_u32_e32 v69, vcc, 0, v3, vcc
	global_load_dword v10, v[2:3], off
	global_load_dword v72, v[4:5], off
	global_load_dword v73, v[6:7], off
	global_load_dword v74, v[8:9], off
	global_load_dword v75, v[46:47], off
	global_load_dword v76, v[64:65], off
	global_load_dword v77, v[66:67], off
	global_load_dword v78, v[68:69], off
	v_add_co_u32_e32 v4, vcc, 0x10000, v2
	s_nop 1
	v_addc_co_u32_e32 v5, vcc, 0, v3, vcc
	v_add_co_u32_e32 v6, vcc, 0x12000, v2
	s_nop 1
	v_addc_co_u32_e32 v7, vcc, 0, v3, vcc
	v_add_co_u32_e32 v8, vcc, 0x14000, v2
	s_nop 1
	v_addc_co_u32_e32 v9, vcc, 0, v3, vcc
	v_add_co_u32_e32 v46, vcc, 0x16000, v2
	s_nop 1
	v_addc_co_u32_e32 v47, vcc, 0, v3, vcc
	v_add_co_u32_e32 v64, vcc, 0x18000, v2
	s_nop 1
	v_addc_co_u32_e32 v65, vcc, 0, v3, vcc
	v_add_co_u32_e32 v66, vcc, 0x1a000, v2
	s_nop 1
	v_addc_co_u32_e32 v67, vcc, 0, v3, vcc
	v_add_co_u32_e32 v68, vcc, 0x1c000, v2
	s_nop 1
	v_addc_co_u32_e32 v69, vcc, 0, v3, vcc
	v_add_co_u32_e32 v70, vcc, 0x1e000, v2
	s_nop 1
	v_addc_co_u32_e32 v71, vcc, 0, v3, vcc
	global_load_dword v79, v[4:5], off
	global_load_dword v80, v[6:7], off
	global_load_dword v81, v[8:9], off
	global_load_dword v82, v[46:47], off
	global_load_dword v83, v[64:65], off
	global_load_dword v84, v[66:67], off
	global_load_dword v85, v[68:69], off
	global_load_dword v86, v[70:71], off
	v_add_co_u32_e32 v4, vcc, 0x20000, v2
	s_nop 1
	v_addc_co_u32_e32 v5, vcc, 0, v3, vcc
	v_add_co_u32_e32 v6, vcc, 0x22000, v2
	s_nop 1
	v_addc_co_u32_e32 v7, vcc, 0, v3, vcc
	v_add_co_u32_e32 v8, vcc, 0x24000, v2
	s_nop 1
	v_addc_co_u32_e32 v9, vcc, 0, v3, vcc
	v_add_co_u32_e32 v46, vcc, 0x26000, v2
	s_nop 1
	v_addc_co_u32_e32 v47, vcc, 0, v3, vcc
	v_add_co_u32_e32 v64, vcc, 0x28000, v2
	s_nop 1
	v_addc_co_u32_e32 v65, vcc, 0, v3, vcc
	v_add_co_u32_e32 v66, vcc, 0x2a000, v2
	s_nop 1
	v_addc_co_u32_e32 v67, vcc, 0, v3, vcc
	v_add_co_u32_e32 v68, vcc, 0x2c000, v2
	s_nop 1
	v_addc_co_u32_e32 v69, vcc, 0, v3, vcc
	v_add_co_u32_e32 v70, vcc, 0x2e000, v2
	s_nop 1
	v_addc_co_u32_e32 v71, vcc, 0, v3, vcc
	global_load_dword v87, v[4:5], off
	global_load_dword v88, v[6:7], off
	global_load_dword v89, v[8:9], off
	global_load_dword v90, v[46:47], off
	global_load_dword v91, v[64:65], off
	global_load_dword v92, v[66:67], off
	global_load_dword v93, v[68:69], off
	s_nop 0
	global_load_dword v70, v[70:71], off
	v_add_co_u32_e32 v4, vcc, 0x30000, v2
	s_nop 1
	v_addc_co_u32_e32 v5, vcc, 0, v3, vcc
	v_add_co_u32_e32 v6, vcc, 0x32000, v2
	s_nop 1
	v_addc_co_u32_e32 v7, vcc, 0, v3, vcc
	v_add_co_u32_e32 v8, vcc, 0x34000, v2
	s_nop 1
	v_addc_co_u32_e32 v9, vcc, 0, v3, vcc
	v_add_co_u32_e32 v46, vcc, 0x36000, v2
	s_nop 1
	v_addc_co_u32_e32 v47, vcc, 0, v3, vcc
	v_add_co_u32_e32 v64, vcc, 0x38000, v2
	s_nop 1
	v_addc_co_u32_e32 v65, vcc, 0, v3, vcc
	v_add_co_u32_e32 v66, vcc, 0x3a000, v2
	s_nop 1
	v_addc_co_u32_e32 v67, vcc, 0, v3, vcc
	v_add_co_u32_e32 v68, vcc, 0x3c000, v2
	s_nop 1
	v_addc_co_u32_e32 v69, vcc, 0, v3, vcc
	v_add_co_u32_e32 v2, vcc, 0x3e000, v2
	s_nop 1
	v_addc_co_u32_e32 v3, vcc, 0, v3, vcc
	global_load_dword v4, v[4:5], off
	s_nop 0
	global_load_dword v5, v[6:7], off
	s_nop 0
	global_load_dword v6, v[8:9], off
	global_load_dword v7, v[46:47], off
	s_nop 0
	global_load_dword v8, v[64:65], off
	global_load_dword v9, v[66:67], off
	global_load_dword v46, v[68:69], off
	s_nop 0
	global_load_dword v2, v[2:3], off
	s_waitcnt vmcnt(30)
	ds_write2_b32 v49, v10, v72 offset1:66
	s_waitcnt vmcnt(28)
	ds_write2_b32 v49, v73, v74 offset0:132 offset1:198
	s_waitcnt vmcnt(26)
	ds_write2_b32 v57, v75, v76 offset0:8 offset1:74
	s_waitcnt vmcnt(24)
	ds_write2_b32 v57, v77, v78 offset0:140 offset1:206
	s_waitcnt vmcnt(22)
	ds_write2_b32 v58, v79, v80 offset0:16 offset1:82
	s_waitcnt vmcnt(20)
	ds_write2_b32 v58, v81, v82 offset0:148 offset1:214
	s_waitcnt vmcnt(18)
	ds_write2_b32 v59, v83, v84 offset0:24 offset1:90
	s_waitcnt vmcnt(16)
	ds_write2_b32 v59, v85, v86 offset0:156 offset1:222
	s_waitcnt vmcnt(14)
	ds_write2_b32 v60, v87, v88 offset0:32 offset1:98
	s_waitcnt vmcnt(12)
	ds_write2_b32 v60, v89, v90 offset0:164 offset1:230
	s_waitcnt vmcnt(10)
	ds_write2_b32 v61, v91, v92 offset0:40 offset1:106
	s_waitcnt vmcnt(8)
	ds_write2_b32 v61, v93, v70 offset0:172 offset1:238
	s_waitcnt vmcnt(6)
	ds_write2_b32 v62, v4, v5 offset0:48 offset1:114
	s_waitcnt vmcnt(4)
	ds_write2_b32 v62, v6, v7 offset0:180 offset1:246
	s_waitcnt vmcnt(2)
	ds_write2_b32 v63, v8, v9 offset0:56 offset1:122
	s_waitcnt vmcnt(0)
	ds_write2_b32 v63, v46, v2 offset0:188 offset1:254
	s_waitcnt lgkmcnt(0)
	ds_read2_b32 v[6:7], v51 offset1:8
	ds_read2_b32 v[46:47], v51 offset0:33 offset1:41
	ds_read2_b32 v[64:65], v51 offset0:66 offset1:74
	ds_read2_b32 v[66:67], v51 offset0:99 offset1:107
	ds_read2_b32 v[68:69], v51 offset0:132 offset1:140
	s_waitcnt lgkmcnt(4)
	v_bfe_u32 v2, v6, 16, 1
	v_add3_u32 v2, v6, v2, s89
	s_waitcnt lgkmcnt(3)
	v_bfe_u32 v3, v46, 16, 1
	v_lshrrev_b32_e32 v2, 16, v2
	v_add3_u32 v3, v46, v3, s89
	ds_read2_b32 v[70:71], v51 offset0:165 offset1:173
	v_and_or_b32 v2, v3, s90, v2
	s_waitcnt lgkmcnt(3)
	v_bfe_u32 v3, v64, 16, 1
	v_add3_u32 v3, v64, v3, s89
	s_waitcnt lgkmcnt(2)
	v_bfe_u32 v4, v66, 16, 1
	ds_read2_b32 v[72:73], v51 offset0:198 offset1:206
	v_lshrrev_b32_e32 v3, 16, v3
	v_add3_u32 v4, v66, v4, s89
	ds_read2_b32 v[74:75], v51 offset0:231 offset1:239
	v_and_or_b32 v3, v4, s90, v3
	s_waitcnt lgkmcnt(3)
	v_bfe_u32 v4, v68, 16, 1
	v_add3_u32 v4, v68, v4, s89
	s_waitcnt lgkmcnt(2)
	v_bfe_u32 v5, v70, 16, 1
	v_lshrrev_b32_e32 v4, 16, v4
	v_add3_u32 v5, v70, v5, s89
	v_and_or_b32 v4, v5, s90, v4
	s_waitcnt lgkmcnt(1)
	v_bfe_u32 v5, v72, 16, 1
	v_add3_u32 v5, v72, v5, s89
	s_waitcnt lgkmcnt(0)
	v_bfe_u32 v6, v74, 16, 1
	v_lshrrev_b32_e32 v5, 16, v5
	v_add3_u32 v6, v74, v6, s89
	v_and_or_b32 v5, v6, s90, v5
	v_or_b32_e32 v6, s4, v50
	v_lshl_add_u64 v[8:9], v[12:13], 0, s[26:27]
	v_lshlrev_b32_e32 v10, 13, v6
	v_lshl_add_u64 v[76:77], v[8:9], 0, v[10:11]
	global_store_dwordx4 v[76:77], v[2:5], off sc1
	v_bfe_u32 v6, v75, 16, 1
	v_or_b32_e32 v10, s4, v52
	v_bfe_u32 v2, v7, 16, 1
	v_add3_u32 v2, v7, v2, s89
	v_bfe_u32 v3, v47, 16, 1
	v_lshrrev_b32_e32 v2, 16, v2
	v_add3_u32 v3, v47, v3, s89
	v_and_or_b32 v2, v3, s90, v2
	v_bfe_u32 v3, v65, 16, 1
	v_add3_u32 v3, v65, v3, s89
	v_bfe_u32 v4, v67, 16, 1
	v_lshrrev_b32_e32 v3, 16, v3
	v_add3_u32 v4, v67, v4, s89
	v_and_or_b32 v3, v4, s90, v3
	v_bfe_u32 v4, v69, 16, 1
	v_add3_u32 v4, v69, v4, s89
	v_bfe_u32 v5, v71, 16, 1
	v_lshrrev_b32_e32 v4, 16, v4
	v_add3_u32 v5, v71, v5, s89
	v_and_or_b32 v4, v5, s90, v4
	v_bfe_u32 v5, v73, 16, 1
	v_add3_u32 v5, v73, v5, s89
	v_lshrrev_b32_e32 v5, 16, v5
	v_add3_u32 v6, v75, v6, s89
	v_lshlrev_b32_e32 v10, 13, v10
	v_and_or_b32 v5, v6, s90, v5
	ds_read2_b32 v[6:7], v51 offset0:16 offset1:24
	v_lshl_add_u64 v[46:47], v[8:9], 0, v[10:11]
	global_store_dwordx4 v[46:47], v[2:5], off sc1
	ds_read2_b32 v[46:47], v51 offset0:49 offset1:57
	ds_read2_b32 v[64:65], v51 offset0:82 offset1:90
	ds_read2_b32 v[66:67], v51 offset0:115 offset1:123
	s_waitcnt lgkmcnt(3)
	v_bfe_u32 v2, v6, 16, 1
	v_add3_u32 v2, v6, v2, s89
	s_waitcnt lgkmcnt(2)
	v_bfe_u32 v3, v46, 16, 1
	ds_read2_b32 v[68:69], v51 offset0:148 offset1:156
	v_lshrrev_b32_e32 v2, 16, v2
	v_add3_u32 v3, v46, v3, s89
	ds_read2_b32 v[70:71], v51 offset0:181 offset1:189
	v_and_or_b32 v2, v3, s90, v2
	s_waitcnt lgkmcnt(3)
	v_bfe_u32 v3, v64, 16, 1
	v_add3_u32 v3, v64, v3, s89
	s_waitcnt lgkmcnt(2)
	v_bfe_u32 v4, v66, 16, 1
	ds_read2_b32 v[72:73], v51 offset0:214 offset1:222
	v_lshrrev_b32_e32 v3, 16, v3
	v_add3_u32 v4, v66, v4, s89
	ds_read2_b32 v[74:75], v51 offset0:247 offset1:255
	v_and_or_b32 v3, v4, s90, v3
	s_waitcnt lgkmcnt(3)
	v_bfe_u32 v4, v68, 16, 1
	v_add3_u32 v4, v68, v4, s89
	s_waitcnt lgkmcnt(2)
	v_bfe_u32 v5, v70, 16, 1
	v_lshrrev_b32_e32 v4, 16, v4
	v_add3_u32 v5, v70, v5, s89
	v_and_or_b32 v4, v5, s90, v4
	s_waitcnt lgkmcnt(1)
	v_bfe_u32 v5, v72, 16, 1
	v_add3_u32 v5, v72, v5, s89
	s_waitcnt lgkmcnt(0)
	v_bfe_u32 v6, v74, 16, 1
	v_lshrrev_b32_e32 v5, 16, v5
	v_add3_u32 v6, v74, v6, s89
	v_and_or_b32 v5, v6, s90, v5
	v_or_b32_e32 v6, s4, v53
	v_lshlrev_b32_e32 v10, 13, v6
	v_lshl_add_u64 v[76:77], v[8:9], 0, v[10:11]
	global_store_dwordx4 v[76:77], v[2:5], off sc1
	v_bfe_u32 v6, v75, 16, 1
	v_add3_u32 v6, v75, v6, s89
	v_bfe_u32 v2, v7, 16, 1
	v_add3_u32 v2, v7, v2, s89
	v_bfe_u32 v3, v47, 16, 1
	v_lshrrev_b32_e32 v2, 16, v2
	v_add3_u32 v3, v47, v3, s89
	v_and_or_b32 v2, v3, s90, v2
	v_bfe_u32 v3, v65, 16, 1
	v_add3_u32 v3, v65, v3, s89
	v_bfe_u32 v4, v67, 16, 1
	v_lshrrev_b32_e32 v3, 16, v3
	v_add3_u32 v4, v67, v4, s89
	v_and_or_b32 v3, v4, s90, v3
	v_bfe_u32 v4, v69, 16, 1
	v_add3_u32 v4, v69, v4, s89
	v_bfe_u32 v5, v71, 16, 1
	v_lshrrev_b32_e32 v4, 16, v4
	v_add3_u32 v5, v71, v5, s89
	v_and_or_b32 v4, v5, s90, v4
	v_bfe_u32 v5, v73, 16, 1
	v_add3_u32 v5, v73, v5, s89
	v_lshrrev_b32_e32 v5, 16, v5
	v_and_or_b32 v5, v6, s90, v5
	v_or_b32_e32 v6, s4, v54
	v_lshlrev_b32_e32 v10, 13, v6
	v_lshl_add_u64 v[6:7], v[8:9], 0, v[10:11]
	global_store_dwordx4 v[6:7], v[2:5], off sc1
	s_waitcnt lgkmcnt(0)

.LBB0_47:
	s_andn2_b64 vcc, exec, s[28:29]
	s_cbranch_vccnz .LBB0_49
	s_add_i32 s4, s21, 0x1000
	s_and_b32 s5, s4, 0x7fffffc0
	s_and_b32 s4, s3, 0x3e0
	v_or_b32_e32 v10, s5, v48
	v_or_b32_e32 v4, s4, v1
	v_lshlrev_b64 v[2:3], 12, v[10:11]
	v_lshl_add_u64 v[2:3], s[50:51], 0, v[2:3]
	v_lshlrev_b32_e32 v10, 2, v4
	v_lshl_add_u64 v[2:3], v[2:3], 0, v[10:11]
	v_add_co_u32_e32 v4, vcc, 0x2000, v2
	s_lshl_b32 s26, s5, 1
	s_nop 0
	v_addc_co_u32_e32 v5, vcc, 0, v3, vcc
	v_add_co_u32_e32 v6, vcc, 0x4000, v2
	s_nop 1
	v_addc_co_u32_e32 v7, vcc, 0, v3, vcc
	v_add_co_u32_e32 v8, vcc, 0x6000, v2
	s_nop 1
	v_addc_co_u32_e32 v9, vcc, 0, v3, vcc
	v_add_co_u32_e32 v46, vcc, 0x8000, v2
	s_nop 1
	v_addc_co_u32_e32 v47, vcc, 0, v3, vcc
	v_add_co_u32_e32 v64, vcc, 0xa000, v2
	s_nop 1
	v_addc_co_u32_e32 v65, vcc, 0, v3, vcc
	v_add_co_u32_e32 v66, vcc, 0xc000, v2
	s_nop 1
	v_addc_co_u32_e32 v67, vcc, 0, v3, vcc
	v_add_co_u32_e32 v68, vcc, 0xe000, v2
	s_nop 1
	v_addc_co_u32_e32 v69, vcc, 0, v3, vcc
	global_load_dword v10, v[2:3], off
	global_load_dword v72, v[4:5], off
	global_load_dword v73, v[6:7], off
	global_load_dword v74, v[8:9], off
	global_load_dword v75, v[46:47], off
	global_load_dword v76, v[64:65], off
	global_load_dword v77, v[66:67], off
	global_load_dword v78, v[68:69], off
	v_add_co_u32_e32 v4, vcc, 0x10000, v2
	s_nop 1
	v_addc_co_u32_e32 v5, vcc, 0, v3, vcc
	v_add_co_u32_e32 v6, vcc, 0x12000, v2
	s_nop 1
	v_addc_co_u32_e32 v7, vcc, 0, v3, vcc
	v_add_co_u32_e32 v8, vcc, 0x14000, v2
	s_nop 1
	v_addc_co_u32_e32 v9, vcc, 0, v3, vcc
	v_add_co_u32_e32 v46, vcc, 0x16000, v2
	s_nop 1
	v_addc_co_u32_e32 v47, vcc, 0, v3, vcc
	v_add_co_u32_e32 v64, vcc, 0x18000, v2
	s_nop 1
	v_addc_co_u32_e32 v65, vcc, 0, v3, vcc
	v_add_co_u32_e32 v66, vcc, 0x1a000, v2
	s_nop 1
	v_addc_co_u32_e32 v67, vcc, 0, v3, vcc
	v_add_co_u32_e32 v68, vcc, 0x1c000, v2
	s_nop 1
	v_addc_co_u32_e32 v69, vcc, 0, v3, vcc
	v_add_co_u32_e32 v70, vcc, 0x1e000, v2
	s_nop 1
	v_addc_co_u32_e32 v71, vcc, 0, v3, vcc
	global_load_dword v79, v[4:5], off
	global_load_dword v80, v[6:7], off
	global_load_dword v81, v[8:9], off
	global_load_dword v82, v[46:47], off
	global_load_dword v83, v[64:65], off
	global_load_dword v84, v[66:67], off
	global_load_dword v85, v[68:69], off
	global_load_dword v86, v[70:71], off
	v_add_co_u32_e32 v4, vcc, 0x20000, v2
	s_nop 1
	v_addc_co_u32_e32 v5, vcc, 0, v3, vcc
	v_add_co_u32_e32 v6, vcc, 0x22000, v2
	s_nop 1
	v_addc_co_u32_e32 v7, vcc, 0, v3, vcc
	v_add_co_u32_e32 v8, vcc, 0x24000, v2
	s_nop 1
	v_addc_co_u32_e32 v9, vcc, 0, v3, vcc
	v_add_co_u32_e32 v46, vcc, 0x26000, v2
	s_nop 1
	v_addc_co_u32_e32 v47, vcc, 0, v3, vcc
	v_add_co_u32_e32 v64, vcc, 0x28000, v2
	s_nop 1
	v_addc_co_u32_e32 v65, vcc, 0, v3, vcc
	v_add_co_u32_e32 v66, vcc, 0x2a000, v2
	s_nop 1
	v_addc_co_u32_e32 v67, vcc, 0, v3, vcc
	v_add_co_u32_e32 v68, vcc, 0x2c000, v2
	s_nop 1
	v_addc_co_u32_e32 v69, vcc, 0, v3, vcc
	v_add_co_u32_e32 v70, vcc, 0x2e000, v2
	s_nop 1
	v_addc_co_u32_e32 v71, vcc, 0, v3, vcc
	global_load_dword v87, v[4:5], off
	global_load_dword v88, v[6:7], off
	global_load_dword v89, v[8:9], off
	global_load_dword v90, v[46:47], off
	global_load_dword v91, v[64:65], off
	global_load_dword v92, v[66:67], off
	global_load_dword v93, v[68:69], off
	s_nop 0
	global_load_dword v70, v[70:71], off
	v_add_co_u32_e32 v4, vcc, 0x30000, v2
	s_nop 1
	v_addc_co_u32_e32 v5, vcc, 0, v3, vcc
	v_add_co_u32_e32 v6, vcc, 0x32000, v2
	s_nop 1
	v_addc_co_u32_e32 v7, vcc, 0, v3, vcc
	v_add_co_u32_e32 v8, vcc, 0x34000, v2
	s_nop 1
	v_addc_co_u32_e32 v9, vcc, 0, v3, vcc
	v_add_co_u32_e32 v46, vcc, 0x36000, v2
	s_nop 1
	v_addc_co_u32_e32 v47, vcc, 0, v3, vcc
	v_add_co_u32_e32 v64, vcc, 0x38000, v2
	s_nop 1
	v_addc_co_u32_e32 v65, vcc, 0, v3, vcc
	v_add_co_u32_e32 v66, vcc, 0x3a000, v2
	s_nop 1
	v_addc_co_u32_e32 v67, vcc, 0, v3, vcc
	v_add_co_u32_e32 v68, vcc, 0x3c000, v2
	s_nop 1
	v_addc_co_u32_e32 v69, vcc, 0, v3, vcc
	v_add_co_u32_e32 v2, vcc, 0x3e000, v2
	s_nop 1
	v_addc_co_u32_e32 v3, vcc, 0, v3, vcc
	global_load_dword v4, v[4:5], off
	s_nop 0
	global_load_dword v5, v[6:7], off
	s_nop 0
	global_load_dword v6, v[8:9], off
	global_load_dword v7, v[46:47], off
	s_nop 0
	global_load_dword v8, v[64:65], off
	global_load_dword v9, v[66:67], off
	global_load_dword v46, v[68:69], off
	s_nop 0
	global_load_dword v2, v[2:3], off
	s_waitcnt vmcnt(30)
	ds_write2_b32 v49, v10, v72 offset1:66
	s_waitcnt vmcnt(28)
	ds_write2_b32 v49, v73, v74 offset0:132 offset1:198
	s_waitcnt vmcnt(26)
	ds_write2_b32 v57, v75, v76 offset0:8 offset1:74
	s_waitcnt vmcnt(24)
	ds_write2_b32 v57, v77, v78 offset0:140 offset1:206
	s_waitcnt vmcnt(22)
	ds_write2_b32 v58, v79, v80 offset0:16 offset1:82
	s_waitcnt vmcnt(20)
	ds_write2_b32 v58, v81, v82 offset0:148 offset1:214
	s_waitcnt vmcnt(18)
	ds_write2_b32 v59, v83, v84 offset0:24 offset1:90
	s_waitcnt vmcnt(16)
	ds_write2_b32 v59, v85, v86 offset0:156 offset1:222
	s_waitcnt vmcnt(14)
	ds_write2_b32 v60, v87, v88 offset0:32 offset1:98
	s_waitcnt vmcnt(12)
	ds_write2_b32 v60, v89, v90 offset0:164 offset1:230
	s_waitcnt vmcnt(10)
	ds_write2_b32 v61, v91, v92 offset0:40 offset1:106
	s_waitcnt vmcnt(8)
	ds_write2_b32 v61, v93, v70 offset0:172 offset1:238
	s_waitcnt vmcnt(6)
	ds_write2_b32 v62, v4, v5 offset0:48 offset1:114
	s_waitcnt vmcnt(4)
	ds_write2_b32 v62, v6, v7 offset0:180 offset1:246
	s_waitcnt vmcnt(2)
	ds_write2_b32 v63, v8, v9 offset0:56 offset1:122
	s_waitcnt vmcnt(0)
	ds_write2_b32 v63, v46, v2 offset0:188 offset1:254
	s_waitcnt lgkmcnt(0)
	ds_read2_b32 v[6:7], v51 offset1:8
	ds_read2_b32 v[46:47], v51 offset0:33 offset1:41
	ds_read2_b32 v[64:65], v51 offset0:66 offset1:74
	ds_read2_b32 v[66:67], v51 offset0:99 offset1:107
	ds_read2_b32 v[68:69], v51 offset0:132 offset1:140
	s_waitcnt lgkmcnt(4)
	v_bfe_u32 v2, v6, 16, 1
	v_add3_u32 v2, v6, v2, s89
	s_waitcnt lgkmcnt(3)
	v_bfe_u32 v3, v46, 16, 1
	v_lshrrev_b32_e32 v2, 16, v2
	v_add3_u32 v3, v46, v3, s89
	ds_read2_b32 v[70:71], v51 offset0:165 offset1:173
	v_and_or_b32 v2, v3, s90, v2
	s_waitcnt lgkmcnt(3)
	v_bfe_u32 v3, v64, 16, 1
	v_add3_u32 v3, v64, v3, s89
	s_waitcnt lgkmcnt(2)
	v_bfe_u32 v4, v66, 16, 1
	ds_read2_b32 v[72:73], v51 offset0:198 offset1:206
	v_lshrrev_b32_e32 v3, 16, v3
	v_add3_u32 v4, v66, v4, s89
	ds_read2_b32 v[74:75], v51 offset0:231 offset1:239
	v_and_or_b32 v3, v4, s90, v3
	s_waitcnt lgkmcnt(3)
	v_bfe_u32 v4, v68, 16, 1
	v_add3_u32 v4, v68, v4, s89
	s_waitcnt lgkmcnt(2)
	v_bfe_u32 v5, v70, 16, 1
	v_lshrrev_b32_e32 v4, 16, v4
	v_add3_u32 v5, v70, v5, s89
	v_and_or_b32 v4, v5, s90, v4
	s_waitcnt lgkmcnt(1)
	v_bfe_u32 v5, v72, 16, 1
	v_add3_u32 v5, v72, v5, s89
	s_waitcnt lgkmcnt(0)
	v_bfe_u32 v6, v74, 16, 1
	v_lshrrev_b32_e32 v5, 16, v5
	v_add3_u32 v6, v74, v6, s89
	v_and_or_b32 v5, v6, s90, v5
	v_or_b32_e32 v6, s4, v50
	v_lshl_add_u64 v[8:9], v[14:15], 0, s[26:27]
	v_lshlrev_b32_e32 v10, 13, v6
	v_lshl_add_u64 v[76:77], v[8:9], 0, v[10:11]
	global_store_dwordx4 v[76:77], v[2:5], off sc1
	v_bfe_u32 v6, v75, 16, 1
	v_or_b32_e32 v10, s4, v52
	v_bfe_u32 v2, v7, 16, 1
	v_add3_u32 v2, v7, v2, s89
	v_bfe_u32 v3, v47, 16, 1
	v_lshrrev_b32_e32 v2, 16, v2
	v_add3_u32 v3, v47, v3, s89
	v_and_or_b32 v2, v3, s90, v2
	v_bfe_u32 v3, v65, 16, 1
	v_add3_u32 v3, v65, v3, s89
	v_bfe_u32 v4, v67, 16, 1
	v_lshrrev_b32_e32 v3, 16, v3
	v_add3_u32 v4, v67, v4, s89
	v_and_or_b32 v3, v4, s90, v3
	v_bfe_u32 v4, v69, 16, 1
	v_add3_u32 v4, v69, v4, s89
	v_bfe_u32 v5, v71, 16, 1
	v_lshrrev_b32_e32 v4, 16, v4
	v_add3_u32 v5, v71, v5, s89
	v_and_or_b32 v4, v5, s90, v4
	v_bfe_u32 v5, v73, 16, 1
	v_add3_u32 v5, v73, v5, s89
	v_lshrrev_b32_e32 v5, 16, v5
	v_add3_u32 v6, v75, v6, s89
	v_lshlrev_b32_e32 v10, 13, v10
	v_and_or_b32 v5, v6, s90, v5
	ds_read2_b32 v[6:7], v51 offset0:16 offset1:24
	v_lshl_add_u64 v[46:47], v[8:9], 0, v[10:11]
	global_store_dwordx4 v[46:47], v[2:5], off sc1
	ds_read2_b32 v[46:47], v51 offset0:49 offset1:57
	ds_read2_b32 v[64:65], v51 offset0:82 offset1:90
	ds_read2_b32 v[66:67], v51 offset0:115 offset1:123
	s_waitcnt lgkmcnt(3)
	v_bfe_u32 v2, v6, 16, 1
	v_add3_u32 v2, v6, v2, s89
	s_waitcnt lgkmcnt(2)
	v_bfe_u32 v3, v46, 16, 1
	ds_read2_b32 v[68:69], v51 offset0:148 offset1:156
	v_lshrrev_b32_e32 v2, 16, v2
	v_add3_u32 v3, v46, v3, s89
	ds_read2_b32 v[70:71], v51 offset0:181 offset1:189
	v_and_or_b32 v2, v3, s90, v2
	s_waitcnt lgkmcnt(3)
	v_bfe_u32 v3, v64, 16, 1
	v_add3_u32 v3, v64, v3, s89
	s_waitcnt lgkmcnt(2)
	v_bfe_u32 v4, v66, 16, 1
	ds_read2_b32 v[72:73], v51 offset0:214 offset1:222
	v_lshrrev_b32_e32 v3, 16, v3
	v_add3_u32 v4, v66, v4, s89
	ds_read2_b32 v[74:75], v51 offset0:247 offset1:255
	v_and_or_b32 v3, v4, s90, v3
	s_waitcnt lgkmcnt(3)
	v_bfe_u32 v4, v68, 16, 1
	v_add3_u32 v4, v68, v4, s89
	s_waitcnt lgkmcnt(2)
	v_bfe_u32 v5, v70, 16, 1
	v_lshrrev_b32_e32 v4, 16, v4
	v_add3_u32 v5, v70, v5, s89
	v_and_or_b32 v4, v5, s90, v4
	s_waitcnt lgkmcnt(1)
	v_bfe_u32 v5, v72, 16, 1
	v_add3_u32 v5, v72, v5, s89
	s_waitcnt lgkmcnt(0)
	v_bfe_u32 v6, v74, 16, 1
	v_lshrrev_b32_e32 v5, 16, v5
	v_add3_u32 v6, v74, v6, s89
	v_and_or_b32 v5, v6, s90, v5
	v_or_b32_e32 v6, s4, v53
	v_lshlrev_b32_e32 v10, 13, v6
	v_lshl_add_u64 v[76:77], v[8:9], 0, v[10:11]
	global_store_dwordx4 v[76:77], v[2:5], off sc1
	v_bfe_u32 v6, v75, 16, 1
	v_add3_u32 v6, v75, v6, s89
	v_bfe_u32 v2, v7, 16, 1
	v_add3_u32 v2, v7, v2, s89
	v_bfe_u32 v3, v47, 16, 1
	v_lshrrev_b32_e32 v2, 16, v2
	v_add3_u32 v3, v47, v3, s89
	v_and_or_b32 v2, v3, s90, v2
	v_bfe_u32 v3, v65, 16, 1
	v_add3_u32 v3, v65, v3, s89
	v_bfe_u32 v4, v67, 16, 1
	v_lshrrev_b32_e32 v3, 16, v3
	v_add3_u32 v4, v67, v4, s89
	v_and_or_b32 v3, v4, s90, v3
	v_bfe_u32 v4, v69, 16, 1
	v_add3_u32 v4, v69, v4, s89
	v_bfe_u32 v5, v71, 16, 1
	v_lshrrev_b32_e32 v4, 16, v4
	v_add3_u32 v5, v71, v5, s89
	v_and_or_b32 v4, v5, s90, v4
	v_bfe_u32 v5, v73, 16, 1
	v_add3_u32 v5, v73, v5, s89
	v_lshrrev_b32_e32 v5, 16, v5
	v_and_or_b32 v5, v6, s90, v5
	v_or_b32_e32 v6, s4, v54
	v_lshlrev_b32_e32 v10, 13, v6
	v_lshl_add_u64 v[6:7], v[8:9], 0, v[10:11]
	global_store_dwordx4 v[6:7], v[2:5], off sc1
	s_waitcnt lgkmcnt(0)

.LBB0_50:
	s_andn2_b64 vcc, exec, s[28:29]
	s_cbranch_vccnz .LBB0_53
	s_andn2_b64 vcc, exec, s[78:79]
	s_cbranch_vccnz .LBB0_53
	s_add_i32 s4, s18, 0xffffea60
	s_lshr_b32 s4, s4, 1
	s_and_b32 s26, s4, 0x7fffffc0
	s_add_i32 s4, s3, 0xfffd4c00
	s_and_b32 s4, s4, 0xfe0
	v_or_b32_e32 v10, s26, v48
	v_or_b32_e32 v4, s4, v1
	v_lshlrev_b64 v[2:3], 14, v[10:11]
	v_lshl_add_u64 v[2:3], s[8:9], 0, v[2:3]
	v_lshlrev_b32_e32 v10, 2, v4
	v_lshl_add_u64 v[2:3], v[2:3], 0, v[10:11]
	v_add_co_u32_e32 v4, vcc, 0x8000, v2
	s_nop 1
	v_addc_co_u32_e32 v5, vcc, 0, v3, vcc
	v_add_co_u32_e32 v6, vcc, 0x10000, v2
	s_nop 1
	v_addc_co_u32_e32 v7, vcc, 0, v3, vcc
	v_add_co_u32_e32 v8, vcc, 0x18000, v2
	s_nop 1
	v_addc_co_u32_e32 v9, vcc, 0, v3, vcc
	v_add_co_u32_e32 v46, vcc, 0x20000, v2
	s_nop 1
	v_addc_co_u32_e32 v47, vcc, 0, v3, vcc
	v_add_co_u32_e32 v64, vcc, 0x28000, v2
	s_nop 1
	v_addc_co_u32_e32 v65, vcc, 0, v3, vcc
	v_add_co_u32_e32 v66, vcc, 0x30000, v2
	s_nop 1
	v_addc_co_u32_e32 v67, vcc, 0, v3, vcc
	v_add_co_u32_e32 v68, vcc, 0x38000, v2
	s_nop 1
	v_addc_co_u32_e32 v69, vcc, 0, v3, vcc
	global_load_dword v10, v[2:3], off
	global_load_dword v72, v[4:5], off
	global_load_dword v73, v[6:7], off
	global_load_dword v74, v[8:9], off
	global_load_dword v75, v[46:47], off
	global_load_dword v76, v[64:65], off
	global_load_dword v77, v[66:67], off
	global_load_dword v78, v[68:69], off
	v_add_co_u32_e32 v4, vcc, 0x40000, v2
	s_nop 1
	v_addc_co_u32_e32 v5, vcc, 0, v3, vcc
	v_add_co_u32_e32 v6, vcc, 0x48000, v2
	s_nop 1
	v_addc_co_u32_e32 v7, vcc, 0, v3, vcc
	v_add_co_u32_e32 v8, vcc, 0x50000, v2
	s_nop 1
	v_addc_co_u32_e32 v9, vcc, 0, v3, vcc
	v_add_co_u32_e32 v46, vcc, 0x58000, v2
	s_nop 1
	v_addc_co_u32_e32 v47, vcc, 0, v3, vcc
	v_add_co_u32_e32 v64, vcc, 0x60000, v2
	s_nop 1
	v_addc_co_u32_e32 v65, vcc, 0, v3, vcc
	v_add_co_u32_e32 v66, vcc, 0x68000, v2
	s_nop 1
	v_addc_co_u32_e32 v67, vcc, 0, v3, vcc
	v_add_co_u32_e32 v68, vcc, 0x70000, v2
	s_nop 1
	v_addc_co_u32_e32 v69, vcc, 0, v3, vcc
	v_add_co_u32_e32 v70, vcc, 0x78000, v2
	s_nop 1
	v_addc_co_u32_e32 v71, vcc, 0, v3, vcc
	global_load_dword v79, v[4:5], off
	global_load_dword v80, v[6:7], off
	global_load_dword v81, v[8:9], off
	global_load_dword v82, v[46:47], off
	global_load_dword v83, v[64:65], off
	global_load_dword v84, v[66:67], off
	global_load_dword v85, v[68:69], off
	global_load_dword v86, v[70:71], off
	v_add_co_u32_e32 v4, vcc, 0x80000, v2
	s_nop 1
	v_addc_co_u32_e32 v5, vcc, 0, v3, vcc
	v_add_co_u32_e32 v6, vcc, 0x88000, v2
	s_nop 1
	v_addc_co_u32_e32 v7, vcc, 0, v3, vcc
	v_add_co_u32_e32 v8, vcc, 0x90000, v2
	s_nop 1
	v_addc_co_u32_e32 v9, vcc, 0, v3, vcc
	v_add_co_u32_e32 v46, vcc, 0x98000, v2
	s_nop 1
	v_addc_co_u32_e32 v47, vcc, 0, v3, vcc
	v_add_co_u32_e32 v64, vcc, 0xa0000, v2
	s_nop 1
	v_addc_co_u32_e32 v65, vcc, 0, v3, vcc
	v_add_co_u32_e32 v66, vcc, 0xa8000, v2
	s_nop 1
	v_addc_co_u32_e32 v67, vcc, 0, v3, vcc
	v_add_co_u32_e32 v68, vcc, 0xb0000, v2
	s_nop 1
	v_addc_co_u32_e32 v69, vcc, 0, v3, vcc
	v_add_co_u32_e32 v70, vcc, 0xb8000, v2
	s_nop 1
	v_addc_co_u32_e32 v71, vcc, 0, v3, vcc
	global_load_dword v87, v[4:5], off
	global_load_dword v88, v[6:7], off
	global_load_dword v89, v[8:9], off
	global_load_dword v90, v[46:47], off
	global_load_dword v91, v[64:65], off
	global_load_dword v92, v[66:67], off
	global_load_dword v93, v[68:69], off
	s_nop 0
	global_load_dword v70, v[70:71], off
	v_add_co_u32_e32 v4, vcc, 0xc0000, v2
	s_nop 1
	v_addc_co_u32_e32 v5, vcc, 0, v3, vcc
	v_add_co_u32_e32 v6, vcc, 0xc8000, v2
	s_nop 1
	v_addc_co_u32_e32 v7, vcc, 0, v3, vcc
	v_add_co_u32_e32 v8, vcc, 0xd0000, v2
	s_nop 1
	v_addc_co_u32_e32 v9, vcc, 0, v3, vcc
	v_add_co_u32_e32 v46, vcc, 0xd8000, v2
	s_nop 1
	v_addc_co_u32_e32 v47, vcc, 0, v3, vcc
	v_add_co_u32_e32 v64, vcc, 0xe0000, v2
	s_nop 1
	v_addc_co_u32_e32 v65, vcc, 0, v3, vcc
	v_add_co_u32_e32 v66, vcc, 0xe8000, v2
	s_nop 1
	v_addc_co_u32_e32 v67, vcc, 0, v3, vcc
	v_add_co_u32_e32 v68, vcc, 0xf0000, v2
	s_nop 1
	v_addc_co_u32_e32 v69, vcc, 0, v3, vcc
	v_add_co_u32_e32 v2, vcc, 0xf8000, v2
	s_nop 1
	v_addc_co_u32_e32 v3, vcc, 0, v3, vcc
	global_load_dword v71, v[4:5], off
	global_load_dword v94, v[6:7], off
	global_load_dword v95, v[8:9], off
	s_nop 0
	global_load_dword v46, v[46:47], off
	s_nop 0
	global_load_dword v47, v[64:65], off
	s_nop 0
	global_load_dword v64, v[66:67], off
	global_load_dword v65, v[68:69], off
	s_nop 0
	global_load_dword v66, v[2:3], off
	v_lshl_add_u64 v[6:7], s[26:27], 2, v[18:19]
	global_load_dwordx4 v[2:5], v[6:7], off
	s_nop 0
	global_load_dwordx4 v[6:9], v[6:7], off offset:16
	s_waitcnt vmcnt(32)
	ds_write2_b32 v49, v10, v72 offset1:66
	s_waitcnt vmcnt(30)
	ds_write2_b32 v49, v73, v74 offset0:132 offset1:198
	s_waitcnt vmcnt(28)
	ds_write2_b32 v57, v75, v76 offset0:8 offset1:74
	s_waitcnt vmcnt(26)
	ds_write2_b32 v57, v77, v78 offset0:140 offset1:206
	s_waitcnt vmcnt(24)
	ds_write2_b32 v58, v79, v80 offset0:16 offset1:82
	s_waitcnt vmcnt(22)
	ds_write2_b32 v58, v81, v82 offset0:148 offset1:214
	s_waitcnt vmcnt(20)
	ds_write2_b32 v59, v83, v84 offset0:24 offset1:90
	s_waitcnt vmcnt(18)
	ds_write2_b32 v59, v85, v86 offset0:156 offset1:222
	s_waitcnt vmcnt(16)
	ds_write2_b32 v60, v87, v88 offset0:32 offset1:98
	s_waitcnt vmcnt(14)
	ds_write2_b32 v60, v89, v90 offset0:164 offset1:230
	s_waitcnt vmcnt(12)
	ds_write2_b32 v61, v91, v92 offset0:40 offset1:106
	s_waitcnt vmcnt(10)
	ds_write2_b32 v61, v93, v70 offset0:172 offset1:238
	s_waitcnt vmcnt(8)
	ds_write2_b32 v62, v71, v94 offset0:48 offset1:114
	s_waitcnt vmcnt(6)
	ds_write2_b32 v62, v95, v46 offset0:180 offset1:246
	s_waitcnt vmcnt(4)
	ds_write2_b32 v63, v47, v64 offset0:56 offset1:122
	s_waitcnt vmcnt(2)
	ds_write2_b32 v63, v65, v66 offset0:188 offset1:254
	s_waitcnt lgkmcnt(0)
	ds_read2_b32 v[68:69], v51 offset0:33 offset1:41
	ds_read2_b32 v[70:71], v51 offset1:8
	ds_read2_b32 v[72:73], v51 offset0:66 offset1:74
	ds_read2_b32 v[74:75], v51 offset0:99 offset1:107
	ds_read2_b32 v[78:79], v51 offset0:132 offset1:140
	ds_read2_b32 v[80:81], v51 offset0:165 offset1:173
	ds_read2_b32 v[82:83], v51 offset0:198 offset1:206
	ds_read2_b32 v[84:85], v51 offset0:231 offset1:239
	s_waitcnt vmcnt(1)
	v_mov_b32_e32 v76, v2
	v_mov_b32_e32 v77, v4
	v_mov_b32_e32 v4, v3
	s_waitcnt lgkmcnt(7)
	v_mov_b32_e32 v2, v68
	s_waitcnt lgkmcnt(4)
	v_mov_b32_e32 v3, v74
	s_waitcnt vmcnt(0)
	v_mov_b32_e32 v86, v6
	v_mov_b32_e32 v87, v8
	v_mov_b32_e32 v8, v7
	s_waitcnt lgkmcnt(2)
	v_mov_b32_e32 v6, v80
	s_waitcnt lgkmcnt(0)
	v_mov_b32_e32 v7, v84
	v_mov_b32_e32 v64, v70
	v_mov_b32_e32 v65, v72
	v_pk_mul_f32 v[2:3], v[4:5], v[2:3]
	v_mov_b32_e32 v66, v78
	v_mov_b32_e32 v67, v82
	v_pk_mul_f32 v[6:7], v[8:9], v[6:7]
	v_pk_mul_f32 v[64:65], v[76:77], v[64:65]
	v_pk_mul_f32 v[66:67], v[86:87], v[66:67]
	v_bfe_u32 v10, v7, 16, 1
	v_bfe_u32 v68, v6, 16, 1
	v_bfe_u32 v70, v3, 16, 1
	v_bfe_u32 v72, v2, 16, 1
	v_add3_u32 v2, v2, v72, s89
	v_add3_u32 v3, v3, v70, s89
	v_add3_u32 v6, v6, v68, s89
	v_add3_u32 v7, v7, v10, s89
	v_bfe_u32 v10, v64, 16, 1
	v_bfe_u32 v68, v65, 16, 1
	v_bfe_u32 v70, v66, 16, 1
	v_bfe_u32 v72, v67, 16, 1
	v_add3_u32 v67, v67, v72, s89
	v_add3_u32 v66, v66, v70, s89
	v_add3_u32 v65, v65, v68, s89
	v_add3_u32 v10, v64, v10, s89
	v_lshrrev_b32_e32 v10, 16, v10
	v_lshrrev_b32_e32 v64, 16, v65
	v_lshrrev_b32_e32 v65, 16, v66
	v_lshrrev_b32_e32 v66, 16, v67
	s_lshl_b32 s26, s26, 1
	v_and_or_b32 v67, v7, s90, v66
	v_and_or_b32 v66, v6, s90, v65
	v_and_or_b32 v65, v3, s90, v64
	v_and_or_b32 v64, v2, s90, v10
	v_or_b32_e32 v2, s4, v50
	v_lshl_add_u64 v[46:47], v[20:21], 0, s[26:27]
	v_lshlrev_b32_e32 v10, 11, v2
	v_lshl_add_u64 v[2:3], v[46:47], 0, v[10:11]
	v_mov_b32_e32 v74, v69
	v_mov_b32_e32 v84, v81
	global_store_dwordx4 v[2:3], v[64:67], off sc1
	v_mov_b32_e32 v72, v71
	v_pk_mul_f32 v[6:7], v[4:5], v[74:75]
	v_mov_b32_e32 v82, v79
	v_pk_mul_f32 v[66:67], v[8:9], v[84:85]
	v_pk_mul_f32 v[2:3], v[76:77], v[72:73]
	v_pk_mul_f32 v[64:65], v[86:87], v[82:83]
	v_bfe_u32 v10, v67, 16, 1
	v_bfe_u32 v69, v7, 16, 1
	v_bfe_u32 v70, v6, 16, 1
	v_add3_u32 v7, v7, v69, s89
	v_add3_u32 v10, v67, v10, s89
	v_bfe_u32 v67, v2, 16, 1
	v_bfe_u32 v69, v64, 16, 1
	v_bfe_u32 v68, v66, 16, 1
	v_add3_u32 v6, v6, v70, s89
	v_bfe_u32 v70, v65, 16, 1
	v_add3_u32 v64, v64, v69, s89
	v_add3_u32 v2, v2, v67, s89
	v_add3_u32 v66, v66, v68, s89
	v_bfe_u32 v68, v3, 16, 1
	v_add3_u32 v65, v65, v70, s89
	v_lshrrev_b32_e32 v2, 16, v2
	v_lshrrev_b32_e32 v64, 16, v64
	v_add3_u32 v3, v3, v68, s89
	v_lshrrev_b32_e32 v65, 16, v65
	v_and_or_b32 v66, v66, s90, v64
	v_and_or_b32 v64, v6, s90, v2
	v_or_b32_e32 v2, s4, v52
	v_lshrrev_b32_e32 v3, 16, v3
	v_and_or_b32 v67, v10, s90, v65
	v_lshlrev_b32_e32 v10, 11, v2
	v_and_or_b32 v65, v7, s90, v3
	v_lshl_add_u64 v[2:3], v[46:47], 0, v[10:11]
	ds_read2_b32 v[6:7], v51 offset0:16 offset1:24
	ds_read2_b32 v[68:69], v51 offset0:82 offset1:90
	global_store_dwordx4 v[2:3], v[64:67], off sc1
	ds_read2_b32 v[2:3], v51 offset0:49 offset1:57
	ds_read2_b32 v[70:71], v51 offset0:115 offset1:123
	ds_read2_b32 v[72:73], v51 offset0:148 offset1:156
	ds_read2_b32 v[74:75], v51 offset0:214 offset1:222
	ds_read2_b32 v[78:79], v51 offset0:181 offset1:189
	ds_read2_b32 v[80:81], v51 offset0:247 offset1:255
	s_waitcnt lgkmcnt(7)
	v_mov_b32_e32 v64, v6
	s_waitcnt lgkmcnt(5)
	v_mov_b32_e32 v66, v2
	s_waitcnt lgkmcnt(4)
	v_mov_b32_e32 v67, v70
	s_waitcnt lgkmcnt(3)
	v_mov_b32_e32 v82, v72
	s_waitcnt lgkmcnt(2)
	v_mov_b32_e32 v83, v74
	v_mov_b32_e32 v65, v68
	v_pk_mul_f32 v[66:67], v[4:5], v[66:67]
	v_pk_mul_f32 v[82:83], v[86:87], v[82:83]
	s_waitcnt lgkmcnt(1)
	v_mov_b32_e32 v84, v78
	s_waitcnt lgkmcnt(0)
	v_mov_b32_e32 v85, v80
	v_pk_mul_f32 v[64:65], v[76:77], v[64:65]
	v_pk_mul_f32 v[84:85], v[8:9], v[84:85]
	v_bfe_u32 v10, v67, 16, 1
	v_bfe_u32 v68, v66, 16, 1
	v_bfe_u32 v72, v83, 16, 1
	v_bfe_u32 v2, v85, 16, 1
	v_add3_u32 v68, v66, v68, s89
	v_add3_u32 v10, v67, v10, s89
	v_bfe_u32 v66, v64, 16, 1
	v_bfe_u32 v67, v65, 16, 1
	v_add3_u32 v72, v83, v72, s89
	v_add3_u32 v2, v85, v2, s89
	v_bfe_u32 v70, v82, 16, 1
	v_add3_u32 v65, v65, v67, s89
	v_add3_u32 v64, v64, v66, s89
	v_lshrrev_b32_e32 v67, 16, v72
	v_bfe_u32 v6, v84, 16, 1
	v_add3_u32 v70, v82, v70, s89
	v_lshrrev_b32_e32 v64, 16, v64
	v_lshrrev_b32_e32 v65, 16, v65
	v_and_or_b32 v67, v2, s90, v67
	v_or_b32_e32 v2, s4, v53
	v_mov_b32_e32 v80, v79
	v_add3_u32 v6, v84, v6, s89
	v_lshrrev_b32_e32 v66, 16, v70
	v_and_or_b32 v65, v10, s90, v65
	v_and_or_b32 v64, v68, s90, v64
	v_lshlrev_b32_e32 v10, 11, v2
	v_mov_b32_e32 v68, v7
	v_pk_mul_f32 v[8:9], v[8:9], v[80:81]
	v_and_or_b32 v66, v6, s90, v66
	v_lshl_add_u64 v[82:83], v[46:47], 0, v[10:11]
	v_pk_mul_f32 v[6:7], v[76:77], v[68:69]
	v_mov_b32_e32 v70, v3
	v_bfe_u32 v10, v9, 16, 1
	v_pk_mul_f32 v[2:3], v[4:5], v[70:71]
	v_mov_b32_e32 v74, v73
	v_add3_u32 v9, v9, v10, s89
	v_bfe_u32 v10, v6, 16, 1
	global_store_dwordx4 v[82:83], v[64:67], off sc1
	v_pk_mul_f32 v[4:5], v[86:87], v[74:75]
	v_add3_u32 v6, v6, v10, s89
	v_bfe_u32 v64, v8, 16, 1
	v_bfe_u32 v65, v3, 16, 1
	v_bfe_u32 v66, v2, 16, 1
	v_add3_u32 v2, v2, v66, s89
	v_add3_u32 v3, v3, v65, s89
	v_add3_u32 v8, v8, v64, s89
	v_bfe_u32 v64, v7, 16, 1
	v_bfe_u32 v65, v4, 16, 1
	v_bfe_u32 v66, v5, 16, 1
	v_lshrrev_b32_e32 v6, 16, v6
	v_add3_u32 v5, v5, v66, s89
	v_add3_u32 v4, v4, v65, s89
	v_add3_u32 v7, v7, v64, s89
	v_and_or_b32 v2, v2, s90, v6
	v_or_b32_e32 v6, s4, v54
	v_lshrrev_b32_e32 v7, 16, v7
	v_lshrrev_b32_e32 v4, 16, v4
	v_lshrrev_b32_e32 v5, 16, v5
	v_lshlrev_b32_e32 v10, 11, v6
	v_and_or_b32 v5, v9, s90, v5
	v_and_or_b32 v4, v8, s90, v4
	v_and_or_b32 v3, v3, s90, v7
	v_lshl_add_u64 v[6:7], v[46:47], 0, v[10:11]
	global_store_dwordx4 v[6:7], v[2:5], off sc1
	s_waitcnt lgkmcnt(0)

.LBB0_58:
	s_waitcnt lgkmcnt(0)
	ds_read2_b32 v[8:9], v51 offset1:8
	ds_read2_b32 v[68:69], v51 offset0:66 offset1:74
	ds_read2_b32 v[72:73], v51 offset0:33 offset1:41
	ds_read2_b32 v[74:75], v51 offset0:99 offset1:107
	ds_read2_b32 v[76:77], v51 offset0:132 offset1:140
	ds_read2_b32 v[78:79], v51 offset0:198 offset1:206
	ds_read2_b32 v[80:81], v51 offset0:165 offset1:173
	ds_read2_b32 v[82:83], v51 offset0:231 offset1:239
	s_waitcnt lgkmcnt(7)
	v_mov_b32_e32 v64, v8
	s_waitcnt lgkmcnt(5)
	v_mov_b32_e32 v66, v72
	s_waitcnt lgkmcnt(4)
	v_mov_b32_e32 v67, v74
	s_waitcnt lgkmcnt(3)
	v_mov_b32_e32 v84, v76
	s_waitcnt lgkmcnt(2)
	v_mov_b32_e32 v85, v78
	v_mov_b32_e32 v65, v68
	v_pk_mul_f32 v[66:67], v[46:47], v[66:67]
	v_pk_mul_f32 v[84:85], v[6:7], v[84:85]
	s_waitcnt lgkmcnt(1)
	v_mov_b32_e32 v86, v80
	s_waitcnt lgkmcnt(0)
	v_mov_b32_e32 v87, v82
	v_pk_mul_f32 v[64:65], v[2:3], v[64:65]
	v_pk_mul_f32 v[86:87], v[4:5], v[86:87]
	v_bfe_u32 v68, v67, 16, 1
	v_bfe_u32 v76, v85, 16, 1
	v_bfe_u32 v8, v87, 16, 1
	v_bfe_u32 v72, v66, 16, 1
	v_add3_u32 v68, v67, v68, s89
	v_bfe_u32 v67, v65, 16, 1
	v_bfe_u32 v74, v84, 16, 1
	v_add3_u32 v76, v85, v76, s89
	v_bfe_u32 v10, v86, 16, 1
	v_add3_u32 v72, v66, v72, s89
	v_add3_u32 v8, v87, v8, s89
	v_bfe_u32 v66, v64, 16, 1
	v_add3_u32 v74, v84, v74, s89
	v_add3_u32 v65, v65, v67, s89
	v_lshrrev_b32_e32 v67, 16, v76
	s_lshl_b32 s26, s26, 1
	v_add3_u32 v10, v86, v10, s89
	v_add3_u32 v64, v64, v66, s89
	v_lshrrev_b32_e32 v65, 16, v65
	v_lshrrev_b32_e32 v66, 16, v74
	v_and_or_b32 v67, v8, s90, v67
	v_or_b32_e32 v8, s4, v50
	v_lshl_add_u64 v[70:71], v[38:39], 0, s[26:27]
	v_lshrrev_b32_e32 v64, 16, v64
	v_and_or_b32 v66, v10, s90, v66
	v_and_or_b32 v65, v68, s90, v65
	v_lshlrev_b32_e32 v10, 11, v8
	v_mov_b32_e32 v68, v9
	v_mov_b32_e32 v82, v81
	v_and_or_b32 v64, v72, s90, v64
	v_lshl_add_u64 v[84:85], v[70:71], 0, v[10:11]
	v_pk_mul_f32 v[8:9], v[2:3], v[68:69]
	v_mov_b32_e32 v74, v73
	v_pk_mul_f32 v[68:69], v[4:5], v[82:83]
	global_store_dwordx4 v[84:85], v[64:67], off sc1
	v_mov_b32_e32 v78, v77
	v_bfe_u32 v10, v69, 16, 1
	v_pk_mul_f32 v[64:65], v[46:47], v[74:75]
	v_pk_mul_f32 v[66:67], v[6:7], v[78:79]
	v_bfe_u32 v74, v64, 16, 1
	v_add3_u32 v10, v69, v10, s89
	v_bfe_u32 v69, v8, 16, 1
	v_bfe_u32 v72, v68, 16, 1
	v_bfe_u32 v73, v65, 16, 1
	v_add3_u32 v64, v64, v74, s89
	v_bfe_u32 v74, v67, 16, 1
	v_add3_u32 v8, v8, v69, s89
	v_add3_u32 v65, v65, v73, s89
	v_add3_u32 v68, v68, v72, s89
	v_bfe_u32 v72, v9, 16, 1
	v_bfe_u32 v73, v66, 16, 1
	v_add3_u32 v67, v67, v74, s89
	v_lshrrev_b32_e32 v8, 16, v8
	v_add3_u32 v66, v66, v73, s89
	v_add3_u32 v9, v9, v72, s89
	v_lshrrev_b32_e32 v67, 16, v67
	v_and_or_b32 v64, v64, s90, v8
	v_or_b32_e32 v8, s4, v52
	v_lshrrev_b32_e32 v9, 16, v9
	v_lshrrev_b32_e32 v66, 16, v66
	v_and_or_b32 v67, v10, s90, v67
	v_lshlrev_b32_e32 v10, 11, v8
	v_and_or_b32 v66, v68, s90, v66
	v_and_or_b32 v65, v65, s90, v9
	v_lshl_add_u64 v[8:9], v[70:71], 0, v[10:11]
	ds_read2_b32 v[68:69], v51 offset0:16 offset1:24
	ds_read2_b32 v[72:73], v51 offset0:82 offset1:90
	global_store_dwordx4 v[8:9], v[64:67], off sc1
	ds_read2_b32 v[8:9], v51 offset0:49 offset1:57
	ds_read2_b32 v[74:75], v51 offset0:115 offset1:123
	ds_read2_b32 v[76:77], v51 offset0:148 offset1:156
	ds_read2_b32 v[78:79], v51 offset0:214 offset1:222
	ds_read2_b32 v[80:81], v51 offset0:181 offset1:189
	ds_read2_b32 v[82:83], v51 offset0:247 offset1:255
	s_waitcnt lgkmcnt(7)
	v_mov_b32_e32 v64, v68
	s_waitcnt lgkmcnt(5)
	v_mov_b32_e32 v66, v8
	s_waitcnt lgkmcnt(4)
	v_mov_b32_e32 v67, v74
	s_waitcnt lgkmcnt(3)
	v_mov_b32_e32 v84, v76
	s_waitcnt lgkmcnt(2)
	v_mov_b32_e32 v85, v78
	v_mov_b32_e32 v65, v72
	v_pk_mul_f32 v[66:67], v[46:47], v[66:67]
	v_pk_mul_f32 v[84:85], v[6:7], v[84:85]
	s_waitcnt lgkmcnt(1)
	v_mov_b32_e32 v86, v80
	s_waitcnt lgkmcnt(0)
	v_mov_b32_e32 v87, v82
	v_pk_mul_f32 v[64:65], v[2:3], v[64:65]
	v_pk_mul_f32 v[86:87], v[4:5], v[86:87]
	v_bfe_u32 v68, v67, 16, 1
	v_bfe_u32 v76, v85, 16, 1
	v_bfe_u32 v8, v87, 16, 1
	v_bfe_u32 v72, v66, 16, 1
	v_add3_u32 v68, v67, v68, s89
	v_bfe_u32 v67, v65, 16, 1
	v_bfe_u32 v74, v84, 16, 1
	v_add3_u32 v76, v85, v76, s89
	v_bfe_u32 v10, v86, 16, 1
	v_add3_u32 v72, v66, v72, s89
	v_add3_u32 v8, v87, v8, s89
	v_bfe_u32 v66, v64, 16, 1
	v_add3_u32 v74, v84, v74, s89
	v_add3_u32 v65, v65, v67, s89
	v_lshrrev_b32_e32 v67, 16, v76
	v_add3_u32 v10, v86, v10, s89
	v_add3_u32 v64, v64, v66, s89
	v_lshrrev_b32_e32 v66, 16, v74
	v_and_or_b32 v67, v8, s90, v67
	v_or_b32_e32 v8, s4, v53
	v_mov_b32_e32 v74, v9
	v_and_or_b32 v66, v10, s90, v66
	v_lshlrev_b32_e32 v10, 11, v8
	v_pk_mul_f32 v[8:9], v[46:47], v[74:75]
	v_mov_b32_e32 v78, v77
	v_lshrrev_b32_e32 v64, 16, v64
	v_lshrrev_b32_e32 v65, 16, v65
	v_pk_mul_f32 v[6:7], v[6:7], v[78:79]
	v_mov_b32_e32 v82, v81
	v_bfe_u32 v47, v9, 16, 1
	v_and_or_b32 v65, v68, s90, v65
	v_and_or_b32 v64, v72, s90, v64
	v_lshl_add_u64 v[84:85], v[70:71], 0, v[10:11]
	v_mov_b32_e32 v72, v69
	v_pk_mul_f32 v[4:5], v[4:5], v[82:83]
	v_add3_u32 v9, v9, v47, s89
	v_bfe_u32 v47, v6, 16, 1
	global_store_dwordx4 v[84:85], v[64:67], off sc1
	v_pk_mul_f32 v[2:3], v[2:3], v[72:73]
	v_bfe_u32 v10, v5, 16, 1
	v_bfe_u32 v46, v4, 16, 1
	v_bfe_u32 v64, v8, 16, 1
	v_add3_u32 v6, v6, v47, s89
	v_add3_u32 v8, v8, v64, s89
	v_add3_u32 v4, v4, v46, s89
	v_add3_u32 v5, v5, v10, s89
	v_bfe_u32 v10, v2, 16, 1
	v_bfe_u32 v46, v3, 16, 1
	v_bfe_u32 v64, v7, 16, 1
	v_lshrrev_b32_e32 v6, 16, v6
	v_add3_u32 v7, v7, v64, s89
	v_add3_u32 v3, v3, v46, s89
	v_add3_u32 v2, v2, v10, s89
	v_and_or_b32 v4, v4, s90, v6
	v_or_b32_e32 v6, s4, v54
	v_lshrrev_b32_e32 v2, 16, v2
	v_lshrrev_b32_e32 v3, 16, v3
	v_lshrrev_b32_e32 v7, 16, v7
	v_lshlrev_b32_e32 v10, 11, v6
	v_and_or_b32 v5, v5, s90, v7
	v_and_or_b32 v3, v9, s90, v3
	v_and_or_b32 v2, v8, s90, v2
	v_lshl_add_u64 v[6:7], v[70:71], 0, v[10:11]
	global_store_dwordx4 v[6:7], v[2:5], off sc1
	s_waitcnt lgkmcnt(0)

.LBB0_60:
	s_andn2_b64 vcc, exec, s[28:29]
	s_cbranch_vccnz .LBB0_63
	s_andn2_b64 vcc, exec, s[78:79]
	s_cbranch_vccnz .LBB0_63
	s_add_i32 s4, s21, 0x3400
	s_and_b32 s5, s4, 0x7fffffc0
	s_and_b32 s4, s3, 0x3e0
	v_or_b32_e32 v10, s5, v48
	v_or_b32_e32 v4, s4, v1
	v_lshlrev_b64 v[2:3], 12, v[10:11]
	v_lshl_add_u64 v[2:3], s[46:47], 0, v[2:3]
	v_lshlrev_b32_e32 v10, 2, v4
	v_lshl_add_u64 v[2:3], v[2:3], 0, v[10:11]
	v_add_co_u32_e32 v4, vcc, 0x2000, v2
	s_lshl_b32 s26, s5, 1
	s_nop 0
	v_addc_co_u32_e32 v5, vcc, 0, v3, vcc
	v_add_co_u32_e32 v6, vcc, 0x4000, v2
	s_nop 1
	v_addc_co_u32_e32 v7, vcc, 0, v3, vcc
	v_add_co_u32_e32 v8, vcc, 0x6000, v2
	s_nop 1
	v_addc_co_u32_e32 v9, vcc, 0, v3, vcc
	v_add_co_u32_e32 v46, vcc, 0x8000, v2
	s_nop 1
	v_addc_co_u32_e32 v47, vcc, 0, v3, vcc
	v_add_co_u32_e32 v64, vcc, 0xa000, v2
	s_nop 1
	v_addc_co_u32_e32 v65, vcc, 0, v3, vcc
	v_add_co_u32_e32 v66, vcc, 0xc000, v2
	s_nop 1
	v_addc_co_u32_e32 v67, vcc, 0, v3, vcc
	v_add_co_u32_e32 v68, vcc, 0xe000, v2
	s_nop 1
	v_addc_co_u32_e32 v69, vcc, 0, v3, vcc
	global_load_dword v10, v[2:3], off
	global_load_dword v72, v[4:5], off
	global_load_dword v73, v[6:7], off
	global_load_dword v74, v[8:9], off
	global_load_dword v75, v[46:47], off
	global_load_dword v76, v[64:65], off
	global_load_dword v77, v[66:67], off
	global_load_dword v78, v[68:69], off
	v_add_co_u32_e32 v4, vcc, 0x10000, v2
	s_nop 1
	v_addc_co_u32_e32 v5, vcc, 0, v3, vcc
	v_add_co_u32_e32 v6, vcc, 0x12000, v2
	s_nop 1
	v_addc_co_u32_e32 v7, vcc, 0, v3, vcc
	v_add_co_u32_e32 v8, vcc, 0x14000, v2
	s_nop 1
	v_addc_co_u32_e32 v9, vcc, 0, v3, vcc
	v_add_co_u32_e32 v46, vcc, 0x16000, v2
	s_nop 1
	v_addc_co_u32_e32 v47, vcc, 0, v3, vcc
	v_add_co_u32_e32 v64, vcc, 0x18000, v2
	s_nop 1
	v_addc_co_u32_e32 v65, vcc, 0, v3, vcc
	v_add_co_u32_e32 v66, vcc, 0x1a000, v2
	s_nop 1
	v_addc_co_u32_e32 v67, vcc, 0, v3, vcc
	v_add_co_u32_e32 v68, vcc, 0x1c000, v2
	s_nop 1
	v_addc_co_u32_e32 v69, vcc, 0, v3, vcc
	v_add_co_u32_e32 v70, vcc, 0x1e000, v2
	s_nop 1
	v_addc_co_u32_e32 v71, vcc, 0, v3, vcc
	global_load_dword v79, v[4:5], off
	global_load_dword v80, v[6:7], off
	global_load_dword v81, v[8:9], off
	global_load_dword v82, v[46:47], off
	global_load_dword v83, v[64:65], off
	global_load_dword v84, v[66:67], off
	global_load_dword v85, v[68:69], off
	global_load_dword v86, v[70:71], off
	v_add_co_u32_e32 v4, vcc, 0x20000, v2
	s_nop 1
	v_addc_co_u32_e32 v5, vcc, 0, v3, vcc
	v_add_co_u32_e32 v6, vcc, 0x22000, v2
	s_nop 1
	v_addc_co_u32_e32 v7, vcc, 0, v3, vcc
	v_add_co_u32_e32 v8, vcc, 0x24000, v2
	s_nop 1
	v_addc_co_u32_e32 v9, vcc, 0, v3, vcc
	v_add_co_u32_e32 v46, vcc, 0x26000, v2
	s_nop 1
	v_addc_co_u32_e32 v47, vcc, 0, v3, vcc
	v_add_co_u32_e32 v64, vcc, 0x28000, v2
	s_nop 1
	v_addc_co_u32_e32 v65, vcc, 0, v3, vcc
	v_add_co_u32_e32 v66, vcc, 0x2a000, v2
	s_nop 1
	v_addc_co_u32_e32 v67, vcc, 0, v3, vcc
	v_add_co_u32_e32 v68, vcc, 0x2c000, v2
	s_nop 1
	v_addc_co_u32_e32 v69, vcc, 0, v3, vcc
	v_add_co_u32_e32 v70, vcc, 0x2e000, v2
	s_nop 1
	v_addc_co_u32_e32 v71, vcc, 0, v3, vcc
	global_load_dword v87, v[4:5], off
	global_load_dword v88, v[6:7], off
	global_load_dword v89, v[8:9], off
	global_load_dword v90, v[46:47], off
	global_load_dword v91, v[64:65], off
	global_load_dword v92, v[66:67], off
	global_load_dword v93, v[68:69], off
	s_nop 0
	global_load_dword v70, v[70:71], off
	v_add_co_u32_e32 v4, vcc, 0x30000, v2
	s_nop 1
	v_addc_co_u32_e32 v5, vcc, 0, v3, vcc
	v_add_co_u32_e32 v6, vcc, 0x32000, v2
	s_nop 1
	v_addc_co_u32_e32 v7, vcc, 0, v3, vcc
	v_add_co_u32_e32 v8, vcc, 0x34000, v2
	s_nop 1
	v_addc_co_u32_e32 v9, vcc, 0, v3, vcc
	v_add_co_u32_e32 v46, vcc, 0x36000, v2
	s_nop 1
	v_addc_co_u32_e32 v47, vcc, 0, v3, vcc
	v_add_co_u32_e32 v64, vcc, 0x38000, v2
	s_nop 1
	v_addc_co_u32_e32 v65, vcc, 0, v3, vcc
	v_add_co_u32_e32 v66, vcc, 0x3a000, v2
	s_nop 1
	v_addc_co_u32_e32 v67, vcc, 0, v3, vcc
	v_add_co_u32_e32 v68, vcc, 0x3c000, v2
	s_nop 1
	v_addc_co_u32_e32 v69, vcc, 0, v3, vcc
	v_add_co_u32_e32 v2, vcc, 0x3e000, v2
	s_nop 1
	v_addc_co_u32_e32 v3, vcc, 0, v3, vcc
	global_load_dword v4, v[4:5], off
	s_nop 0
	global_load_dword v5, v[6:7], off
	s_nop 0
	global_load_dword v6, v[8:9], off
	global_load_dword v7, v[46:47], off
	s_nop 0
	global_load_dword v8, v[64:65], off
	global_load_dword v9, v[66:67], off
	global_load_dword v46, v[68:69], off
	s_nop 0
	global_load_dword v2, v[2:3], off
	s_waitcnt vmcnt(30)
	ds_write2_b32 v49, v10, v72 offset1:66
	s_waitcnt vmcnt(28)
	ds_write2_b32 v49, v73, v74 offset0:132 offset1:198
	s_waitcnt vmcnt(26)
	ds_write2_b32 v57, v75, v76 offset0:8 offset1:74
	s_waitcnt vmcnt(24)
	ds_write2_b32 v57, v77, v78 offset0:140 offset1:206
	s_waitcnt vmcnt(22)
	ds_write2_b32 v58, v79, v80 offset0:16 offset1:82
	s_waitcnt vmcnt(20)
	ds_write2_b32 v58, v81, v82 offset0:148 offset1:214
	s_waitcnt vmcnt(18)
	ds_write2_b32 v59, v83, v84 offset0:24 offset1:90
	s_waitcnt vmcnt(16)
	ds_write2_b32 v59, v85, v86 offset0:156 offset1:222
	s_waitcnt vmcnt(14)
	ds_write2_b32 v60, v87, v88 offset0:32 offset1:98
	s_waitcnt vmcnt(12)
	ds_write2_b32 v60, v89, v90 offset0:164 offset1:230
	s_waitcnt vmcnt(10)
	ds_write2_b32 v61, v91, v92 offset0:40 offset1:106
	s_waitcnt vmcnt(8)
	ds_write2_b32 v61, v93, v70 offset0:172 offset1:238
	s_waitcnt vmcnt(6)
	ds_write2_b32 v62, v4, v5 offset0:48 offset1:114
	s_waitcnt vmcnt(4)
	ds_write2_b32 v62, v6, v7 offset0:180 offset1:246
	s_waitcnt vmcnt(2)
	ds_write2_b32 v63, v8, v9 offset0:56 offset1:122
	s_waitcnt vmcnt(0)
	ds_write2_b32 v63, v46, v2 offset0:188 offset1:254
	s_waitcnt lgkmcnt(0)
	ds_read2_b32 v[6:7], v51 offset1:8
	ds_read2_b32 v[46:47], v51 offset0:33 offset1:41
	ds_read2_b32 v[64:65], v51 offset0:66 offset1:74
	ds_read2_b32 v[66:67], v51 offset0:99 offset1:107
	ds_read2_b32 v[68:69], v51 offset0:132 offset1:140
	s_waitcnt lgkmcnt(4)
	v_bfe_u32 v2, v6, 16, 1
	v_add3_u32 v2, v6, v2, s89
	s_waitcnt lgkmcnt(3)
	v_bfe_u32 v3, v46, 16, 1
	v_lshrrev_b32_e32 v2, 16, v2
	v_add3_u32 v3, v46, v3, s89
	ds_read2_b32 v[70:71], v51 offset0:165 offset1:173
	v_and_or_b32 v2, v3, s90, v2
	s_waitcnt lgkmcnt(3)
	v_bfe_u32 v3, v64, 16, 1
	v_add3_u32 v3, v64, v3, s89
	s_waitcnt lgkmcnt(2)
	v_bfe_u32 v4, v66, 16, 1
	ds_read2_b32 v[72:73], v51 offset0:198 offset1:206
	v_lshrrev_b32_e32 v3, 16, v3
	v_add3_u32 v4, v66, v4, s89
	ds_read2_b32 v[74:75], v51 offset0:231 offset1:239
	v_and_or_b32 v3, v4, s90, v3
	s_waitcnt lgkmcnt(3)
	v_bfe_u32 v4, v68, 16, 1
	v_add3_u32 v4, v68, v4, s89
	s_waitcnt lgkmcnt(2)
	v_bfe_u32 v5, v70, 16, 1
	v_lshrrev_b32_e32 v4, 16, v4
	v_add3_u32 v5, v70, v5, s89
	v_and_or_b32 v4, v5, s90, v4
	s_waitcnt lgkmcnt(1)
	v_bfe_u32 v5, v72, 16, 1
	v_add3_u32 v5, v72, v5, s89
	s_waitcnt lgkmcnt(0)
	v_bfe_u32 v6, v74, 16, 1
	v_lshrrev_b32_e32 v5, 16, v5
	v_add3_u32 v6, v74, v6, s89
	v_and_or_b32 v5, v6, s90, v5
	v_or_b32_e32 v6, s4, v50
	v_lshl_add_u64 v[8:9], v[22:23], 0, s[26:27]
	v_lshlrev_b32_e32 v10, 11, v6
	v_lshl_add_u64 v[76:77], v[8:9], 0, v[10:11]
	global_store_dwordx4 v[76:77], v[2:5], off sc1
	v_bfe_u32 v6, v75, 16, 1
	v_or_b32_e32 v10, s4, v52
	v_bfe_u32 v2, v7, 16, 1
	v_add3_u32 v2, v7, v2, s89
	v_bfe_u32 v3, v47, 16, 1
	v_lshrrev_b32_e32 v2, 16, v2
	v_add3_u32 v3, v47, v3, s89
	v_and_or_b32 v2, v3, s90, v2
	v_bfe_u32 v3, v65, 16, 1
	v_add3_u32 v3, v65, v3, s89
	v_bfe_u32 v4, v67, 16, 1
	v_lshrrev_b32_e32 v3, 16, v3
	v_add3_u32 v4, v67, v4, s89
	v_and_or_b32 v3, v4, s90, v3
	v_bfe_u32 v4, v69, 16, 1
	v_add3_u32 v4, v69, v4, s89
	v_bfe_u32 v5, v71, 16, 1
	v_lshrrev_b32_e32 v4, 16, v4
	v_add3_u32 v5, v71, v5, s89
	v_and_or_b32 v4, v5, s90, v4
	v_bfe_u32 v5, v73, 16, 1
	v_add3_u32 v5, v73, v5, s89
	v_lshrrev_b32_e32 v5, 16, v5
	v_add3_u32 v6, v75, v6, s89
	v_lshlrev_b32_e32 v10, 11, v10
	v_and_or_b32 v5, v6, s90, v5
	ds_read2_b32 v[6:7], v51 offset0:16 offset1:24
	v_lshl_add_u64 v[46:47], v[8:9], 0, v[10:11]
	global_store_dwordx4 v[46:47], v[2:5], off sc1
	ds_read2_b32 v[46:47], v51 offset0:49 offset1:57
	ds_read2_b32 v[64:65], v51 offset0:82 offset1:90
	ds_read2_b32 v[66:67], v51 offset0:115 offset1:123
	s_waitcnt lgkmcnt(3)
	v_bfe_u32 v2, v6, 16, 1
	v_add3_u32 v2, v6, v2, s89
	s_waitcnt lgkmcnt(2)
	v_bfe_u32 v3, v46, 16, 1
	ds_read2_b32 v[68:69], v51 offset0:148 offset1:156
	v_lshrrev_b32_e32 v2, 16, v2
	v_add3_u32 v3, v46, v3, s89
	ds_read2_b32 v[70:71], v51 offset0:181 offset1:189
	v_and_or_b32 v2, v3, s90, v2
	s_waitcnt lgkmcnt(3)
	v_bfe_u32 v3, v64, 16, 1
	v_add3_u32 v3, v64, v3, s89
	s_waitcnt lgkmcnt(2)
	v_bfe_u32 v4, v66, 16, 1
	ds_read2_b32 v[72:73], v51 offset0:214 offset1:222
	v_lshrrev_b32_e32 v3, 16, v3
	v_add3_u32 v4, v66, v4, s89
	ds_read2_b32 v[74:75], v51 offset0:247 offset1:255
	v_and_or_b32 v3, v4, s90, v3
	s_waitcnt lgkmcnt(3)
	v_bfe_u32 v4, v68, 16, 1
	v_add3_u32 v4, v68, v4, s89
	s_waitcnt lgkmcnt(2)
	v_bfe_u32 v5, v70, 16, 1
	v_lshrrev_b32_e32 v4, 16, v4
	v_add3_u32 v5, v70, v5, s89
	v_and_or_b32 v4, v5, s90, v4
	s_waitcnt lgkmcnt(1)
	v_bfe_u32 v5, v72, 16, 1
	v_add3_u32 v5, v72, v5, s89
	s_waitcnt lgkmcnt(0)
	v_bfe_u32 v6, v74, 16, 1
	v_lshrrev_b32_e32 v5, 16, v5
	v_add3_u32 v6, v74, v6, s89
	v_and_or_b32 v5, v6, s90, v5
	v_or_b32_e32 v6, s4, v53
	v_lshlrev_b32_e32 v10, 11, v6
	v_lshl_add_u64 v[76:77], v[8:9], 0, v[10:11]
	global_store_dwordx4 v[76:77], v[2:5], off sc1
	v_bfe_u32 v6, v75, 16, 1
	v_add3_u32 v6, v75, v6, s89
	v_bfe_u32 v2, v7, 16, 1
	v_add3_u32 v2, v7, v2, s89
	v_bfe_u32 v3, v47, 16, 1
	v_lshrrev_b32_e32 v2, 16, v2
	v_add3_u32 v3, v47, v3, s89
	v_and_or_b32 v2, v3, s90, v2
	v_bfe_u32 v3, v65, 16, 1
	v_add3_u32 v3, v65, v3, s89
	v_bfe_u32 v4, v67, 16, 1
	v_lshrrev_b32_e32 v3, 16, v3
	v_add3_u32 v4, v67, v4, s89
	v_and_or_b32 v3, v4, s90, v3
	v_bfe_u32 v4, v69, 16, 1
	v_add3_u32 v4, v69, v4, s89
	v_bfe_u32 v5, v71, 16, 1
	v_lshrrev_b32_e32 v4, 16, v4
	v_add3_u32 v5, v71, v5, s89
	v_and_or_b32 v4, v5, s90, v4
	v_bfe_u32 v5, v73, 16, 1
	v_add3_u32 v5, v73, v5, s89
	v_lshrrev_b32_e32 v5, 16, v5
	v_and_or_b32 v5, v6, s90, v5
	v_or_b32_e32 v6, s4, v54
	v_lshlrev_b32_e32 v10, 11, v6
	v_lshl_add_u64 v[6:7], v[8:9], 0, v[10:11]
	global_store_dwordx4 v[6:7], v[2:5], off sc1
	s_waitcnt lgkmcnt(0)

.LBB0_72:
	s_waitcnt lgkmcnt(0)
	ds_read2_b32 v[8:9], v51 offset1:8
	ds_read2_b32 v[68:69], v51 offset0:66 offset1:74
	ds_read2_b32 v[72:73], v51 offset0:33 offset1:41
	ds_read2_b32 v[74:75], v51 offset0:99 offset1:107
	ds_read2_b32 v[76:77], v51 offset0:132 offset1:140
	ds_read2_b32 v[78:79], v51 offset0:198 offset1:206
	ds_read2_b32 v[80:81], v51 offset0:165 offset1:173
	ds_read2_b32 v[82:83], v51 offset0:231 offset1:239
	s_waitcnt lgkmcnt(7)
	v_mov_b32_e32 v64, v8
	s_waitcnt lgkmcnt(5)
	v_mov_b32_e32 v66, v72
	s_waitcnt lgkmcnt(4)
	v_mov_b32_e32 v67, v74
	s_waitcnt lgkmcnt(3)
	v_mov_b32_e32 v84, v76
	s_waitcnt lgkmcnt(2)
	v_mov_b32_e32 v85, v78
	v_mov_b32_e32 v65, v68
	v_pk_mul_f32 v[66:67], v[46:47], v[66:67]
	v_pk_mul_f32 v[84:85], v[6:7], v[84:85]
	s_waitcnt lgkmcnt(1)
	v_mov_b32_e32 v86, v80
	s_waitcnt lgkmcnt(0)
	v_mov_b32_e32 v87, v82
	v_pk_mul_f32 v[64:65], v[2:3], v[64:65]
	v_pk_mul_f32 v[86:87], v[4:5], v[86:87]
	v_bfe_u32 v68, v67, 16, 1
	v_bfe_u32 v76, v85, 16, 1
	v_bfe_u32 v8, v87, 16, 1
	v_add3_u32 v68, v67, v68, s89
	v_bfe_u32 v67, v65, 16, 1
	v_add3_u32 v76, v85, v76, s89
	v_bfe_u32 v72, v66, 16, 1
	v_add3_u32 v8, v87, v8, s89
	v_bfe_u32 v74, v84, 16, 1
	v_add3_u32 v65, v65, v67, s89
	v_lshrrev_b32_e32 v67, 16, v76
	v_bfe_u32 v10, v86, 16, 1
	v_add3_u32 v72, v66, v72, s89
	v_bfe_u32 v66, v64, 16, 1
	v_add3_u32 v74, v84, v74, s89
	v_lshrrev_b32_e32 v65, 16, v65
	v_and_or_b32 v67, v8, s90, v67
	v_or_b32_e32 v8, s4, v50
	s_lshl_b32 s26, s5, 1
	v_add3_u32 v10, v86, v10, s89
	v_add3_u32 v64, v64, v66, s89
	v_lshrrev_b32_e32 v66, 16, v74
	v_and_or_b32 v65, v68, s90, v65
	v_mul_u32_u24_e32 v8, 0x180, v8
	v_mov_b32_e32 v68, v9
	v_mov_b32_e32 v82, v81
	v_lshl_add_u64 v[70:71], v[40:41], 0, s[26:27]
	v_lshrrev_b32_e32 v64, 16, v64
	v_and_or_b32 v66, v10, s90, v66
	v_lshlrev_b32_e32 v10, 1, v8
	v_pk_mul_f32 v[8:9], v[2:3], v[68:69]
	v_pk_mul_f32 v[68:69], v[4:5], v[82:83]
	v_and_or_b32 v64, v72, s90, v64
	v_lshl_add_u64 v[84:85], v[70:71], 0, v[10:11]
	v_mov_b32_e32 v74, v73
	v_bfe_u32 v10, v69, 16, 1
	global_store_dwordx4 v[84:85], v[64:67], off sc1
	v_mov_b32_e32 v78, v77
	v_add3_u32 v10, v69, v10, s89
	v_pk_mul_f32 v[64:65], v[46:47], v[74:75]
	v_bfe_u32 v69, v8, 16, 1
	v_pk_mul_f32 v[66:67], v[6:7], v[78:79]
	v_bfe_u32 v74, v64, 16, 1
	v_add3_u32 v8, v8, v69, s89
	v_bfe_u32 v72, v68, 16, 1
	v_bfe_u32 v73, v65, 16, 1
	v_add3_u32 v64, v64, v74, s89
	v_bfe_u32 v74, v67, 16, 1
	v_lshrrev_b32_e32 v8, 16, v8
	v_add3_u32 v65, v65, v73, s89
	v_add3_u32 v68, v68, v72, s89
	v_bfe_u32 v72, v9, 16, 1
	v_bfe_u32 v73, v66, 16, 1
	v_add3_u32 v67, v67, v74, s89
	v_and_or_b32 v64, v64, s90, v8
	v_or_b32_e32 v8, s4, v52
	v_add3_u32 v66, v66, v73, s89
	v_add3_u32 v9, v9, v72, s89
	v_lshrrev_b32_e32 v67, 16, v67
	v_mul_u32_u24_e32 v8, 0x180, v8
	v_lshrrev_b32_e32 v9, 16, v9
	v_lshrrev_b32_e32 v66, 16, v66
	v_and_or_b32 v67, v10, s90, v67
	v_lshlrev_b32_e32 v10, 1, v8
	v_and_or_b32 v66, v68, s90, v66
	v_and_or_b32 v65, v65, s90, v9
	v_lshl_add_u64 v[8:9], v[70:71], 0, v[10:11]
	ds_read2_b32 v[68:69], v51 offset0:16 offset1:24
	ds_read2_b32 v[72:73], v51 offset0:82 offset1:90
	global_store_dwordx4 v[8:9], v[64:67], off sc1
	ds_read2_b32 v[8:9], v51 offset0:49 offset1:57
	ds_read2_b32 v[74:75], v51 offset0:115 offset1:123
	ds_read2_b32 v[76:77], v51 offset0:148 offset1:156
	ds_read2_b32 v[78:79], v51 offset0:214 offset1:222
	ds_read2_b32 v[80:81], v51 offset0:181 offset1:189
	ds_read2_b32 v[82:83], v51 offset0:247 offset1:255
	s_waitcnt lgkmcnt(7)
	v_mov_b32_e32 v64, v68
	s_waitcnt lgkmcnt(5)
	v_mov_b32_e32 v66, v8
	s_waitcnt lgkmcnt(4)
	v_mov_b32_e32 v67, v74
	s_waitcnt lgkmcnt(3)
	v_mov_b32_e32 v84, v76
	s_waitcnt lgkmcnt(2)
	v_mov_b32_e32 v85, v78
	v_mov_b32_e32 v65, v72
	v_pk_mul_f32 v[66:67], v[46:47], v[66:67]
	v_pk_mul_f32 v[84:85], v[6:7], v[84:85]
	s_waitcnt lgkmcnt(1)
	v_mov_b32_e32 v86, v80
	s_waitcnt lgkmcnt(0)
	v_mov_b32_e32 v87, v82
	v_pk_mul_f32 v[64:65], v[2:3], v[64:65]
	v_pk_mul_f32 v[86:87], v[4:5], v[86:87]
	v_bfe_u32 v68, v67, 16, 1
	v_bfe_u32 v76, v85, 16, 1
	v_bfe_u32 v8, v87, 16, 1
	v_add3_u32 v68, v67, v68, s89
	v_bfe_u32 v67, v65, 16, 1
	v_add3_u32 v76, v85, v76, s89
	v_bfe_u32 v72, v66, 16, 1
	v_add3_u32 v8, v87, v8, s89
	v_bfe_u32 v74, v84, 16, 1
	v_add3_u32 v65, v65, v67, s89
	v_lshrrev_b32_e32 v67, 16, v76
	v_bfe_u32 v10, v86, 16, 1
	v_add3_u32 v72, v66, v72, s89
	v_bfe_u32 v66, v64, 16, 1
	v_add3_u32 v74, v84, v74, s89
	v_and_or_b32 v67, v8, s90, v67
	v_or_b32_e32 v8, s4, v53
	v_add3_u32 v10, v86, v10, s89
	v_add3_u32 v64, v64, v66, s89
	v_lshrrev_b32_e32 v66, 16, v74
	v_mul_u32_u24_e32 v8, 0x180, v8
	v_mov_b32_e32 v74, v9
	v_and_or_b32 v66, v10, s90, v66
	v_lshlrev_b32_e32 v10, 1, v8
	v_pk_mul_f32 v[8:9], v[46:47], v[74:75]
	v_mov_b32_e32 v78, v77
	v_pk_mul_f32 v[6:7], v[6:7], v[78:79]
	v_mov_b32_e32 v82, v81
	v_bfe_u32 v47, v9, 16, 1
	v_lshrrev_b32_e32 v64, 16, v64
	v_lshrrev_b32_e32 v65, 16, v65
	v_pk_mul_f32 v[4:5], v[4:5], v[82:83]
	v_add3_u32 v9, v9, v47, s89
	v_bfe_u32 v47, v6, 16, 1
	v_and_or_b32 v65, v68, s90, v65
	v_and_or_b32 v64, v72, s90, v64
	v_lshl_add_u64 v[84:85], v[70:71], 0, v[10:11]
	v_mov_b32_e32 v72, v69
	v_bfe_u32 v46, v4, 16, 1
	v_add3_u32 v6, v6, v47, s89
	global_store_dwordx4 v[84:85], v[64:67], off sc1
	v_pk_mul_f32 v[2:3], v[2:3], v[72:73]
	v_bfe_u32 v10, v5, 16, 1
	v_bfe_u32 v64, v8, 16, 1
	v_add3_u32 v4, v4, v46, s89
	v_lshrrev_b32_e32 v6, 16, v6
	v_add3_u32 v8, v8, v64, s89
	v_add3_u32 v5, v5, v10, s89
	v_bfe_u32 v10, v2, 16, 1
	v_bfe_u32 v46, v3, 16, 1
	v_bfe_u32 v64, v7, 16, 1
	v_and_or_b32 v4, v4, s90, v6
	v_or_b32_e32 v6, s4, v54
	v_add3_u32 v7, v7, v64, s89
	v_add3_u32 v3, v3, v46, s89
	v_add3_u32 v2, v2, v10, s89
	v_mul_u32_u24_e32 v6, 0x180, v6
	v_lshrrev_b32_e32 v2, 16, v2
	v_lshrrev_b32_e32 v3, 16, v3
	v_lshrrev_b32_e32 v7, 16, v7
	v_lshlrev_b32_e32 v10, 1, v6
	v_and_or_b32 v5, v5, s90, v7
	v_and_or_b32 v3, v9, s90, v3
	v_and_or_b32 v2, v8, s90, v2
	v_lshl_add_u64 v[6:7], v[70:71], 0, v[10:11]
	global_store_dwordx4 v[6:7], v[2:5], off sc1
	s_waitcnt lgkmcnt(0)

.LBB0_78:
	s_waitcnt lgkmcnt(0)
	ds_read2_b32 v[8:9], v51 offset1:8
	ds_read2_b32 v[68:69], v51 offset0:66 offset1:74
	ds_read2_b32 v[72:73], v51 offset0:33 offset1:41
	ds_read2_b32 v[74:75], v51 offset0:99 offset1:107
	ds_read2_b32 v[76:77], v51 offset0:132 offset1:140
	ds_read2_b32 v[78:79], v51 offset0:198 offset1:206
	ds_read2_b32 v[80:81], v51 offset0:165 offset1:173
	ds_read2_b32 v[82:83], v51 offset0:231 offset1:239
	s_waitcnt lgkmcnt(7)
	v_mov_b32_e32 v64, v8
	s_waitcnt lgkmcnt(5)
	v_mov_b32_e32 v66, v72
	s_waitcnt lgkmcnt(4)
	v_mov_b32_e32 v67, v74
	s_waitcnt lgkmcnt(3)
	v_mov_b32_e32 v84, v76
	s_waitcnt lgkmcnt(2)
	v_mov_b32_e32 v85, v78
	v_mov_b32_e32 v65, v68
	v_pk_mul_f32 v[66:67], v[46:47], v[66:67]
	v_pk_mul_f32 v[84:85], v[6:7], v[84:85]
	s_waitcnt lgkmcnt(1)
	v_mov_b32_e32 v86, v80
	s_waitcnt lgkmcnt(0)
	v_mov_b32_e32 v87, v82
	v_pk_mul_f32 v[64:65], v[2:3], v[64:65]
	v_pk_mul_f32 v[86:87], v[4:5], v[86:87]
	v_bfe_u32 v68, v67, 16, 1
	v_bfe_u32 v76, v85, 16, 1
	v_bfe_u32 v8, v87, 16, 1
	v_bfe_u32 v72, v66, 16, 1
	v_add3_u32 v68, v67, v68, s89
	v_bfe_u32 v67, v65, 16, 1
	v_bfe_u32 v74, v84, 16, 1
	v_add3_u32 v76, v85, v76, s89
	v_bfe_u32 v10, v86, 16, 1
	v_add3_u32 v72, v66, v72, s89
	v_add3_u32 v8, v87, v8, s89
	v_bfe_u32 v66, v64, 16, 1
	v_add3_u32 v74, v84, v74, s89
	v_add3_u32 v65, v65, v67, s89
	v_lshrrev_b32_e32 v67, 16, v76
	v_add3_u32 v10, v86, v10, s89
	v_add3_u32 v64, v64, v66, s89
	v_lshrrev_b32_e32 v65, 16, v65
	v_lshrrev_b32_e32 v66, 16, v74
	v_and_or_b32 v67, v8, s90, v67
	v_or_b32_e32 v8, s4, v50
	v_lshl_add_u64 v[70:71], s[26:27], 1, v[42:43]
	v_lshrrev_b32_e32 v64, 16, v64
	v_and_or_b32 v66, v10, s90, v66
	v_and_or_b32 v65, v68, s90, v65
	v_lshlrev_b32_e32 v10, 9, v8
	v_mov_b32_e32 v68, v9
	v_mov_b32_e32 v82, v81
	v_and_or_b32 v64, v72, s90, v64
	v_lshl_add_u64 v[84:85], v[70:71], 0, v[10:11]
	v_pk_mul_f32 v[8:9], v[2:3], v[68:69]
	v_mov_b32_e32 v74, v73
	v_pk_mul_f32 v[68:69], v[4:5], v[82:83]
	global_store_dwordx4 v[84:85], v[64:67], off sc1
	v_mov_b32_e32 v78, v77
	v_bfe_u32 v10, v69, 16, 1
	v_pk_mul_f32 v[64:65], v[46:47], v[74:75]
	v_pk_mul_f32 v[66:67], v[6:7], v[78:79]
	v_bfe_u32 v74, v64, 16, 1
	v_add3_u32 v10, v69, v10, s89
	v_bfe_u32 v69, v8, 16, 1
	v_bfe_u32 v72, v68, 16, 1
	v_bfe_u32 v73, v65, 16, 1
	v_add3_u32 v64, v64, v74, s89
	v_bfe_u32 v74, v67, 16, 1
	v_add3_u32 v8, v8, v69, s89
	v_add3_u32 v65, v65, v73, s89
	v_add3_u32 v68, v68, v72, s89
	v_bfe_u32 v72, v9, 16, 1
	v_bfe_u32 v73, v66, 16, 1
	v_add3_u32 v67, v67, v74, s89
	v_lshrrev_b32_e32 v8, 16, v8
	v_add3_u32 v66, v66, v73, s89
	v_add3_u32 v9, v9, v72, s89
	v_lshrrev_b32_e32 v67, 16, v67
	v_and_or_b32 v64, v64, s90, v8
	v_or_b32_e32 v8, s4, v52
	v_lshrrev_b32_e32 v9, 16, v9
	v_lshrrev_b32_e32 v66, 16, v66
	v_and_or_b32 v67, v10, s90, v67
	v_lshlrev_b32_e32 v10, 9, v8
	v_and_or_b32 v66, v68, s90, v66
	v_and_or_b32 v65, v65, s90, v9
	v_lshl_add_u64 v[8:9], v[70:71], 0, v[10:11]
	ds_read2_b32 v[68:69], v51 offset0:16 offset1:24
	ds_read2_b32 v[72:73], v51 offset0:82 offset1:90
	global_store_dwordx4 v[8:9], v[64:67], off sc1
	ds_read2_b32 v[8:9], v51 offset0:49 offset1:57
	ds_read2_b32 v[74:75], v51 offset0:115 offset1:123
	ds_read2_b32 v[76:77], v51 offset0:148 offset1:156
	ds_read2_b32 v[78:79], v51 offset0:214 offset1:222
	ds_read2_b32 v[80:81], v51 offset0:181 offset1:189
	ds_read2_b32 v[82:83], v51 offset0:247 offset1:255
	s_waitcnt lgkmcnt(7)
	v_mov_b32_e32 v64, v68
	s_waitcnt lgkmcnt(5)
	v_mov_b32_e32 v66, v8
	s_waitcnt lgkmcnt(4)
	v_mov_b32_e32 v67, v74
	s_waitcnt lgkmcnt(3)
	v_mov_b32_e32 v84, v76
	s_waitcnt lgkmcnt(2)
	v_mov_b32_e32 v85, v78
	v_mov_b32_e32 v65, v72
	v_pk_mul_f32 v[66:67], v[46:47], v[66:67]
	v_pk_mul_f32 v[84:85], v[6:7], v[84:85]
	s_waitcnt lgkmcnt(1)
	v_mov_b32_e32 v86, v80
	s_waitcnt lgkmcnt(0)
	v_mov_b32_e32 v87, v82
	v_pk_mul_f32 v[64:65], v[2:3], v[64:65]
	v_pk_mul_f32 v[86:87], v[4:5], v[86:87]
	v_bfe_u32 v68, v67, 16, 1
	v_bfe_u32 v76, v85, 16, 1
	v_bfe_u32 v8, v87, 16, 1
	v_bfe_u32 v72, v66, 16, 1
	v_add3_u32 v68, v67, v68, s89
	v_bfe_u32 v67, v65, 16, 1
	v_bfe_u32 v74, v84, 16, 1
	v_add3_u32 v76, v85, v76, s89
	v_bfe_u32 v10, v86, 16, 1
	v_add3_u32 v72, v66, v72, s89
	v_add3_u32 v8, v87, v8, s89
	v_bfe_u32 v66, v64, 16, 1
	v_add3_u32 v74, v84, v74, s89
	v_add3_u32 v65, v65, v67, s89
	v_lshrrev_b32_e32 v67, 16, v76
	v_add3_u32 v10, v86, v10, s89
	v_add3_u32 v64, v64, v66, s89
	v_lshrrev_b32_e32 v66, 16, v74
	v_and_or_b32 v67, v8, s90, v67
	v_or_b32_e32 v8, s4, v53
	v_mov_b32_e32 v74, v9
	v_and_or_b32 v66, v10, s90, v66
	v_lshlrev_b32_e32 v10, 9, v8
	v_pk_mul_f32 v[8:9], v[46:47], v[74:75]
	v_mov_b32_e32 v78, v77
	v_lshrrev_b32_e32 v64, 16, v64
	v_lshrrev_b32_e32 v65, 16, v65
	v_pk_mul_f32 v[6:7], v[6:7], v[78:79]
	v_mov_b32_e32 v82, v81
	v_bfe_u32 v47, v9, 16, 1
	v_and_or_b32 v65, v68, s90, v65
	v_and_or_b32 v64, v72, s90, v64
	v_lshl_add_u64 v[84:85], v[70:71], 0, v[10:11]
	v_mov_b32_e32 v72, v69
	v_pk_mul_f32 v[4:5], v[4:5], v[82:83]
	v_add3_u32 v9, v9, v47, s89
	v_bfe_u32 v47, v6, 16, 1
	global_store_dwordx4 v[84:85], v[64:67], off sc1
	v_pk_mul_f32 v[2:3], v[2:3], v[72:73]
	v_bfe_u32 v10, v5, 16, 1
	v_bfe_u32 v46, v4, 16, 1
	v_bfe_u32 v64, v8, 16, 1
	v_add3_u32 v6, v6, v47, s89
	v_add3_u32 v8, v8, v64, s89
	v_add3_u32 v4, v4, v46, s89
	v_add3_u32 v5, v5, v10, s89
	v_bfe_u32 v10, v2, 16, 1
	v_bfe_u32 v46, v3, 16, 1
	v_bfe_u32 v64, v7, 16, 1
	v_lshrrev_b32_e32 v6, 16, v6
	v_add3_u32 v7, v7, v64, s89
	v_add3_u32 v3, v3, v46, s89
	v_add3_u32 v2, v2, v10, s89
	v_and_or_b32 v4, v4, s90, v6
	v_or_b32_e32 v6, s4, v54
	v_lshrrev_b32_e32 v2, 16, v2
	v_lshrrev_b32_e32 v3, 16, v3
	v_lshrrev_b32_e32 v7, 16, v7
	v_lshlrev_b32_e32 v10, 9, v6
	v_and_or_b32 v5, v5, s90, v7
	v_and_or_b32 v3, v9, s90, v3
	v_and_or_b32 v2, v8, s90, v2
	v_lshl_add_u64 v[6:7], v[70:71], 0, v[10:11]
	global_store_dwordx4 v[6:7], v[2:5], off sc1
	s_waitcnt lgkmcnt(0)

.LBB0_80:
	s_andn2_b64 vcc, exec, s[28:29]
	s_cbranch_vccnz .LBB0_98
	s_add_i32 s4, s18, 0xf800
	s_and_b32 s5, s4, 0xffff
	s_mul_i32 s5, s5, 0xaaab
	s_lshr_b32 s26, s5, 20
	s_lshl_b32 s5, s26, 6
	s_mul_i32 s26, s26, 24
	s_sub_i32 s26, s4, s26
	s_lshl_b32 s4, s26, 5
	s_and_b32 s4, s4, 0xffe0
	s_and_b32 s26, s26, 0xffff
	v_or_b32_e32 v64, s4, v1
	s_cmp_gt_u32 s26, 7
	s_mov_b64 s[28:29], -1
	s_cbranch_scc0 .LBB0_93
	s_cmp_gt_u32 s26, 19
	s_cbranch_scc0 .LBB0_90
	s_cmp_gt_u32 s26, 21
	s_cbranch_scc0 .LBB0_85
	v_or_b32_e32 v2, s5, v48
	v_mul_u32_u24_e32 v2, 0x140, v2
	v_lshlrev_b32_e32 v10, 2, v2
	v_lshl_add_u64 v[2:3], s[66:67], 0, v[10:11]
	v_add_co_u32_e32 v4, vcc, 0x1000, v2
	global_load_dword v65, v10, s[66:67]
	s_nop 0
	global_load_dword v10, v10, s[66:67] offset:2560
	v_addc_co_u32_e32 v5, vcc, 0, v3, vcc
	v_add_co_u32_e32 v6, vcc, 0x2000, v2
	s_lshl_b32 s26, s5, 1
	s_nop 0
	v_addc_co_u32_e32 v7, vcc, 0, v3, vcc
	v_add_co_u32_e32 v8, vcc, 0x3000, v2
	s_mov_b64 s[28:29], 0
	s_nop 0
	v_addc_co_u32_e32 v9, vcc, 0, v3, vcc
	v_add_co_u32_e32 v46, vcc, 0x4000, v2
	s_nop 1
	v_addc_co_u32_e32 v47, vcc, 0, v3, vcc
	v_add_co_u32_e32 v66, vcc, 0x5000, v2
	s_nop 1
	v_addc_co_u32_e32 v67, vcc, 0, v3, vcc
	global_load_dword v68, v[4:5], off offset:1024
	global_load_dword v69, v[4:5], off offset:3584
	global_load_dword v70, v[6:7], off offset:2048
	global_load_dword v71, v[8:9], off offset:512
	global_load_dword v72, v[8:9], off offset:3072
	global_load_dword v73, v[46:47], off offset:1536
	global_load_dword v74, v[66:67], off
	global_load_dword v75, v[66:67], off offset:2560
	v_add_co_u32_e32 v4, vcc, 0x6000, v2
	s_nop 1
	v_addc_co_u32_e32 v5, vcc, 0, v3, vcc
	v_add_co_u32_e32 v6, vcc, 0x7000, v2
	s_nop 1
	v_addc_co_u32_e32 v7, vcc, 0, v3, vcc
	v_add_co_u32_e32 v8, vcc, 0x8000, v2
	s_nop 1
	v_addc_co_u32_e32 v9, vcc, 0, v3, vcc
	v_add_co_u32_e32 v46, vcc, 0x9000, v2
	s_nop 1
	v_addc_co_u32_e32 v47, vcc, 0, v3, vcc
	v_add_co_u32_e32 v66, vcc, 0xa000, v2
	s_nop 1
	v_addc_co_u32_e32 v67, vcc, 0, v3, vcc
	global_load_dword v76, v[4:5], off offset:1024
	global_load_dword v77, v[4:5], off offset:3584
	global_load_dword v78, v[6:7], off offset:2048
	global_load_dword v79, v[8:9], off offset:512
	global_load_dword v80, v[8:9], off offset:3072
	global_load_dword v81, v[46:47], off offset:1536
	global_load_dword v82, v[66:67], off
	global_load_dword v83, v[66:67], off offset:2560
	v_add_co_u32_e32 v4, vcc, 0xb000, v2
	s_nop 1
	v_addc_co_u32_e32 v5, vcc, 0, v3, vcc
	v_add_co_u32_e32 v6, vcc, 0xc000, v2
	s_nop 1
	v_addc_co_u32_e32 v7, vcc, 0, v3, vcc
	v_add_co_u32_e32 v8, vcc, 0xd000, v2
	s_nop 1
	v_addc_co_u32_e32 v9, vcc, 0, v3, vcc
	v_add_co_u32_e32 v46, vcc, 0xe000, v2
	s_nop 1
	v_addc_co_u32_e32 v47, vcc, 0, v3, vcc
	v_add_co_u32_e32 v66, vcc, 0xf000, v2
	s_nop 1
	v_addc_co_u32_e32 v67, vcc, 0, v3, vcc
	global_load_dword v84, v[4:5], off offset:1024
	global_load_dword v85, v[4:5], off offset:3584
	global_load_dword v86, v[6:7], off offset:2048
	global_load_dword v87, v[8:9], off offset:512
	global_load_dword v88, v[8:9], off offset:3072
	s_nop 0
	global_load_dword v46, v[46:47], off offset:1536
	s_nop 0
	global_load_dword v47, v[66:67], off
	s_nop 0
	global_load_dword v66, v[66:67], off offset:2560
	v_add_co_u32_e32 v4, vcc, 0x10000, v2
	s_nop 1
	v_addc_co_u32_e32 v5, vcc, 0, v3, vcc
	v_add_co_u32_e32 v6, vcc, 0x11000, v2
	s_nop 1
	v_addc_co_u32_e32 v7, vcc, 0, v3, vcc
	v_add_co_u32_e32 v8, vcc, 0x12000, v2
	s_nop 1
	v_addc_co_u32_e32 v9, vcc, 0, v3, vcc
	global_load_dword v67, v[4:5], off offset:1024
	s_nop 0
	global_load_dword v4, v[4:5], off offset:3584
	s_nop 0
	global_load_dword v5, v[6:7], off offset:2048
	s_nop 0
	global_load_dword v6, v[8:9], off offset:512
	v_add_co_u32_e32 v2, vcc, 0x13000, v2
	s_waitcnt vmcnt(2)
	v_mul_f32_e32 v4, 0, v4
	v_addc_co_u32_e32 v3, vcc, 0, v3, vcc
	global_load_dword v7, v[8:9], off offset:3072
	s_nop 0
	global_load_dword v2, v[2:3], off offset:1536
	v_mul_f32_e32 v3, 0, v65
	v_mul_f32_e32 v8, 0, v10
	ds_write2_b32 v49, v3, v8 offset1:66
	v_mul_f32_e32 v3, 0, v68
	v_mul_f32_e32 v8, 0, v69
	ds_write2_b32 v49, v3, v8 offset0:132 offset1:198
	v_mul_f32_e32 v3, 0, v70
	v_mul_f32_e32 v8, 0, v71
	ds_write2_b32 v57, v3, v8 offset0:8 offset1:74
	v_mul_f32_e32 v3, 0, v72
	v_mul_f32_e32 v8, 0, v73
	ds_write2_b32 v57, v3, v8 offset0:140 offset1:206
	v_mul_f32_e32 v3, 0, v74
	v_mul_f32_e32 v8, 0, v75
	ds_write2_b32 v58, v3, v8 offset0:16 offset1:82
	v_mul_f32_e32 v3, 0, v76
	v_mul_f32_e32 v8, 0, v77
	ds_write2_b32 v58, v3, v8 offset0:148 offset1:214
	v_mul_f32_e32 v3, 0, v78
	v_mul_f32_e32 v8, 0, v79
	ds_write2_b32 v59, v3, v8 offset0:24 offset1:90
	v_mul_f32_e32 v3, 0, v80
	v_mul_f32_e32 v8, 0, v81
	ds_write2_b32 v59, v3, v8 offset0:156 offset1:222
	v_mul_f32_e32 v3, 0, v82
	v_mul_f32_e32 v8, 0, v83
	ds_write2_b32 v60, v3, v8 offset0:32 offset1:98
	v_mul_f32_e32 v3, 0, v84
	v_mul_f32_e32 v8, 0, v85
	ds_write2_b32 v60, v3, v8 offset0:164 offset1:230
	v_mul_f32_e32 v3, 0, v86
	v_mul_f32_e32 v8, 0, v87
	ds_write2_b32 v61, v3, v8 offset0:40 offset1:106
	v_mul_f32_e32 v3, 0, v88
	v_mul_f32_e32 v8, 0, v46
	ds_write2_b32 v61, v3, v8 offset0:172 offset1:238
	v_mul_f32_e32 v3, 0, v47
	v_mul_f32_e32 v8, 0, v66
	ds_write2_b32 v62, v3, v8 offset0:48 offset1:114
	v_mul_f32_e32 v3, 0, v67
	ds_write2_b32 v62, v3, v4 offset0:180 offset1:246
	s_waitcnt vmcnt(3)
	v_mul_f32_e32 v3, 0, v5
	s_waitcnt vmcnt(2)
	v_mul_f32_e32 v4, 0, v6
	ds_write2_b32 v63, v3, v4 offset0:56 offset1:122
	v_lshl_add_u64 v[8:9], v[28:29], 0, s[26:27]
	s_waitcnt vmcnt(1)
	v_mul_f32_e32 v3, 0, v7
	s_waitcnt vmcnt(0)
	v_mul_f32_e32 v2, 0, v2
	ds_write2_b32 v63, v3, v2 offset0:188 offset1:254
	s_waitcnt lgkmcnt(0)
	ds_read2_b32 v[6:7], v51 offset1:8
	ds_read2_b32 v[46:47], v51 offset0:33 offset1:41
	ds_read2_b32 v[66:67], v51 offset0:66 offset1:74
	ds_read2_b32 v[68:69], v51 offset0:99 offset1:107
	ds_read2_b32 v[70:71], v51 offset0:132 offset1:140
	s_waitcnt lgkmcnt(4)
	v_bfe_u32 v2, v6, 16, 1
	v_add3_u32 v2, v6, v2, s89
	s_waitcnt lgkmcnt(3)
	v_bfe_u32 v3, v46, 16, 1
	v_lshrrev_b32_e32 v2, 16, v2
	v_add3_u32 v3, v46, v3, s89
	ds_read2_b32 v[72:73], v51 offset0:165 offset1:173
	v_and_or_b32 v2, v3, s90, v2
	s_waitcnt lgkmcnt(3)
	v_bfe_u32 v3, v66, 16, 1
	v_add3_u32 v3, v66, v3, s89
	s_waitcnt lgkmcnt(2)
	v_bfe_u32 v4, v68, 16, 1
	ds_read2_b32 v[74:75], v51 offset0:198 offset1:206
	v_lshrrev_b32_e32 v3, 16, v3
	v_add3_u32 v4, v68, v4, s89
	ds_read2_b32 v[76:77], v51 offset0:231 offset1:239
	v_and_or_b32 v3, v4, s90, v3
	s_waitcnt lgkmcnt(3)
	v_bfe_u32 v4, v70, 16, 1
	v_add3_u32 v4, v70, v4, s89
	s_waitcnt lgkmcnt(2)
	v_bfe_u32 v5, v72, 16, 1
	v_lshrrev_b32_e32 v4, 16, v4
	v_add3_u32 v5, v72, v5, s89
	v_and_or_b32 v4, v5, s90, v4
	s_waitcnt lgkmcnt(1)
	v_bfe_u32 v5, v74, 16, 1
	v_add3_u32 v5, v74, v5, s89
	s_waitcnt lgkmcnt(0)
	v_bfe_u32 v6, v76, 16, 1
	v_lshrrev_b32_e32 v5, 16, v5
	v_add3_u32 v6, v76, v6, s89
	v_and_or_b32 v5, v6, s90, v5
	v_or_b32_e32 v6, s4, v50
	v_lshlrev_b32_e32 v10, 11, v6
	v_lshl_add_u64 v[78:79], v[8:9], 0, v[10:11]
	global_store_dwordx4 v[78:79], v[2:5], off sc1
	v_bfe_u32 v6, v77, 16, 1
	v_or_b32_e32 v10, s4, v52
	v_bfe_u32 v2, v7, 16, 1
	v_add3_u32 v2, v7, v2, s89
	v_bfe_u32 v3, v47, 16, 1
	v_lshrrev_b32_e32 v2, 16, v2
	v_add3_u32 v3, v47, v3, s89
	v_and_or_b32 v2, v3, s90, v2
	v_bfe_u32 v3, v67, 16, 1
	v_add3_u32 v3, v67, v3, s89
	v_bfe_u32 v4, v69, 16, 1
	v_lshrrev_b32_e32 v3, 16, v3
	v_add3_u32 v4, v69, v4, s89
	v_and_or_b32 v3, v4, s90, v3
	v_bfe_u32 v4, v71, 16, 1
	v_add3_u32 v4, v71, v4, s89
	v_bfe_u32 v5, v73, 16, 1
	v_lshrrev_b32_e32 v4, 16, v4
	v_add3_u32 v5, v73, v5, s89
	v_and_or_b32 v4, v5, s90, v4
	v_bfe_u32 v5, v75, 16, 1
	v_add3_u32 v5, v75, v5, s89
	v_lshrrev_b32_e32 v5, 16, v5
	v_add3_u32 v6, v77, v6, s89
	v_lshlrev_b32_e32 v10, 11, v10
	v_and_or_b32 v5, v6, s90, v5
	ds_read2_b32 v[6:7], v51 offset0:16 offset1:24
	v_lshl_add_u64 v[46:47], v[8:9], 0, v[10:11]
	global_store_dwordx4 v[46:47], v[2:5], off sc1
	ds_read2_b32 v[46:47], v51 offset0:49 offset1:57
	ds_read2_b32 v[66:67], v51 offset0:82 offset1:90
	ds_read2_b32 v[68:69], v51 offset0:115 offset1:123
	s_waitcnt lgkmcnt(3)
	v_bfe_u32 v2, v6, 16, 1
	v_add3_u32 v2, v6, v2, s89
	s_waitcnt lgkmcnt(2)
	v_bfe_u32 v3, v46, 16, 1
	ds_read2_b32 v[70:71], v51 offset0:148 offset1:156
	v_lshrrev_b32_e32 v2, 16, v2
	v_add3_u32 v3, v46, v3, s89
	ds_read2_b32 v[72:73], v51 offset0:181 offset1:189
	v_and_or_b32 v2, v3, s90, v2
	s_waitcnt lgkmcnt(3)
	v_bfe_u32 v3, v66, 16, 1
	v_add3_u32 v3, v66, v3, s89
	s_waitcnt lgkmcnt(2)
	v_bfe_u32 v4, v68, 16, 1
	ds_read2_b32 v[74:75], v51 offset0:214 offset1:222
	v_lshrrev_b32_e32 v3, 16, v3
	v_add3_u32 v4, v68, v4, s89
	ds_read2_b32 v[76:77], v51 offset0:247 offset1:255
	v_and_or_b32 v3, v4, s90, v3
	s_waitcnt lgkmcnt(3)
	v_bfe_u32 v4, v70, 16, 1
	v_add3_u32 v4, v70, v4, s89
	s_waitcnt lgkmcnt(2)
	v_bfe_u32 v5, v72, 16, 1
	v_lshrrev_b32_e32 v4, 16, v4
	v_add3_u32 v5, v72, v5, s89
	v_and_or_b32 v4, v5, s90, v4
	s_waitcnt lgkmcnt(1)
	v_bfe_u32 v5, v74, 16, 1
	v_add3_u32 v5, v74, v5, s89
	s_waitcnt lgkmcnt(0)
	v_bfe_u32 v6, v76, 16, 1
	v_lshrrev_b32_e32 v5, 16, v5
	v_add3_u32 v6, v76, v6, s89
	v_and_or_b32 v5, v6, s90, v5
	v_or_b32_e32 v6, s4, v53
	v_lshlrev_b32_e32 v10, 11, v6
	v_lshl_add_u64 v[78:79], v[8:9], 0, v[10:11]
	global_store_dwordx4 v[78:79], v[2:5], off sc1
	v_bfe_u32 v6, v77, 16, 1
	v_add3_u32 v6, v77, v6, s89
	v_bfe_u32 v2, v7, 16, 1
	v_add3_u32 v2, v7, v2, s89
	v_bfe_u32 v3, v47, 16, 1
	v_lshrrev_b32_e32 v2, 16, v2
	v_add3_u32 v3, v47, v3, s89
	v_and_or_b32 v2, v3, s90, v2
	v_bfe_u32 v3, v67, 16, 1
	v_add3_u32 v3, v67, v3, s89
	v_bfe_u32 v4, v69, 16, 1
	v_lshrrev_b32_e32 v3, 16, v3
	v_add3_u32 v4, v69, v4, s89
	v_and_or_b32 v3, v4, s90, v3
	v_bfe_u32 v4, v71, 16, 1
	v_add3_u32 v4, v71, v4, s89
	v_bfe_u32 v5, v73, 16, 1
	v_lshrrev_b32_e32 v4, 16, v4
	v_add3_u32 v5, v73, v5, s89
	v_and_or_b32 v4, v5, s90, v4
	v_bfe_u32 v5, v75, 16, 1
	v_add3_u32 v5, v75, v5, s89
	v_lshrrev_b32_e32 v5, 16, v5
	v_and_or_b32 v5, v6, s90, v5
	v_or_b32_e32 v6, s4, v54
	v_lshlrev_b32_e32 v10, 11, v6
	v_lshl_add_u64 v[6:7], v[8:9], 0, v[10:11]
	global_store_dwordx4 v[6:7], v[2:5], off sc1
	s_waitcnt lgkmcnt(0)

.LBB0_88:
	s_waitcnt lgkmcnt(0)
	ds_read2_b32 v[8:9], v51 offset1:8
	ds_read2_b32 v[70:71], v51 offset0:66 offset1:74
	ds_read2_b32 v[74:75], v51 offset0:33 offset1:41
	ds_read2_b32 v[76:77], v51 offset0:99 offset1:107
	ds_read2_b32 v[78:79], v51 offset0:132 offset1:140
	ds_read2_b32 v[80:81], v51 offset0:198 offset1:206
	ds_read2_b32 v[82:83], v51 offset0:165 offset1:173
	ds_read2_b32 v[84:85], v51 offset0:231 offset1:239
	s_waitcnt lgkmcnt(7)
	v_mov_b32_e32 v66, v8
	s_waitcnt lgkmcnt(5)
	v_mov_b32_e32 v68, v74
	s_waitcnt lgkmcnt(4)
	v_mov_b32_e32 v69, v76
	s_waitcnt lgkmcnt(3)
	v_mov_b32_e32 v86, v78
	s_waitcnt lgkmcnt(2)
	v_mov_b32_e32 v87, v80
	v_mov_b32_e32 v67, v70
	v_pk_mul_f32 v[68:69], v[46:47], v[68:69]
	v_pk_mul_f32 v[86:87], v[6:7], v[86:87]
	s_waitcnt lgkmcnt(1)
	v_mov_b32_e32 v88, v82
	s_waitcnt lgkmcnt(0)
	v_mov_b32_e32 v89, v84
	v_pk_mul_f32 v[66:67], v[2:3], v[66:67]
	v_pk_mul_f32 v[88:89], v[4:5], v[88:89]
	v_bfe_u32 v65, v69, 16, 1
	v_bfe_u32 v70, v68, 16, 1
	v_bfe_u32 v76, v87, 16, 1
	v_bfe_u32 v8, v89, 16, 1
	v_add3_u32 v70, v68, v70, s89
	v_add3_u32 v65, v69, v65, s89
	v_bfe_u32 v68, v66, 16, 1
	v_bfe_u32 v69, v67, 16, 1
	v_bfe_u32 v74, v86, 16, 1
	v_add3_u32 v76, v87, v76, s89
	v_bfe_u32 v10, v88, 16, 1
	v_add3_u32 v8, v89, v8, s89
	v_add3_u32 v74, v86, v74, s89
	v_add3_u32 v67, v67, v69, s89
	v_add3_u32 v66, v66, v68, s89
	v_lshrrev_b32_e32 v69, 16, v76
	s_lshl_b32 s26, s5, 1
	v_add3_u32 v10, v88, v10, s89
	v_lshrrev_b32_e32 v66, 16, v66
	v_lshrrev_b32_e32 v68, 16, v74
	v_and_or_b32 v69, v8, s90, v69
	v_or_b32_e32 v8, s4, v50
	v_lshl_add_u64 v[72:73], v[28:29], 0, s[26:27]
	v_lshrrev_b32_e32 v67, 16, v67
	v_and_or_b32 v68, v10, s90, v68
	v_and_or_b32 v66, v70, s90, v66
	v_lshlrev_b32_e32 v10, 11, v8
	v_mov_b32_e32 v70, v9
	v_mov_b32_e32 v84, v83
	v_and_or_b32 v67, v65, s90, v67
	v_lshl_add_u64 v[86:87], v[72:73], 0, v[10:11]
	v_pk_mul_f32 v[8:9], v[2:3], v[70:71]
	v_mov_b32_e32 v76, v75
	v_pk_mul_f32 v[70:71], v[4:5], v[84:85]
	global_store_dwordx4 v[86:87], v[66:69], off sc1
	v_mov_b32_e32 v80, v79
	v_bfe_u32 v65, v70, 16, 1
	v_pk_mul_f32 v[66:67], v[46:47], v[76:77]
	v_pk_mul_f32 v[68:69], v[6:7], v[80:81]
	v_bfe_u32 v75, v66, 16, 1
	v_add3_u32 v65, v70, v65, s89
	v_bfe_u32 v70, v8, 16, 1
	v_bfe_u32 v10, v71, 16, 1
	v_bfe_u32 v74, v67, 16, 1
	v_add3_u32 v66, v66, v75, s89
	v_bfe_u32 v75, v69, 16, 1
	v_add3_u32 v8, v8, v70, s89
	v_add3_u32 v67, v67, v74, s89
	v_add3_u32 v10, v71, v10, s89
	v_bfe_u32 v71, v9, 16, 1
	v_bfe_u32 v74, v68, 16, 1
	v_add3_u32 v69, v69, v75, s89
	v_lshrrev_b32_e32 v8, 16, v8
	v_add3_u32 v68, v68, v74, s89
	v_add3_u32 v9, v9, v71, s89
	v_lshrrev_b32_e32 v69, 16, v69
	v_and_or_b32 v66, v66, s90, v8
	v_or_b32_e32 v8, s4, v52
	v_lshrrev_b32_e32 v9, 16, v9
	v_lshrrev_b32_e32 v68, 16, v68
	v_and_or_b32 v69, v10, s90, v69
	v_lshlrev_b32_e32 v10, 11, v8
	v_and_or_b32 v68, v65, s90, v68
	v_and_or_b32 v67, v67, s90, v9
	v_lshl_add_u64 v[8:9], v[72:73], 0, v[10:11]
	ds_read2_b32 v[70:71], v51 offset0:16 offset1:24
	ds_read2_b32 v[74:75], v51 offset0:82 offset1:90
	global_store_dwordx4 v[8:9], v[66:69], off sc1
	ds_read2_b32 v[8:9], v51 offset0:49 offset1:57
	ds_read2_b32 v[76:77], v51 offset0:115 offset1:123
	ds_read2_b32 v[78:79], v51 offset0:148 offset1:156
	ds_read2_b32 v[80:81], v51 offset0:214 offset1:222
	ds_read2_b32 v[82:83], v51 offset0:181 offset1:189
	ds_read2_b32 v[84:85], v51 offset0:247 offset1:255
	s_waitcnt lgkmcnt(7)
	v_mov_b32_e32 v66, v70
	s_waitcnt lgkmcnt(5)
	v_mov_b32_e32 v68, v8
	s_waitcnt lgkmcnt(4)
	v_mov_b32_e32 v69, v76
	s_waitcnt lgkmcnt(3)
	v_mov_b32_e32 v86, v78
	s_waitcnt lgkmcnt(2)
	v_mov_b32_e32 v87, v80
	v_mov_b32_e32 v67, v74
	v_pk_mul_f32 v[68:69], v[46:47], v[68:69]
	v_pk_mul_f32 v[86:87], v[6:7], v[86:87]
	s_waitcnt lgkmcnt(1)
	v_mov_b32_e32 v88, v82
	s_waitcnt lgkmcnt(0)
	v_mov_b32_e32 v89, v84
	v_pk_mul_f32 v[66:67], v[2:3], v[66:67]
	v_pk_mul_f32 v[88:89], v[4:5], v[88:89]
	v_bfe_u32 v65, v69, 16, 1
	v_bfe_u32 v76, v87, 16, 1
	v_bfe_u32 v8, v89, 16, 1
	v_bfe_u32 v70, v68, 16, 1
	v_add3_u32 v65, v69, v65, s89
	v_bfe_u32 v69, v67, 16, 1
	v_bfe_u32 v74, v86, 16, 1
	v_add3_u32 v76, v87, v76, s89
	v_bfe_u32 v10, v88, 16, 1
	v_add3_u32 v70, v68, v70, s89
	v_add3_u32 v8, v89, v8, s89
	v_bfe_u32 v68, v66, 16, 1
	v_add3_u32 v74, v86, v74, s89
	v_add3_u32 v67, v67, v69, s89
	v_lshrrev_b32_e32 v69, 16, v76
	v_add3_u32 v10, v88, v10, s89
	v_add3_u32 v66, v66, v68, s89
	v_lshrrev_b32_e32 v68, 16, v74
	v_and_or_b32 v69, v8, s90, v69
	v_or_b32_e32 v8, s4, v53
	v_mov_b32_e32 v76, v9
	v_and_or_b32 v68, v10, s90, v68
	v_lshlrev_b32_e32 v10, 11, v8
	v_pk_mul_f32 v[8:9], v[46:47], v[76:77]
	v_mov_b32_e32 v80, v79
	v_pk_mul_f32 v[6:7], v[6:7], v[80:81]
	v_mov_b32_e32 v84, v83
	v_bfe_u32 v47, v9, 16, 1
	v_lshrrev_b32_e32 v67, 16, v67
	v_mov_b32_e32 v74, v71
	v_pk_mul_f32 v[4:5], v[4:5], v[84:85]
	v_add3_u32 v9, v9, v47, s89
	v_bfe_u32 v47, v6, 16, 1
	v_and_or_b32 v67, v65, s90, v67
	v_lshl_add_u64 v[86:87], v[72:73], 0, v[10:11]
	v_pk_mul_f32 v[2:3], v[2:3], v[74:75]
	v_bfe_u32 v10, v5, 16, 1
	v_bfe_u32 v46, v4, 16, 1
	v_bfe_u32 v65, v8, 16, 1
	v_add3_u32 v6, v6, v47, s89
	v_add3_u32 v8, v8, v65, s89
	v_add3_u32 v4, v4, v46, s89
	v_add3_u32 v5, v5, v10, s89
	v_bfe_u32 v10, v2, 16, 1
	v_bfe_u32 v46, v3, 16, 1
	v_bfe_u32 v65, v7, 16, 1
	v_lshrrev_b32_e32 v6, 16, v6
	v_add3_u32 v7, v7, v65, s89
	v_add3_u32 v3, v3, v46, s89
	v_add3_u32 v2, v2, v10, s89
	v_and_or_b32 v4, v4, s90, v6
	v_or_b32_e32 v6, s4, v54
	v_lshrrev_b32_e32 v66, 16, v66
	v_lshrrev_b32_e32 v2, 16, v2
	v_lshrrev_b32_e32 v3, 16, v3
	v_lshrrev_b32_e32 v7, 16, v7
	v_lshlrev_b32_e32 v10, 11, v6
	v_and_or_b32 v66, v70, s90, v66
	v_and_or_b32 v5, v5, s90, v7
	v_and_or_b32 v3, v9, s90, v3
	v_and_or_b32 v2, v8, s90, v2
	v_lshl_add_u64 v[6:7], v[72:73], 0, v[10:11]
	global_store_dwordx4 v[86:87], v[66:69], off sc1
	global_store_dwordx4 v[6:7], v[2:5], off sc1
	s_waitcnt lgkmcnt(0)

.LBB0_90:
	s_andn2_b64 vcc, exec, s[28:29]
	s_cbranch_vccnz .LBB0_92
	v_or_b32_e32 v2, s5, v48
	v_mul_u32_u24_e32 v2, 0x180, v2
	v_lshlrev_b32_e32 v10, 2, v2
	v_max_i32_e32 v4, 0x100, v64
	v_lshl_add_u64 v[2:3], s[40:41], 0, v[10:11]
	v_lshlrev_b32_e32 v10, 2, v4
	v_lshl_add_u64 v[2:3], v[2:3], 0, v[10:11]
	v_add_co_u32_e32 v4, vcc, 0x1000, v2
	s_mov_b32 s26, 0x14000
	s_nop 0
	v_addc_co_u32_e32 v5, vcc, 0, v3, vcc
	v_add_co_u32_e32 v6, vcc, s31, v2
	s_nop 1
	v_addc_co_u32_e32 v7, vcc, 0, v3, vcc
	v_add_co_u32_e32 v8, vcc, 0x3000, v2
	s_nop 1
	v_addc_co_u32_e32 v9, vcc, 0, v3, vcc
	v_add_co_u32_e32 v46, vcc, s34, v2
	s_nop 1
	v_addc_co_u32_e32 v47, vcc, 0, v3, vcc
	v_add_co_u32_e32 v66, vcc, 0x5000, v2
	s_nop 1
	v_addc_co_u32_e32 v67, vcc, 0, v3, vcc
	global_load_dword v10, v[2:3], off offset:-1024
	global_load_dword v65, v[2:3], off offset:2048
	global_load_dword v72, v[4:5], off offset:1024
	global_load_dword v73, v[6:7], off
	global_load_dword v74, v[6:7], off offset:3072
	global_load_dword v75, v[8:9], off offset:2048
	global_load_dword v76, v[46:47], off offset:1024
	global_load_dword v77, v[66:67], off
	v_add_co_u32_e32 v4, vcc, s35, v2
	s_nop 1
	v_addc_co_u32_e32 v5, vcc, 0, v3, vcc
	v_add_co_u32_e32 v6, vcc, 0x7000, v2
	s_nop 1
	v_addc_co_u32_e32 v7, vcc, 0, v3, vcc
	v_add_co_u32_e32 v8, vcc, s36, v2
	s_nop 1
	v_addc_co_u32_e32 v9, vcc, 0, v3, vcc
	v_add_co_u32_e32 v46, vcc, s92, v2
	s_nop 1
	v_addc_co_u32_e32 v47, vcc, 0, v3, vcc
	v_add_co_u32_e32 v68, vcc, s37, v2
	s_nop 1
	v_addc_co_u32_e32 v69, vcc, 0, v3, vcc
	v_add_co_u32_e32 v70, vcc, s94, v2
	s_nop 1
	v_addc_co_u32_e32 v71, vcc, 0, v3, vcc
	global_load_dword v78, v[66:67], off offset:3072
	global_load_dword v79, v[4:5], off offset:2048
	global_load_dword v80, v[6:7], off offset:1024
	global_load_dword v81, v[8:9], off
	global_load_dword v82, v[8:9], off offset:3072
	global_load_dword v83, v[46:47], off offset:2048
	global_load_dword v84, v[68:69], off offset:1024
	global_load_dword v85, v[70:71], off
	v_add_co_u32_e32 v4, vcc, s42, v2
	s_nop 1
	v_addc_co_u32_e32 v5, vcc, 0, v3, vcc
	v_add_co_u32_e32 v6, vcc, s95, v2
	s_nop 1
	v_addc_co_u32_e32 v7, vcc, 0, v3, vcc
	v_add_co_u32_e32 v8, vcc, s43, v2
	s_nop 1
	v_addc_co_u32_e32 v9, vcc, 0, v3, vcc
	v_add_co_u32_e32 v46, vcc, s93, v2
	s_nop 1
	v_addc_co_u32_e32 v47, vcc, 0, v3, vcc
	v_add_co_u32_e32 v66, vcc, s52, v2
	s_nop 1
	v_addc_co_u32_e32 v67, vcc, 0, v3, vcc
	v_add_co_u32_e32 v68, vcc, s96, v2
	s_nop 1
	v_addc_co_u32_e32 v69, vcc, 0, v3, vcc
	global_load_dword v70, v[70:71], off offset:3072
	s_nop 0
	global_load_dword v71, v[4:5], off offset:2048
	global_load_dword v86, v[6:7], off offset:1024
	global_load_dword v87, v[8:9], off
	global_load_dword v88, v[8:9], off offset:3072
	global_load_dword v89, v[46:47], off offset:2048
	global_load_dword v90, v[66:67], off offset:1024
	global_load_dword v91, v[68:69], off
	v_add_co_u32_e32 v4, vcc, s53, v2
	s_nop 1
	v_addc_co_u32_e32 v5, vcc, 0, v3, vcc
	v_add_co_u32_e32 v6, vcc, s97, v2
	s_nop 1
	v_addc_co_u32_e32 v7, vcc, 0, v3, vcc
	v_add_co_u32_e32 v8, vcc, s26, v2
	s_mov_b32 s26, 0x15000
	s_nop 0
	v_addc_co_u32_e32 v9, vcc, 0, v3, vcc
	v_add_co_u32_e32 v46, vcc, s26, v2
	s_mov_b32 s26, 0x16000
	s_nop 0
	v_addc_co_u32_e32 v47, vcc, 0, v3, vcc
	v_add_co_u32_e32 v66, vcc, s26, v2
	s_mov_b32 s26, 0x17000
	s_nop 0
	v_addc_co_u32_e32 v67, vcc, 0, v3, vcc
	v_add_co_u32_e32 v2, vcc, s26, v2
	s_lshl_b32 s26, s5, 2
	s_nop 0
	v_addc_co_u32_e32 v3, vcc, 0, v3, vcc
	global_load_dword v68, v[68:69], off offset:3072
	s_nop 0
	global_load_dword v69, v[4:5], off offset:2048
	global_load_dword v92, v[6:7], off offset:1024
	global_load_dword v93, v[8:9], off
	global_load_dword v94, v[8:9], off offset:3072
	s_nop 0
	global_load_dword v46, v[46:47], off offset:2048
	s_nop 0
	global_load_dword v47, v[66:67], off offset:1024
	s_nop 0
	global_load_dword v66, v[2:3], off
	v_lshl_add_u64 v[6:7], v[34:35], 0, s[26:27]
	global_load_dwordx4 v[2:5], v[6:7], off
	s_nop 0
	global_load_dwordx4 v[6:9], v[6:7], off offset:16
	s_lshl_b32 s26, s5, 1
	s_waitcnt vmcnt(32)
	ds_write2_b32 v49, v10, v65 offset1:66
	s_waitcnt vmcnt(30)
	ds_write2_b32 v49, v72, v73 offset0:132 offset1:198
	s_waitcnt vmcnt(28)
	ds_write2_b32 v57, v74, v75 offset0:8 offset1:74
	s_waitcnt vmcnt(26)
	ds_write2_b32 v57, v76, v77 offset0:140 offset1:206
	s_waitcnt vmcnt(24)
	ds_write2_b32 v58, v78, v79 offset0:16 offset1:82
	s_waitcnt vmcnt(22)
	ds_write2_b32 v58, v80, v81 offset0:148 offset1:214
	s_waitcnt vmcnt(20)
	ds_write2_b32 v59, v82, v83 offset0:24 offset1:90
	s_waitcnt vmcnt(18)
	ds_write2_b32 v59, v84, v85 offset0:156 offset1:222
	s_waitcnt vmcnt(16)
	ds_write2_b32 v60, v70, v71 offset0:32 offset1:98
	s_waitcnt vmcnt(14)
	ds_write2_b32 v60, v86, v87 offset0:164 offset1:230
	s_waitcnt vmcnt(12)
	ds_write2_b32 v61, v88, v89 offset0:40 offset1:106
	s_waitcnt vmcnt(10)
	ds_write2_b32 v61, v90, v91 offset0:172 offset1:238
	s_waitcnt vmcnt(8)
	ds_write2_b32 v62, v68, v69 offset0:48 offset1:114
	s_waitcnt vmcnt(6)
	ds_write2_b32 v62, v92, v93 offset0:180 offset1:246
	s_waitcnt vmcnt(4)
	ds_write2_b32 v63, v94, v46 offset0:56 offset1:122
	s_waitcnt vmcnt(2)
	ds_write2_b32 v63, v47, v66 offset0:188 offset1:254
	s_waitcnt lgkmcnt(0)
	ds_read2_b32 v[70:71], v51 offset0:33 offset1:41
	ds_read2_b32 v[72:73], v51 offset1:8
	ds_read2_b32 v[74:75], v51 offset0:66 offset1:74
	ds_read2_b32 v[76:77], v51 offset0:99 offset1:107
	ds_read2_b32 v[80:81], v51 offset0:132 offset1:140
	ds_read2_b32 v[82:83], v51 offset0:165 offset1:173
	ds_read2_b32 v[84:85], v51 offset0:198 offset1:206
	ds_read2_b32 v[86:87], v51 offset0:231 offset1:239
	s_waitcnt vmcnt(1)
	v_mov_b32_e32 v78, v2
	v_mov_b32_e32 v79, v4
	v_mov_b32_e32 v4, v3
	s_waitcnt lgkmcnt(7)
	v_mov_b32_e32 v2, v70
	s_waitcnt lgkmcnt(4)
	v_mov_b32_e32 v3, v76
	s_waitcnt vmcnt(0)
	v_mov_b32_e32 v88, v6
	v_mov_b32_e32 v89, v8
	v_mov_b32_e32 v8, v7
	s_waitcnt lgkmcnt(2)
	v_mov_b32_e32 v6, v82
	s_waitcnt lgkmcnt(0)
	v_mov_b32_e32 v7, v86
	v_mov_b32_e32 v66, v72
	v_mov_b32_e32 v67, v74
	v_pk_mul_f32 v[2:3], v[4:5], v[2:3]
	v_mov_b32_e32 v68, v80
	v_mov_b32_e32 v69, v84
	v_pk_mul_f32 v[6:7], v[8:9], v[6:7]
	v_pk_mul_f32 v[66:67], v[78:79], v[66:67]
	v_pk_mul_f32 v[68:69], v[88:89], v[68:69]
	v_bfe_u32 v10, v7, 16, 1
	v_bfe_u32 v70, v3, 16, 1
	v_add3_u32 v3, v3, v70, s89
	v_add3_u32 v7, v7, v10, s89
	v_bfe_u32 v10, v66, 16, 1
	v_bfe_u32 v70, v68, 16, 1
	v_bfe_u32 v65, v6, 16, 1
	v_bfe_u32 v72, v2, 16, 1
	v_add3_u32 v68, v68, v70, s89
	v_add3_u32 v10, v66, v10, s89
	v_add3_u32 v2, v2, v72, s89
	v_add3_u32 v6, v6, v65, s89
	v_bfe_u32 v65, v67, 16, 1
	v_bfe_u32 v72, v69, 16, 1
	v_lshrrev_b32_e32 v10, 16, v10
	v_lshrrev_b32_e32 v66, 16, v68
	v_add3_u32 v69, v69, v72, s89
	v_add3_u32 v65, v67, v65, s89
	v_and_or_b32 v68, v6, s90, v66
	v_and_or_b32 v66, v2, s90, v10
	v_or_b32_e32 v2, s4, v50
	v_lshl_add_u64 v[46:47], v[28:29], 0, s[26:27]
	v_lshrrev_b32_e32 v65, 16, v65
	v_lshrrev_b32_e32 v67, 16, v69
	v_lshlrev_b32_e32 v10, 11, v2
	v_and_or_b32 v69, v7, s90, v67
	v_and_or_b32 v67, v3, s90, v65
	v_lshl_add_u64 v[2:3], v[46:47], 0, v[10:11]
	v_mov_b32_e32 v76, v71
	v_mov_b32_e32 v86, v83
	global_store_dwordx4 v[2:3], v[66:69], off sc1
	v_mov_b32_e32 v74, v73
	v_pk_mul_f32 v[6:7], v[4:5], v[76:77]
	v_mov_b32_e32 v84, v81
	v_pk_mul_f32 v[68:69], v[8:9], v[86:87]
	v_pk_mul_f32 v[2:3], v[78:79], v[74:75]
	v_pk_mul_f32 v[66:67], v[88:89], v[84:85]
	v_bfe_u32 v65, v68, 16, 1
	v_bfe_u32 v70, v7, 16, 1
	v_bfe_u32 v71, v6, 16, 1
	v_add3_u32 v7, v7, v70, s89
	v_add3_u32 v65, v68, v65, s89
	v_bfe_u32 v68, v2, 16, 1
	v_bfe_u32 v70, v66, 16, 1
	v_bfe_u32 v10, v69, 16, 1
	v_add3_u32 v6, v6, v71, s89
	v_bfe_u32 v71, v67, 16, 1
	v_add3_u32 v66, v66, v70, s89
	v_add3_u32 v2, v2, v68, s89
	v_add3_u32 v10, v69, v10, s89
	v_bfe_u32 v69, v3, 16, 1
	v_add3_u32 v67, v67, v71, s89
	v_lshrrev_b32_e32 v2, 16, v2
	v_lshrrev_b32_e32 v66, 16, v66
	v_add3_u32 v3, v3, v69, s89
	v_lshrrev_b32_e32 v67, 16, v67
	v_and_or_b32 v68, v65, s90, v66
	v_and_or_b32 v66, v6, s90, v2
	v_or_b32_e32 v2, s4, v52
	v_lshrrev_b32_e32 v3, 16, v3
	v_and_or_b32 v69, v10, s90, v67
	v_lshlrev_b32_e32 v10, 11, v2
	v_and_or_b32 v67, v7, s90, v3
	v_lshl_add_u64 v[2:3], v[46:47], 0, v[10:11]
	ds_read2_b32 v[6:7], v51 offset0:16 offset1:24
	ds_read2_b32 v[70:71], v51 offset0:82 offset1:90
	global_store_dwordx4 v[2:3], v[66:69], off sc1
	ds_read2_b32 v[2:3], v51 offset0:49 offset1:57
	ds_read2_b32 v[72:73], v51 offset0:115 offset1:123
	ds_read2_b32 v[74:75], v51 offset0:148 offset1:156
	ds_read2_b32 v[76:77], v51 offset0:214 offset1:222
	ds_read2_b32 v[80:81], v51 offset0:181 offset1:189
	ds_read2_b32 v[82:83], v51 offset0:247 offset1:255
	s_waitcnt lgkmcnt(7)
	v_mov_b32_e32 v66, v6
	s_waitcnt lgkmcnt(5)
	v_mov_b32_e32 v68, v2
	s_waitcnt lgkmcnt(4)
	v_mov_b32_e32 v69, v72
	s_waitcnt lgkmcnt(3)
	v_mov_b32_e32 v84, v74
	s_waitcnt lgkmcnt(2)
	v_mov_b32_e32 v85, v76
	v_mov_b32_e32 v67, v70
	v_pk_mul_f32 v[68:69], v[4:5], v[68:69]
	v_pk_mul_f32 v[84:85], v[88:89], v[84:85]
	s_waitcnt lgkmcnt(1)
	v_mov_b32_e32 v86, v80
	s_waitcnt lgkmcnt(0)
	v_mov_b32_e32 v87, v82
	v_pk_mul_f32 v[66:67], v[78:79], v[66:67]
	v_pk_mul_f32 v[86:87], v[8:9], v[86:87]
	v_bfe_u32 v10, v69, 16, 1
	v_bfe_u32 v72, v85, 16, 1
	v_bfe_u32 v2, v87, 16, 1
	v_add3_u32 v10, v69, v10, s89
	v_bfe_u32 v69, v67, 16, 1
	v_add3_u32 v72, v85, v72, s89
	v_bfe_u32 v65, v68, 16, 1
	v_add3_u32 v2, v87, v2, s89
	v_bfe_u32 v70, v84, 16, 1
	v_add3_u32 v67, v67, v69, s89
	v_lshrrev_b32_e32 v69, 16, v72
	v_bfe_u32 v6, v86, 16, 1
	v_add3_u32 v65, v68, v65, s89
	v_bfe_u32 v68, v66, 16, 1
	v_add3_u32 v70, v84, v70, s89
	v_lshrrev_b32_e32 v67, 16, v67
	v_and_or_b32 v69, v2, s90, v69
	v_or_b32_e32 v2, s4, v53
	v_mov_b32_e32 v82, v81
	v_add3_u32 v6, v86, v6, s89
	v_add3_u32 v66, v66, v68, s89
	v_lshrrev_b32_e32 v68, 16, v70
	v_and_or_b32 v67, v10, s90, v67
	v_lshlrev_b32_e32 v10, 11, v2
	v_mov_b32_e32 v70, v7
	v_pk_mul_f32 v[8:9], v[8:9], v[82:83]
	v_lshrrev_b32_e32 v66, 16, v66
	v_and_or_b32 v68, v6, s90, v68
	v_lshl_add_u64 v[84:85], v[46:47], 0, v[10:11]
	v_pk_mul_f32 v[6:7], v[78:79], v[70:71]
	v_mov_b32_e32 v72, v3
	v_bfe_u32 v10, v9, 16, 1
	v_and_or_b32 v66, v65, s90, v66
	v_pk_mul_f32 v[2:3], v[4:5], v[72:73]
	v_mov_b32_e32 v76, v75
	v_add3_u32 v9, v9, v10, s89
	v_bfe_u32 v10, v6, 16, 1
	global_store_dwordx4 v[84:85], v[66:69], off sc1
	v_pk_mul_f32 v[4:5], v[88:89], v[76:77]
	v_bfe_u32 v65, v8, 16, 1
	v_bfe_u32 v66, v3, 16, 1
	v_bfe_u32 v67, v2, 16, 1
	v_add3_u32 v6, v6, v10, s89
	v_add3_u32 v2, v2, v67, s89
	v_add3_u32 v3, v3, v66, s89
	v_add3_u32 v8, v8, v65, s89
	v_bfe_u32 v65, v7, 16, 1
	v_bfe_u32 v66, v4, 16, 1
	v_bfe_u32 v67, v5, 16, 1
	v_lshrrev_b32_e32 v6, 16, v6
	v_add3_u32 v5, v5, v67, s89
	v_add3_u32 v4, v4, v66, s89
	v_add3_u32 v7, v7, v65, s89
	v_and_or_b32 v2, v2, s90, v6
	v_or_b32_e32 v6, s4, v54
	v_lshrrev_b32_e32 v7, 16, v7
	v_lshrrev_b32_e32 v4, 16, v4
	v_lshrrev_b32_e32 v5, 16, v5
	v_lshlrev_b32_e32 v10, 11, v6
	v_and_or_b32 v5, v9, s90, v5
	v_and_or_b32 v4, v8, s90, v4
	v_and_or_b32 v3, v3, s90, v7
	v_lshl_add_u64 v[6:7], v[46:47], 0, v[10:11]
	global_store_dwordx4 v[6:7], v[2:5], off sc1
	s_waitcnt lgkmcnt(0)

.LBB0_97:
	s_waitcnt lgkmcnt(0)
	ds_read2_b32 v[8:9], v51 offset1:8
	ds_read2_b32 v[68:69], v51 offset0:66 offset1:74
	ds_read2_b32 v[72:73], v51 offset0:33 offset1:41
	ds_read2_b32 v[74:75], v51 offset0:99 offset1:107
	ds_read2_b32 v[76:77], v51 offset0:132 offset1:140
	ds_read2_b32 v[78:79], v51 offset0:198 offset1:206
	ds_read2_b32 v[80:81], v51 offset0:165 offset1:173
	ds_read2_b32 v[82:83], v51 offset0:231 offset1:239
	s_waitcnt lgkmcnt(7)
	v_mov_b32_e32 v64, v8
	s_waitcnt lgkmcnt(5)
	v_mov_b32_e32 v66, v72
	s_waitcnt lgkmcnt(4)
	v_mov_b32_e32 v67, v74
	s_waitcnt lgkmcnt(3)
	v_mov_b32_e32 v84, v76
	s_waitcnt lgkmcnt(2)
	v_mov_b32_e32 v85, v78
	v_mov_b32_e32 v65, v68
	v_pk_mul_f32 v[66:67], v[46:47], v[66:67]
	v_pk_mul_f32 v[84:85], v[6:7], v[84:85]
	s_waitcnt lgkmcnt(1)
	v_mov_b32_e32 v86, v80
	s_waitcnt lgkmcnt(0)
	v_mov_b32_e32 v87, v82
	v_pk_mul_f32 v[64:65], v[2:3], v[64:65]
	v_pk_mul_f32 v[86:87], v[4:5], v[86:87]
	v_bfe_u32 v68, v67, 16, 1
	v_bfe_u32 v76, v85, 16, 1
	v_bfe_u32 v8, v87, 16, 1
	v_bfe_u32 v72, v66, 16, 1
	v_add3_u32 v68, v67, v68, s89
	v_bfe_u32 v67, v65, 16, 1
	v_bfe_u32 v74, v84, 16, 1
	v_add3_u32 v76, v85, v76, s89
	v_bfe_u32 v10, v86, 16, 1
	v_add3_u32 v72, v66, v72, s89
	v_add3_u32 v8, v87, v8, s89
	v_bfe_u32 v66, v64, 16, 1
	v_add3_u32 v74, v84, v74, s89
	v_add3_u32 v65, v65, v67, s89
	v_lshrrev_b32_e32 v67, 16, v76
	s_lshl_b32 s26, s5, 1
	v_add3_u32 v10, v86, v10, s89
	v_add3_u32 v64, v64, v66, s89
	v_lshrrev_b32_e32 v65, 16, v65
	v_lshrrev_b32_e32 v66, 16, v74
	v_and_or_b32 v67, v8, s90, v67
	v_or_b32_e32 v8, s4, v50
	v_lshl_add_u64 v[70:71], v[28:29], 0, s[26:27]
	v_lshrrev_b32_e32 v64, 16, v64
	v_and_or_b32 v66, v10, s90, v66
	v_and_or_b32 v65, v68, s90, v65
	v_lshlrev_b32_e32 v10, 11, v8
	v_mov_b32_e32 v68, v9
	v_mov_b32_e32 v82, v81
	v_and_or_b32 v64, v72, s90, v64
	v_lshl_add_u64 v[84:85], v[70:71], 0, v[10:11]
	v_pk_mul_f32 v[8:9], v[2:3], v[68:69]
	v_mov_b32_e32 v74, v73
	v_pk_mul_f32 v[68:69], v[4:5], v[82:83]
	global_store_dwordx4 v[84:85], v[64:67], off sc1
	v_mov_b32_e32 v78, v77
	v_bfe_u32 v10, v69, 16, 1
	v_pk_mul_f32 v[64:65], v[46:47], v[74:75]
	v_pk_mul_f32 v[66:67], v[6:7], v[78:79]
	v_bfe_u32 v74, v64, 16, 1
	v_add3_u32 v10, v69, v10, s89
	v_bfe_u32 v69, v8, 16, 1
	v_bfe_u32 v72, v68, 16, 1
	v_bfe_u32 v73, v65, 16, 1
	v_add3_u32 v64, v64, v74, s89
	v_bfe_u32 v74, v67, 16, 1
	v_add3_u32 v8, v8, v69, s89
	v_add3_u32 v65, v65, v73, s89
	v_add3_u32 v68, v68, v72, s89
	v_bfe_u32 v72, v9, 16, 1
	v_bfe_u32 v73, v66, 16, 1
	v_add3_u32 v67, v67, v74, s89
	v_lshrrev_b32_e32 v8, 16, v8
	v_add3_u32 v66, v66, v73, s89
	v_add3_u32 v9, v9, v72, s89
	v_lshrrev_b32_e32 v67, 16, v67
	v_and_or_b32 v64, v64, s90, v8
	v_or_b32_e32 v8, s4, v52
	v_lshrrev_b32_e32 v9, 16, v9
	v_lshrrev_b32_e32 v66, 16, v66
	v_and_or_b32 v67, v10, s90, v67
	v_lshlrev_b32_e32 v10, 11, v8
	v_and_or_b32 v66, v68, s90, v66
	v_and_or_b32 v65, v65, s90, v9
	v_lshl_add_u64 v[8:9], v[70:71], 0, v[10:11]
	ds_read2_b32 v[68:69], v51 offset0:16 offset1:24
	ds_read2_b32 v[72:73], v51 offset0:82 offset1:90
	global_store_dwordx4 v[8:9], v[64:67], off sc1
	ds_read2_b32 v[8:9], v51 offset0:49 offset1:57
	ds_read2_b32 v[74:75], v51 offset0:115 offset1:123
	ds_read2_b32 v[76:77], v51 offset0:148 offset1:156
	ds_read2_b32 v[78:79], v51 offset0:214 offset1:222
	ds_read2_b32 v[80:81], v51 offset0:181 offset1:189
	ds_read2_b32 v[82:83], v51 offset0:247 offset1:255
	s_waitcnt lgkmcnt(7)
	v_mov_b32_e32 v64, v68
	s_waitcnt lgkmcnt(5)
	v_mov_b32_e32 v66, v8
	s_waitcnt lgkmcnt(4)
	v_mov_b32_e32 v67, v74
	s_waitcnt lgkmcnt(3)
	v_mov_b32_e32 v84, v76
	s_waitcnt lgkmcnt(2)
	v_mov_b32_e32 v85, v78
	v_mov_b32_e32 v65, v72
	v_pk_mul_f32 v[66:67], v[46:47], v[66:67]
	v_pk_mul_f32 v[84:85], v[6:7], v[84:85]
	s_waitcnt lgkmcnt(1)
	v_mov_b32_e32 v86, v80
	s_waitcnt lgkmcnt(0)
	v_mov_b32_e32 v87, v82
	v_pk_mul_f32 v[64:65], v[2:3], v[64:65]
	v_pk_mul_f32 v[86:87], v[4:5], v[86:87]
	v_bfe_u32 v68, v67, 16, 1
	v_bfe_u32 v76, v85, 16, 1
	v_bfe_u32 v8, v87, 16, 1
	v_bfe_u32 v72, v66, 16, 1
	v_add3_u32 v68, v67, v68, s89
	v_bfe_u32 v67, v65, 16, 1
	v_bfe_u32 v74, v84, 16, 1
	v_add3_u32 v76, v85, v76, s89
	v_bfe_u32 v10, v86, 16, 1
	v_add3_u32 v72, v66, v72, s89
	v_add3_u32 v8, v87, v8, s89
	v_bfe_u32 v66, v64, 16, 1
	v_add3_u32 v74, v84, v74, s89
	v_add3_u32 v65, v65, v67, s89
	v_lshrrev_b32_e32 v67, 16, v76
	v_add3_u32 v10, v86, v10, s89
	v_add3_u32 v64, v64, v66, s89
	v_lshrrev_b32_e32 v66, 16, v74
	v_and_or_b32 v67, v8, s90, v67
	v_or_b32_e32 v8, s4, v53
	v_mov_b32_e32 v74, v9
	v_and_or_b32 v66, v10, s90, v66
	v_lshlrev_b32_e32 v10, 11, v8
	v_pk_mul_f32 v[8:9], v[46:47], v[74:75]
	v_mov_b32_e32 v78, v77
	v_lshrrev_b32_e32 v64, 16, v64
	v_lshrrev_b32_e32 v65, 16, v65
	v_pk_mul_f32 v[6:7], v[6:7], v[78:79]
	v_mov_b32_e32 v82, v81
	v_bfe_u32 v47, v9, 16, 1
	v_and_or_b32 v65, v68, s90, v65
	v_and_or_b32 v64, v72, s90, v64
	v_lshl_add_u64 v[84:85], v[70:71], 0, v[10:11]
	v_mov_b32_e32 v72, v69
	v_pk_mul_f32 v[4:5], v[4:5], v[82:83]
	v_add3_u32 v9, v9, v47, s89
	v_bfe_u32 v47, v6, 16, 1
	global_store_dwordx4 v[84:85], v[64:67], off sc1
	v_pk_mul_f32 v[2:3], v[2:3], v[72:73]
	v_bfe_u32 v10, v5, 16, 1
	v_bfe_u32 v46, v4, 16, 1
	v_bfe_u32 v64, v8, 16, 1
	v_add3_u32 v6, v6, v47, s89
	v_add3_u32 v8, v8, v64, s89
	v_add3_u32 v4, v4, v46, s89
	v_add3_u32 v5, v5, v10, s89
	v_bfe_u32 v10, v2, 16, 1
	v_bfe_u32 v46, v3, 16, 1
	v_bfe_u32 v64, v7, 16, 1
	v_lshrrev_b32_e32 v6, 16, v6
	v_add3_u32 v7, v7, v64, s89
	v_add3_u32 v3, v3, v46, s89
	v_add3_u32 v2, v2, v10, s89
	v_and_or_b32 v4, v4, s90, v6
	v_or_b32_e32 v6, s4, v54
	v_lshrrev_b32_e32 v2, 16, v2
	v_lshrrev_b32_e32 v3, 16, v3
	v_lshrrev_b32_e32 v7, 16, v7
	v_lshlrev_b32_e32 v10, 11, v6
	v_and_or_b32 v5, v5, s90, v7
	v_and_or_b32 v3, v9, s90, v3
	v_and_or_b32 v2, v8, s90, v2
	v_lshl_add_u64 v[6:7], v[70:71], 0, v[10:11]
	global_store_dwordx4 v[6:7], v[2:5], off sc1
	s_waitcnt lgkmcnt(0)

.LBB0_99:
	s_andn2_b64 vcc, exec, s[28:29]
	s_cbranch_vccnz .LBB0_101
	s_add_i32 s4, s21, 0x3f40
	s_and_b32 s5, s4, 0x7fffffc0
	s_and_b32 s4, s3, 0x3e0
	v_or_b32_e32 v10, s5, v48
	v_or_b32_e32 v4, s4, v1
	v_lshlrev_b64 v[2:3], 12, v[10:11]
	v_lshl_add_u64 v[2:3], s[62:63], 0, v[2:3]
	v_lshlrev_b32_e32 v10, 2, v4
	v_lshl_add_u64 v[2:3], v[2:3], 0, v[10:11]
	v_add_co_u32_e32 v4, vcc, 0x2000, v2
	s_lshl_b32 s26, s5, 1
	s_nop 0
	v_addc_co_u32_e32 v5, vcc, 0, v3, vcc
	v_add_co_u32_e32 v6, vcc, 0x4000, v2
	s_nop 1
	v_addc_co_u32_e32 v7, vcc, 0, v3, vcc
	v_add_co_u32_e32 v8, vcc, 0x6000, v2
	s_nop 1
	v_addc_co_u32_e32 v9, vcc, 0, v3, vcc
	v_add_co_u32_e32 v46, vcc, 0x8000, v2
	s_nop 1
	v_addc_co_u32_e32 v47, vcc, 0, v3, vcc
	v_add_co_u32_e32 v64, vcc, 0xa000, v2
	s_nop 1
	v_addc_co_u32_e32 v65, vcc, 0, v3, vcc
	v_add_co_u32_e32 v66, vcc, 0xc000, v2
	s_nop 1
	v_addc_co_u32_e32 v67, vcc, 0, v3, vcc
	v_add_co_u32_e32 v68, vcc, 0xe000, v2
	s_nop 1
	v_addc_co_u32_e32 v69, vcc, 0, v3, vcc
	global_load_dword v10, v[2:3], off
	global_load_dword v72, v[4:5], off
	global_load_dword v73, v[6:7], off
	global_load_dword v74, v[8:9], off
	global_load_dword v75, v[46:47], off
	global_load_dword v76, v[64:65], off
	global_load_dword v77, v[66:67], off
	global_load_dword v78, v[68:69], off
	v_add_co_u32_e32 v4, vcc, 0x10000, v2
	s_nop 1
	v_addc_co_u32_e32 v5, vcc, 0, v3, vcc
	v_add_co_u32_e32 v6, vcc, 0x12000, v2
	s_nop 1
	v_addc_co_u32_e32 v7, vcc, 0, v3, vcc
	v_add_co_u32_e32 v8, vcc, 0x14000, v2
	s_nop 1
	v_addc_co_u32_e32 v9, vcc, 0, v3, vcc
	v_add_co_u32_e32 v46, vcc, 0x16000, v2
	s_nop 1
	v_addc_co_u32_e32 v47, vcc, 0, v3, vcc
	v_add_co_u32_e32 v64, vcc, 0x18000, v2
	s_nop 1
	v_addc_co_u32_e32 v65, vcc, 0, v3, vcc
	v_add_co_u32_e32 v66, vcc, 0x1a000, v2
	s_nop 1
	v_addc_co_u32_e32 v67, vcc, 0, v3, vcc
	v_add_co_u32_e32 v68, vcc, 0x1c000, v2
	s_nop 1
	v_addc_co_u32_e32 v69, vcc, 0, v3, vcc
	v_add_co_u32_e32 v70, vcc, 0x1e000, v2
	s_nop 1
	v_addc_co_u32_e32 v71, vcc, 0, v3, vcc
	global_load_dword v79, v[4:5], off
	global_load_dword v80, v[6:7], off
	global_load_dword v81, v[8:9], off
	global_load_dword v82, v[46:47], off
	global_load_dword v83, v[64:65], off
	global_load_dword v84, v[66:67], off
	global_load_dword v85, v[68:69], off
	global_load_dword v86, v[70:71], off
	v_add_co_u32_e32 v4, vcc, 0x20000, v2
	s_nop 1
	v_addc_co_u32_e32 v5, vcc, 0, v3, vcc
	v_add_co_u32_e32 v6, vcc, 0x22000, v2
	s_nop 1
	v_addc_co_u32_e32 v7, vcc, 0, v3, vcc
	v_add_co_u32_e32 v8, vcc, 0x24000, v2
	s_nop 1
	v_addc_co_u32_e32 v9, vcc, 0, v3, vcc
	v_add_co_u32_e32 v46, vcc, 0x26000, v2
	s_nop 1
	v_addc_co_u32_e32 v47, vcc, 0, v3, vcc
	v_add_co_u32_e32 v64, vcc, 0x28000, v2
	s_nop 1
	v_addc_co_u32_e32 v65, vcc, 0, v3, vcc
	v_add_co_u32_e32 v66, vcc, 0x2a000, v2
	s_nop 1
	v_addc_co_u32_e32 v67, vcc, 0, v3, vcc
	v_add_co_u32_e32 v68, vcc, 0x2c000, v2
	s_nop 1
	v_addc_co_u32_e32 v69, vcc, 0, v3, vcc
	v_add_co_u32_e32 v70, vcc, 0x2e000, v2
	s_nop 1
	v_addc_co_u32_e32 v71, vcc, 0, v3, vcc
	global_load_dword v87, v[4:5], off
	global_load_dword v88, v[6:7], off
	global_load_dword v89, v[8:9], off
	global_load_dword v90, v[46:47], off
	global_load_dword v91, v[64:65], off
	global_load_dword v92, v[66:67], off
	global_load_dword v93, v[68:69], off
	s_nop 0
	global_load_dword v70, v[70:71], off
	v_add_co_u32_e32 v4, vcc, 0x30000, v2
	s_nop 1
	v_addc_co_u32_e32 v5, vcc, 0, v3, vcc
	v_add_co_u32_e32 v6, vcc, 0x32000, v2
	s_nop 1
	v_addc_co_u32_e32 v7, vcc, 0, v3, vcc
	v_add_co_u32_e32 v8, vcc, 0x34000, v2
	s_nop 1
	v_addc_co_u32_e32 v9, vcc, 0, v3, vcc
	v_add_co_u32_e32 v46, vcc, 0x36000, v2
	s_nop 1
	v_addc_co_u32_e32 v47, vcc, 0, v3, vcc
	v_add_co_u32_e32 v64, vcc, 0x38000, v2
	s_nop 1
	v_addc_co_u32_e32 v65, vcc, 0, v3, vcc
	v_add_co_u32_e32 v66, vcc, 0x3a000, v2
	s_nop 1
	v_addc_co_u32_e32 v67, vcc, 0, v3, vcc
	v_add_co_u32_e32 v68, vcc, 0x3c000, v2
	s_nop 1
	v_addc_co_u32_e32 v69, vcc, 0, v3, vcc
	v_add_co_u32_e32 v2, vcc, 0x3e000, v2
	s_nop 1
	v_addc_co_u32_e32 v3, vcc, 0, v3, vcc
	global_load_dword v4, v[4:5], off
	s_nop 0
	global_load_dword v5, v[6:7], off
	s_nop 0
	global_load_dword v6, v[8:9], off
	global_load_dword v7, v[46:47], off
	s_nop 0
	global_load_dword v8, v[64:65], off
	global_load_dword v9, v[66:67], off
	global_load_dword v46, v[68:69], off
	s_nop 0
	global_load_dword v2, v[2:3], off
	s_waitcnt vmcnt(30)
	ds_write2_b32 v49, v10, v72 offset1:66
	s_waitcnt vmcnt(28)
	ds_write2_b32 v49, v73, v74 offset0:132 offset1:198
	s_waitcnt vmcnt(26)
	ds_write2_b32 v57, v75, v76 offset0:8 offset1:74
	s_waitcnt vmcnt(24)
	ds_write2_b32 v57, v77, v78 offset0:140 offset1:206
	s_waitcnt vmcnt(22)
	ds_write2_b32 v58, v79, v80 offset0:16 offset1:82
	s_waitcnt vmcnt(20)
	ds_write2_b32 v58, v81, v82 offset0:148 offset1:214
	s_waitcnt vmcnt(18)
	ds_write2_b32 v59, v83, v84 offset0:24 offset1:90
	s_waitcnt vmcnt(16)
	ds_write2_b32 v59, v85, v86 offset0:156 offset1:222
	s_waitcnt vmcnt(14)
	ds_write2_b32 v60, v87, v88 offset0:32 offset1:98
	s_waitcnt vmcnt(12)
	ds_write2_b32 v60, v89, v90 offset0:164 offset1:230
	s_waitcnt vmcnt(10)
	ds_write2_b32 v61, v91, v92 offset0:40 offset1:106
	s_waitcnt vmcnt(8)
	ds_write2_b32 v61, v93, v70 offset0:172 offset1:238
	s_waitcnt vmcnt(6)
	ds_write2_b32 v62, v4, v5 offset0:48 offset1:114
	s_waitcnt vmcnt(4)
	ds_write2_b32 v62, v6, v7 offset0:180 offset1:246
	s_waitcnt vmcnt(2)
	ds_write2_b32 v63, v8, v9 offset0:56 offset1:122
	s_waitcnt vmcnt(0)
	ds_write2_b32 v63, v46, v2 offset0:188 offset1:254
	s_waitcnt lgkmcnt(0)
	ds_read2_b32 v[6:7], v51 offset1:8
	ds_read2_b32 v[46:47], v51 offset0:33 offset1:41
	ds_read2_b32 v[64:65], v51 offset0:66 offset1:74
	ds_read2_b32 v[66:67], v51 offset0:99 offset1:107
	ds_read2_b32 v[68:69], v51 offset0:132 offset1:140
	s_waitcnt lgkmcnt(4)
	v_bfe_u32 v2, v6, 16, 1
	v_add3_u32 v2, v6, v2, s89
	s_waitcnt lgkmcnt(3)
	v_bfe_u32 v3, v46, 16, 1
	v_lshrrev_b32_e32 v2, 16, v2
	v_add3_u32 v3, v46, v3, s89
	ds_read2_b32 v[70:71], v51 offset0:165 offset1:173
	v_and_or_b32 v2, v3, s90, v2
	s_waitcnt lgkmcnt(3)
	v_bfe_u32 v3, v64, 16, 1
	v_add3_u32 v3, v64, v3, s89
	s_waitcnt lgkmcnt(2)
	v_bfe_u32 v4, v66, 16, 1
	ds_read2_b32 v[72:73], v51 offset0:198 offset1:206
	v_lshrrev_b32_e32 v3, 16, v3
	v_add3_u32 v4, v66, v4, s89
	ds_read2_b32 v[74:75], v51 offset0:231 offset1:239
	v_and_or_b32 v3, v4, s90, v3
	s_waitcnt lgkmcnt(3)
	v_bfe_u32 v4, v68, 16, 1
	v_add3_u32 v4, v68, v4, s89
	s_waitcnt lgkmcnt(2)
	v_bfe_u32 v5, v70, 16, 1
	v_lshrrev_b32_e32 v4, 16, v4
	v_add3_u32 v5, v70, v5, s89
	v_and_or_b32 v4, v5, s90, v4
	s_waitcnt lgkmcnt(1)
	v_bfe_u32 v5, v72, 16, 1
	v_add3_u32 v5, v72, v5, s89
	s_waitcnt lgkmcnt(0)
	v_bfe_u32 v6, v74, 16, 1
	v_lshrrev_b32_e32 v5, 16, v5
	v_add3_u32 v6, v74, v6, s89
	v_and_or_b32 v5, v6, s90, v5
	v_or_b32_e32 v6, s4, v50
	v_lshl_add_u64 v[8:9], v[36:37], 0, s[26:27]
	v_lshlrev_b32_e32 v10, 11, v6
	v_lshl_add_u64 v[76:77], v[8:9], 0, v[10:11]
	global_store_dwordx4 v[76:77], v[2:5], off sc1
	v_bfe_u32 v6, v75, 16, 1
	v_or_b32_e32 v10, s4, v52
	v_bfe_u32 v2, v7, 16, 1
	v_add3_u32 v2, v7, v2, s89
	v_bfe_u32 v3, v47, 16, 1
	v_lshrrev_b32_e32 v2, 16, v2
	v_add3_u32 v3, v47, v3, s89
	v_and_or_b32 v2, v3, s90, v2
	v_bfe_u32 v3, v65, 16, 1
	v_add3_u32 v3, v65, v3, s89
	v_bfe_u32 v4, v67, 16, 1
	v_lshrrev_b32_e32 v3, 16, v3
	v_add3_u32 v4, v67, v4, s89
	v_and_or_b32 v3, v4, s90, v3
	v_bfe_u32 v4, v69, 16, 1
	v_add3_u32 v4, v69, v4, s89
	v_bfe_u32 v5, v71, 16, 1
	v_lshrrev_b32_e32 v4, 16, v4
	v_add3_u32 v5, v71, v5, s89
	v_and_or_b32 v4, v5, s90, v4
	v_bfe_u32 v5, v73, 16, 1
	v_add3_u32 v5, v73, v5, s89
	v_lshrrev_b32_e32 v5, 16, v5
	v_add3_u32 v6, v75, v6, s89
	v_lshlrev_b32_e32 v10, 11, v10
	v_and_or_b32 v5, v6, s90, v5
	ds_read2_b32 v[6:7], v51 offset0:16 offset1:24
	v_lshl_add_u64 v[46:47], v[8:9], 0, v[10:11]
	global_store_dwordx4 v[46:47], v[2:5], off sc1
	ds_read2_b32 v[46:47], v51 offset0:49 offset1:57
	ds_read2_b32 v[64:65], v51 offset0:82 offset1:90
	ds_read2_b32 v[66:67], v51 offset0:115 offset1:123
	s_waitcnt lgkmcnt(3)
	v_bfe_u32 v2, v6, 16, 1
	v_add3_u32 v2, v6, v2, s89
	s_waitcnt lgkmcnt(2)
	v_bfe_u32 v3, v46, 16, 1
	ds_read2_b32 v[68:69], v51 offset0:148 offset1:156
	v_lshrrev_b32_e32 v2, 16, v2
	v_add3_u32 v3, v46, v3, s89
	ds_read2_b32 v[70:71], v51 offset0:181 offset1:189
	v_and_or_b32 v2, v3, s90, v2
	s_waitcnt lgkmcnt(3)
	v_bfe_u32 v3, v64, 16, 1
	v_add3_u32 v3, v64, v3, s89
	s_waitcnt lgkmcnt(2)
	v_bfe_u32 v4, v66, 16, 1
	ds_read2_b32 v[72:73], v51 offset0:214 offset1:222
	v_lshrrev_b32_e32 v3, 16, v3
	v_add3_u32 v4, v66, v4, s89
	ds_read2_b32 v[74:75], v51 offset0:247 offset1:255
	v_and_or_b32 v3, v4, s90, v3
	s_waitcnt lgkmcnt(3)
	v_bfe_u32 v4, v68, 16, 1
	v_add3_u32 v4, v68, v4, s89
	s_waitcnt lgkmcnt(2)
	v_bfe_u32 v5, v70, 16, 1
	v_lshrrev_b32_e32 v4, 16, v4
	v_add3_u32 v5, v70, v5, s89
	v_and_or_b32 v4, v5, s90, v4
	s_waitcnt lgkmcnt(1)
	v_bfe_u32 v5, v72, 16, 1
	v_add3_u32 v5, v72, v5, s89
	s_waitcnt lgkmcnt(0)
	v_bfe_u32 v6, v74, 16, 1
	v_lshrrev_b32_e32 v5, 16, v5
	v_add3_u32 v6, v74, v6, s89
	v_and_or_b32 v5, v6, s90, v5
	v_or_b32_e32 v6, s4, v53
	v_lshlrev_b32_e32 v10, 11, v6
	v_lshl_add_u64 v[76:77], v[8:9], 0, v[10:11]
	global_store_dwordx4 v[76:77], v[2:5], off sc1
	v_bfe_u32 v6, v75, 16, 1
	v_add3_u32 v6, v75, v6, s89
	v_bfe_u32 v2, v7, 16, 1
	v_add3_u32 v2, v7, v2, s89
	v_bfe_u32 v3, v47, 16, 1
	v_lshrrev_b32_e32 v2, 16, v2
	v_add3_u32 v3, v47, v3, s89
	v_and_or_b32 v2, v3, s90, v2
	v_bfe_u32 v3, v65, 16, 1
	v_add3_u32 v3, v65, v3, s89
	v_bfe_u32 v4, v67, 16, 1
	v_lshrrev_b32_e32 v3, 16, v3
	v_add3_u32 v4, v67, v4, s89
	v_and_or_b32 v3, v4, s90, v3
	v_bfe_u32 v4, v69, 16, 1
	v_add3_u32 v4, v69, v4, s89
	v_bfe_u32 v5, v71, 16, 1
	v_lshrrev_b32_e32 v4, 16, v4
	v_add3_u32 v5, v71, v5, s89
	v_and_or_b32 v4, v5, s90, v4
	v_bfe_u32 v5, v73, 16, 1
	v_add3_u32 v5, v73, v5, s89
	v_lshrrev_b32_e32 v5, 16, v5
	v_and_or_b32 v5, v6, s90, v5
	v_or_b32_e32 v6, s4, v54
	v_lshlrev_b32_e32 v10, 11, v6
	v_lshl_add_u64 v[6:7], v[8:9], 0, v[10:11]
	global_store_dwordx4 v[6:7], v[2:5], off sc1
	s_waitcnt lgkmcnt(0)
